# v40 with the GEMV row loads as a rotating prefetch (next group's row j issued when this group's row j is consumed; last group peeled) instead of a burst of 8 per group
# speedup vs baseline: 1.0007x; 1.0007x over previous
; #define LAS __attribute__((address_space(3)))
; __device__ __forceinline__ void gemv24_item(const float* W, int N, int j0, LAS float* sc, LAS float* red, float (&res)[6], const int tid) {
;     const int lane = tid & 63, wave = tid >> 6, cg = lane & 31, ks = wave * 2 + (lane >> 5);
;     f32x4 acc[24];
; #pragma unroll
;     for (int b = 0; b < 24; ++b) acc[b] = (f32x4){0.f, 0.f, 0.f, 0.f};
;     const float* w = W + (size_t)(ks * 64) * N + j0 + cg * 4;
; #pragma unroll 8
;     for (int kk = 0; kk < 64; ++kk) {
;         const f32x4 wv = *(const f32x4*)(w + (size_t)kk * N);
;         const LAS f32x4* s4 = (const LAS f32x4*)(sc + (ks * 64 + kk) * 24);
; #pragma unroll
;         for (int b4 = 0; b4 < 6; ++b4) { const f32x4 s = s4[b4]; acc[4 * b4] += wv * s[0]; acc[4 * b4 + 1] += wv * s[1]; acc[4 * b4 + 2] += wv * s[2]; acc[4 * b4 + 3] += wv * s[3]; }
;     }
.LBB0_435:
	s_lshl_b32 s30, s54, 7
	s_and_b64 s[0:1], exec, s[28:29]
	s_movk_i32 s0, 0xb00
	s_cselect_b32 s9, s0, 0x1000
	s_ashr_i32 s31, s30, 31
	s_lshl_b64 s[0:1], s[34:35], 2
	s_lshl_b64 s[16:17], s[30:31], 2
	s_add_u32 s0, s16, s0
	s_addc_u32 s1, s17, s1
	v_mov_b64_e32 v[20:21], s[0:1]
	v_mad_u64_u32 v[20:21], s[0:1], v16, s9, v[20:21]
	s_waitcnt lgkmcnt(0)
	v_lshl_add_u64 v[18:19], s[36:37], 0, v[14:15]
	v_mad_i32_i24 v21, v17, s9, v21
	v_lshl_add_u64 v[18:19], v[18:19], 0, v[20:21]
	v_mov_b32_e32 v20, 0
	s_lshl_b32 s22, s9, 5
	s_lshl_b32 s34, s9, 2
	s_mov_b32 s35, s23
	s_mov_b32 s31, 0
	v_mov_b32_e32 v21, v20
	v_mov_b32_e32 v22, v20
	v_mov_b32_e32 v23, v20
	v_mov_b32_e32 v24, v20
	v_mov_b32_e32 v25, v20
	v_mov_b32_e32 v26, v20
	v_mov_b32_e32 v27, v20
	v_mov_b32_e32 v28, v20
	v_mov_b32_e32 v29, v20
	v_mov_b32_e32 v30, v20
	v_mov_b32_e32 v31, v20
	v_mov_b32_e32 v32, v20
	v_mov_b32_e32 v33, v20
	v_mov_b32_e32 v34, v20
	v_mov_b32_e32 v35, v20
	v_mov_b32_e32 v36, v20
	v_mov_b32_e32 v37, v20
	v_mov_b32_e32 v38, v20
	v_mov_b32_e32 v39, v20
	v_mov_b32_e32 v40, v20
	v_mov_b32_e32 v41, v20
	v_mov_b32_e32 v42, v20
	v_mov_b32_e32 v43, v20
	v_mov_b32_e32 v44, v20
	v_mov_b32_e32 v45, v20
	v_mov_b32_e32 v46, v20
	v_mov_b32_e32 v47, v20
	v_mov_b32_e32 v48, v20
	v_mov_b32_e32 v49, v20
	v_mov_b32_e32 v50, v20
	v_mov_b32_e32 v51, v20
	v_mov_b32_e32 v52, v20
	v_mov_b32_e32 v53, v20
	v_mov_b32_e32 v54, v20
	v_mov_b32_e32 v55, v20
	v_mov_b32_e32 v56, v20
	v_mov_b32_e32 v57, v20
	v_mov_b32_e32 v58, v20
	v_mov_b32_e32 v59, v20
	v_mov_b32_e32 v60, v20
	v_mov_b32_e32 v61, v20
	v_mov_b32_e32 v62, v20
	v_mov_b32_e32 v63, v20
	v_mov_b32_e32 v64, v20
	v_mov_b32_e32 v65, v20
	v_mov_b32_e32 v66, v20
	v_mov_b32_e32 v67, v20
	v_mov_b32_e32 v68, v20
	v_mov_b32_e32 v69, v20
	v_mov_b32_e32 v70, v20
	v_mov_b32_e32 v71, v20
	v_mov_b32_e32 v72, v20
	v_mov_b32_e32 v73, v20
	v_mov_b32_e32 v74, v20
	v_mov_b32_e32 v75, v20
	v_mov_b32_e32 v76, v20
	v_mov_b32_e32 v77, v20
	v_mov_b32_e32 v78, v20
	v_mov_b32_e32 v79, v20
	v_mov_b32_e32 v80, v20
	v_mov_b32_e32 v81, v20
	v_mov_b32_e32 v82, v20
	v_mov_b32_e32 v83, v20
	v_mov_b32_e32 v84, v20
	v_mov_b32_e32 v85, v20
	v_mov_b32_e32 v86, v20
	v_mov_b32_e32 v87, v20
	v_mov_b32_e32 v88, v20
	v_mov_b32_e32 v89, v20
	v_mov_b32_e32 v90, v20
	v_mov_b32_e32 v91, v20
	v_mov_b32_e32 v92, v20
	v_mov_b32_e32 v93, v20
	v_mov_b32_e32 v94, v20
	v_mov_b32_e32 v95, v20
	v_mov_b32_e32 v96, v20
	v_mov_b32_e32 v97, v20
	v_mov_b32_e32 v98, v20
	v_mov_b32_e32 v99, v20
	v_mov_b32_e32 v100, v20
	v_mov_b32_e32 v101, v20
	v_mov_b32_e32 v102, v20
	v_mov_b32_e32 v103, v20
	v_mov_b32_e32 v104, v20
	v_mov_b32_e32 v105, v20
	v_mov_b32_e32 v106, v20
	v_mov_b32_e32 v107, v20
	v_mov_b32_e32 v108, v20
	v_mov_b32_e32 v109, v20
	v_mov_b32_e32 v110, v20
	v_mov_b32_e32 v111, v20
	v_mov_b32_e32 v112, v20
	v_mov_b32_e32 v113, v20
	v_mov_b32_e32 v114, v20
	v_mov_b32_e32 v115, v20
	v_mov_b64_e32 v[208:209], v[18:19]
	global_load_dwordx4 v[176:179], v[208:209], off
	v_lshl_add_u64 v[208:209], v[208:209], 0, s[34:35]
	global_load_dwordx4 v[180:183], v[208:209], off
	v_lshl_add_u64 v[208:209], v[208:209], 0, s[34:35]
	global_load_dwordx4 v[184:187], v[208:209], off
	v_lshl_add_u64 v[208:209], v[208:209], 0, s[34:35]
	global_load_dwordx4 v[188:191], v[208:209], off
	v_lshl_add_u64 v[208:209], v[208:209], 0, s[34:35]
	global_load_dwordx4 v[192:195], v[208:209], off
	v_lshl_add_u64 v[208:209], v[208:209], 0, s[34:35]
	global_load_dwordx4 v[196:199], v[208:209], off
	v_lshl_add_u64 v[208:209], v[208:209], 0, s[34:35]
	global_load_dwordx4 v[200:203], v[208:209], off
	v_lshl_add_u64 v[208:209], v[208:209], 0, s[34:35]
	global_load_dwordx4 v[204:207], v[208:209], off
	v_lshl_add_u64 v[208:209], v[208:209], 0, s[34:35]
.LBB0_436:
	v_add_u32_e32 v116, s31, v122
	ds_read_b128 v[128:131], v116
	ds_read_b128 v[132:135], v116 offset:16
	ds_read_b128 v[136:139], v116 offset:32
	ds_read_b128 v[140:143], v116 offset:48
	s_addk_i32 s31, 0x300
	s_cmpk_eq_i32 s31, 0x1500
	s_waitcnt vmcnt(7) lgkmcnt(3)
	v_pk_fma_f32 v[114:115], v[178:179], v[128:129], v[114:115] op_sel_hi:[1, 0, 1]
	v_pk_fma_f32 v[112:113], v[176:177], v[128:129], v[112:113] op_sel_hi:[1, 0, 1]
	v_pk_fma_f32 v[110:111], v[178:179], v[128:129], v[110:111] op_sel:[0, 1, 0]
	v_pk_fma_f32 v[108:109], v[176:177], v[128:129], v[108:109] op_sel:[0, 1, 0]
	v_mov_b32_e32 v128, v131
	v_pk_fma_f32 v[102:103], v[178:179], v[128:129], v[102:103] op_sel_hi:[1, 0, 1]
	v_pk_fma_f32 v[100:101], v[176:177], v[128:129], v[100:101] op_sel_hi:[1, 0, 1]
	s_waitcnt lgkmcnt(2)
	v_mov_b32_e32 v128, v135
	v_pk_fma_f32 v[86:87], v[178:179], v[128:129], v[86:87] op_sel_hi:[1, 0, 1]
	v_pk_fma_f32 v[84:85], v[176:177], v[128:129], v[84:85] op_sel_hi:[1, 0, 1]
	s_waitcnt lgkmcnt(1)
	v_mov_b32_e32 v128, v139
	v_pk_fma_f32 v[70:71], v[178:179], v[128:129], v[70:71] op_sel_hi:[1, 0, 1]
	v_pk_fma_f32 v[68:69], v[176:177], v[128:129], v[68:69] op_sel_hi:[1, 0, 1]
	s_waitcnt lgkmcnt(0)
	v_mov_b32_e32 v128, v143
	v_pk_fma_f32 v[106:107], v[178:179], v[130:131], v[106:107] op_sel_hi:[1, 0, 1]
	v_pk_fma_f32 v[104:105], v[176:177], v[130:131], v[104:105] op_sel_hi:[1, 0, 1]
	v_pk_fma_f32 v[54:55], v[178:179], v[128:129], v[54:55] op_sel_hi:[1, 0, 1]
	v_pk_fma_f32 v[52:53], v[176:177], v[128:129], v[52:53] op_sel_hi:[1, 0, 1]
	ds_read_b128 v[128:131], v116 offset:64
	v_pk_fma_f32 v[98:99], v[178:179], v[132:133], v[98:99] op_sel_hi:[1, 0, 1]
	v_pk_fma_f32 v[96:97], v[176:177], v[132:133], v[96:97] op_sel_hi:[1, 0, 1]
	v_pk_fma_f32 v[94:95], v[178:179], v[132:133], v[94:95] op_sel:[0, 1, 0]
	v_pk_fma_f32 v[92:93], v[176:177], v[132:133], v[92:93] op_sel:[0, 1, 0]
	s_waitcnt lgkmcnt(0)
; #define LAS __attribute__((address_space(3)))
; __device__ __forceinline__ void gemv24_item(const float* W, int N, int j0, LAS float* sc, LAS float* red, float (&res)[6], const int tid) {
;     ...
;     const float* w = W + (size_t)(ks * 64) * N + j0 + cg * 4;
; #pragma unroll 8
;     for (int kk = 0; kk < 64; ++kk) {
;         const f32x4 wv = *(const f32x4*)(w + (size_t)kk * N);
;         const LAS f32x4* s4 = (const LAS f32x4*)(sc + (ks * 64 + kk) * 24);
; #pragma unroll
;         for (int b4 = 0; b4 < 6; ++b4) { const f32x4 s = s4[b4]; acc[4 * b4] += wv * s[0]; acc[4 * b4 + 1] += wv * s[1]; acc[4 * b4 + 2] += wv * s[2]; acc[4 * b4 + 3] += wv * s[3]; }
;     }
	v_pk_fma_f32 v[50:51], v[178:179], v[128:129], v[50:51] op_sel_hi:[1, 0, 1]
	v_pk_fma_f32 v[48:49], v[176:177], v[128:129], v[48:49] op_sel_hi:[1, 0, 1]
	v_pk_fma_f32 v[46:47], v[178:179], v[128:129], v[46:47] op_sel:[0, 1, 0]
	v_pk_fma_f32 v[44:45], v[176:177], v[128:129], v[44:45] op_sel:[0, 1, 0]
	v_mov_b32_e32 v128, v131
	v_pk_fma_f32 v[42:43], v[178:179], v[130:131], v[42:43] op_sel_hi:[1, 0, 1]
	v_pk_fma_f32 v[40:41], v[176:177], v[130:131], v[40:41] op_sel_hi:[1, 0, 1]
	v_pk_fma_f32 v[38:39], v[178:179], v[128:129], v[38:39] op_sel_hi:[1, 0, 1]
	v_pk_fma_f32 v[36:37], v[176:177], v[128:129], v[36:37] op_sel_hi:[1, 0, 1]
	ds_read_b128 v[128:131], v116 offset:80
	v_lshl_add_u64 v[132:133], v[18:19], 0, s[34:35]
	v_pk_fma_f32 v[90:91], v[178:179], v[134:135], v[90:91] op_sel_hi:[1, 0, 1]
	v_pk_fma_f32 v[88:89], v[176:177], v[134:135], v[88:89] op_sel_hi:[1, 0, 1]
	v_pk_fma_f32 v[82:83], v[178:179], v[136:137], v[82:83] op_sel_hi:[1, 0, 1]
	s_waitcnt lgkmcnt(0)
	v_pk_fma_f32 v[34:35], v[178:179], v[128:129], v[34:35] op_sel_hi:[1, 0, 1]
	v_pk_fma_f32 v[32:33], v[176:177], v[128:129], v[32:33] op_sel_hi:[1, 0, 1]
	v_pk_fma_f32 v[30:31], v[178:179], v[128:129], v[30:31] op_sel:[0, 1, 0]
	v_pk_fma_f32 v[28:29], v[176:177], v[128:129], v[28:29] op_sel:[0, 1, 0]
	v_mov_b32_e32 v128, v131
	v_pk_fma_f32 v[80:81], v[176:177], v[136:137], v[80:81] op_sel_hi:[1, 0, 1]
	v_pk_fma_f32 v[78:79], v[178:179], v[136:137], v[78:79] op_sel:[0, 1, 0]
	v_pk_fma_f32 v[76:77], v[176:177], v[136:137], v[76:77] op_sel:[0, 1, 0]
	v_pk_fma_f32 v[74:75], v[178:179], v[138:139], v[74:75] op_sel_hi:[1, 0, 1]
	v_pk_fma_f32 v[72:73], v[176:177], v[138:139], v[72:73] op_sel_hi:[1, 0, 1]
	v_pk_fma_f32 v[66:67], v[178:179], v[140:141], v[66:67] op_sel_hi:[1, 0, 1]
	v_pk_fma_f32 v[64:65], v[176:177], v[140:141], v[64:65] op_sel_hi:[1, 0, 1]
	v_pk_fma_f32 v[62:63], v[178:179], v[140:141], v[62:63] op_sel:[0, 1, 0]
	v_pk_fma_f32 v[60:61], v[176:177], v[140:141], v[60:61] op_sel:[0, 1, 0]
	v_pk_fma_f32 v[58:59], v[178:179], v[142:143], v[58:59] op_sel_hi:[1, 0, 1]
	v_pk_fma_f32 v[56:57], v[176:177], v[142:143], v[56:57] op_sel_hi:[1, 0, 1]
	v_pk_fma_f32 v[26:27], v[178:179], v[130:131], v[26:27] op_sel_hi:[1, 0, 1]
	v_pk_fma_f32 v[24:25], v[176:177], v[130:131], v[24:25] op_sel_hi:[1, 0, 1]
	v_pk_fma_f32 v[22:23], v[178:179], v[128:129], v[22:23] op_sel_hi:[1, 0, 1]
	v_pk_fma_f32 v[20:21], v[176:177], v[128:129], v[20:21] op_sel_hi:[1, 0, 1]
	global_load_dwordx4 v[176:179], v[208:209], off
	v_lshl_add_u64 v[208:209], v[208:209], 0, s[34:35]
	ds_read_b128 v[128:131], v116 offset:96
	v_lshl_add_u64 v[18:19], v[18:19], 0, s[22:23]
	s_waitcnt vmcnt(7) lgkmcnt(0)
	v_pk_fma_f32 v[114:115], v[182:183], v[128:129], v[114:115] op_sel_hi:[1, 0, 1]
	v_pk_fma_f32 v[112:113], v[180:181], v[128:129], v[112:113] op_sel_hi:[1, 0, 1]
	v_pk_fma_f32 v[110:111], v[182:183], v[128:129], v[110:111] op_sel:[0, 1, 0]
	v_pk_fma_f32 v[108:109], v[180:181], v[128:129], v[108:109] op_sel:[0, 1, 0]
	v_mov_b32_e32 v128, v131
	v_pk_fma_f32 v[106:107], v[182:183], v[130:131], v[106:107] op_sel_hi:[1, 0, 1]
	v_pk_fma_f32 v[104:105], v[180:181], v[130:131], v[104:105] op_sel_hi:[1, 0, 1]
	v_pk_fma_f32 v[130:131], v[182:183], v[128:129], v[102:103] op_sel_hi:[1, 0, 1]
	v_pk_fma_f32 v[128:129], v[180:181], v[128:129], v[100:101] op_sel_hi:[1, 0, 1]
	ds_read_b128 v[100:103], v116 offset:112
	s_waitcnt lgkmcnt(0)
	v_pk_fma_f32 v[98:99], v[182:183], v[100:101], v[98:99] op_sel_hi:[1, 0, 1]
	v_pk_fma_f32 v[96:97], v[180:181], v[100:101], v[96:97] op_sel_hi:[1, 0, 1]
	v_pk_fma_f32 v[94:95], v[182:183], v[100:101], v[94:95] op_sel:[0, 1, 0]
	v_pk_fma_f32 v[92:93], v[180:181], v[100:101], v[92:93] op_sel:[0, 1, 0]
	v_mov_b32_e32 v100, v103
	v_pk_fma_f32 v[90:91], v[182:183], v[102:103], v[90:91] op_sel_hi:[1, 0, 1]
	v_pk_fma_f32 v[88:89], v[180:181], v[102:103], v[88:89] op_sel_hi:[1, 0, 1]
	v_pk_fma_f32 v[102:103], v[182:183], v[100:101], v[86:87] op_sel_hi:[1, 0, 1]
	v_pk_fma_f32 v[100:101], v[180:181], v[100:101], v[84:85] op_sel_hi:[1, 0, 1]
	ds_read_b128 v[84:87], v116 offset:128
	s_waitcnt lgkmcnt(0)
	v_pk_fma_f32 v[82:83], v[182:183], v[84:85], v[82:83] op_sel_hi:[1, 0, 1]
	v_pk_fma_f32 v[80:81], v[180:181], v[84:85], v[80:81] op_sel_hi:[1, 0, 1]
	v_pk_fma_f32 v[78:79], v[182:183], v[84:85], v[78:79] op_sel:[0, 1, 0]
	v_pk_fma_f32 v[76:77], v[180:181], v[84:85], v[76:77] op_sel:[0, 1, 0]
	v_mov_b32_e32 v84, v87
	v_pk_fma_f32 v[74:75], v[182:183], v[86:87], v[74:75] op_sel_hi:[1, 0, 1]
	v_pk_fma_f32 v[72:73], v[180:181], v[86:87], v[72:73] op_sel_hi:[1, 0, 1]
	v_pk_fma_f32 v[86:87], v[182:183], v[84:85], v[70:71] op_sel_hi:[1, 0, 1]
	v_pk_fma_f32 v[84:85], v[180:181], v[84:85], v[68:69] op_sel_hi:[1, 0, 1]
	ds_read_b128 v[68:71], v116 offset:144
	s_waitcnt lgkmcnt(0)
	v_pk_fma_f32 v[66:67], v[182:183], v[68:69], v[66:67] op_sel_hi:[1, 0, 1]
	v_pk_fma_f32 v[64:65], v[180:181], v[68:69], v[64:65] op_sel_hi:[1, 0, 1]
	v_pk_fma_f32 v[62:63], v[182:183], v[68:69], v[62:63] op_sel:[0, 1, 0]
	v_pk_fma_f32 v[60:61], v[180:181], v[68:69], v[60:61] op_sel:[0, 1, 0]
	v_mov_b32_e32 v68, v71
	v_pk_fma_f32 v[58:59], v[182:183], v[70:71], v[58:59] op_sel_hi:[1, 0, 1]
	v_pk_fma_f32 v[56:57], v[180:181], v[70:71], v[56:57] op_sel_hi:[1, 0, 1]
	v_pk_fma_f32 v[70:71], v[182:183], v[68:69], v[54:55] op_sel_hi:[1, 0, 1]
	v_pk_fma_f32 v[68:69], v[180:181], v[68:69], v[52:53] op_sel_hi:[1, 0, 1]
	ds_read_b128 v[52:55], v116 offset:160
	s_waitcnt lgkmcnt(0)
; #define LAS __attribute__((address_space(3)))
; __device__ __forceinline__ void gemv24_item(const float* W, int N, int j0, LAS float* sc, LAS float* red, float (&res)[6], const int tid) {
;     ...
;     const float* w = W + (size_t)(ks * 64) * N + j0 + cg * 4;
; #pragma unroll 8
;     for (int kk = 0; kk < 64; ++kk) {
;         const f32x4 wv = *(const f32x4*)(w + (size_t)kk * N);
;         const LAS f32x4* s4 = (const LAS f32x4*)(sc + (ks * 64 + kk) * 24);
; #pragma unroll
;         for (int b4 = 0; b4 < 6; ++b4) { const f32x4 s = s4[b4]; acc[4 * b4] += wv * s[0]; acc[4 * b4 + 1] += wv * s[1]; acc[4 * b4 + 2] += wv * s[2]; acc[4 * b4 + 3] += wv * s[3]; }
;     }
	v_pk_fma_f32 v[50:51], v[182:183], v[52:53], v[50:51] op_sel_hi:[1, 0, 1]
	v_pk_fma_f32 v[48:49], v[180:181], v[52:53], v[48:49] op_sel_hi:[1, 0, 1]
	v_pk_fma_f32 v[46:47], v[182:183], v[52:53], v[46:47] op_sel:[0, 1, 0]
	v_pk_fma_f32 v[44:45], v[180:181], v[52:53], v[44:45] op_sel:[0, 1, 0]
	v_mov_b32_e32 v52, v55
	v_pk_fma_f32 v[42:43], v[182:183], v[54:55], v[42:43] op_sel_hi:[1, 0, 1]
	v_pk_fma_f32 v[40:41], v[180:181], v[54:55], v[40:41] op_sel_hi:[1, 0, 1]
	v_pk_fma_f32 v[54:55], v[182:183], v[52:53], v[38:39] op_sel_hi:[1, 0, 1]
	v_pk_fma_f32 v[52:53], v[180:181], v[52:53], v[36:37] op_sel_hi:[1, 0, 1]
	ds_read_b128 v[36:39], v116 offset:176
	s_waitcnt lgkmcnt(0)
	v_pk_fma_f32 v[134:135], v[180:181], v[38:39], v[24:25] op_sel_hi:[1, 0, 1]
	v_mov_b32_e32 v24, v39
	v_pk_fma_f32 v[34:35], v[182:183], v[36:37], v[34:35] op_sel_hi:[1, 0, 1]
	v_pk_fma_f32 v[32:33], v[180:181], v[36:37], v[32:33] op_sel_hi:[1, 0, 1]
	v_pk_fma_f32 v[30:31], v[182:183], v[36:37], v[30:31] op_sel:[0, 1, 0]
	v_pk_fma_f32 v[28:29], v[180:181], v[36:37], v[28:29] op_sel:[0, 1, 0]
	v_pk_fma_f32 v[36:37], v[182:183], v[38:39], v[26:27] op_sel_hi:[1, 0, 1]
	v_pk_fma_f32 v[38:39], v[182:183], v[24:25], v[22:23] op_sel_hi:[1, 0, 1]
	v_lshl_add_u64 v[126:127], v[132:133], 0, s[34:35]
	v_pk_fma_f32 v[124:125], v[180:181], v[24:25], v[20:21] op_sel_hi:[1, 0, 1]
	global_load_dwordx4 v[180:183], v[208:209], off
	v_lshl_add_u64 v[208:209], v[208:209], 0, s[34:35]
	ds_read_b128 v[24:27], v116 offset:192
	v_lshl_add_u64 v[126:127], v[126:127], 0, s[34:35]
	s_waitcnt vmcnt(7) lgkmcnt(0)
	v_pk_fma_f32 v[114:115], v[186:187], v[24:25], v[114:115] op_sel_hi:[1, 0, 1]
	v_pk_fma_f32 v[112:113], v[184:185], v[24:25], v[112:113] op_sel_hi:[1, 0, 1]
	v_pk_fma_f32 v[110:111], v[186:187], v[24:25], v[110:111] op_sel:[0, 1, 0]
	v_pk_fma_f32 v[108:109], v[184:185], v[24:25], v[108:109] op_sel:[0, 1, 0]
	v_mov_b32_e32 v24, v27
	v_pk_fma_f32 v[106:107], v[186:187], v[26:27], v[106:107] op_sel_hi:[1, 0, 1]
	v_pk_fma_f32 v[104:105], v[184:185], v[26:27], v[104:105] op_sel_hi:[1, 0, 1]
	v_pk_fma_f32 v[130:131], v[186:187], v[24:25], v[130:131] op_sel_hi:[1, 0, 1]
	v_pk_fma_f32 v[128:129], v[184:185], v[24:25], v[128:129] op_sel_hi:[1, 0, 1]
	ds_read_b128 v[24:27], v116 offset:208
	s_waitcnt lgkmcnt(0)
	v_pk_fma_f32 v[98:99], v[186:187], v[24:25], v[98:99] op_sel_hi:[1, 0, 1]
	v_pk_fma_f32 v[96:97], v[184:185], v[24:25], v[96:97] op_sel_hi:[1, 0, 1]
	v_pk_fma_f32 v[94:95], v[186:187], v[24:25], v[94:95] op_sel:[0, 1, 0]
	v_pk_fma_f32 v[92:93], v[184:185], v[24:25], v[92:93] op_sel:[0, 1, 0]
	v_mov_b32_e32 v24, v27
	v_pk_fma_f32 v[90:91], v[186:187], v[26:27], v[90:91] op_sel_hi:[1, 0, 1]
	v_pk_fma_f32 v[88:89], v[184:185], v[26:27], v[88:89] op_sel_hi:[1, 0, 1]
	v_pk_fma_f32 v[102:103], v[186:187], v[24:25], v[102:103] op_sel_hi:[1, 0, 1]
	v_pk_fma_f32 v[100:101], v[184:185], v[24:25], v[100:101] op_sel_hi:[1, 0, 1]
	ds_read_b128 v[24:27], v116 offset:224
	s_waitcnt lgkmcnt(0)
	v_pk_fma_f32 v[82:83], v[186:187], v[24:25], v[82:83] op_sel_hi:[1, 0, 1]
	v_pk_fma_f32 v[80:81], v[184:185], v[24:25], v[80:81] op_sel_hi:[1, 0, 1]
	v_pk_fma_f32 v[78:79], v[186:187], v[24:25], v[78:79] op_sel:[0, 1, 0]
	v_pk_fma_f32 v[76:77], v[184:185], v[24:25], v[76:77] op_sel:[0, 1, 0]
	v_mov_b32_e32 v24, v27
	v_pk_fma_f32 v[74:75], v[186:187], v[26:27], v[74:75] op_sel_hi:[1, 0, 1]
	v_pk_fma_f32 v[72:73], v[184:185], v[26:27], v[72:73] op_sel_hi:[1, 0, 1]
	v_pk_fma_f32 v[86:87], v[186:187], v[24:25], v[86:87] op_sel_hi:[1, 0, 1]
	v_pk_fma_f32 v[84:85], v[184:185], v[24:25], v[84:85] op_sel_hi:[1, 0, 1]
	ds_read_b128 v[24:27], v116 offset:240
	s_waitcnt lgkmcnt(0)
	v_pk_fma_f32 v[66:67], v[186:187], v[24:25], v[66:67] op_sel_hi:[1, 0, 1]
	v_pk_fma_f32 v[64:65], v[184:185], v[24:25], v[64:65] op_sel_hi:[1, 0, 1]
	v_pk_fma_f32 v[62:63], v[186:187], v[24:25], v[62:63] op_sel:[0, 1, 0]
	v_pk_fma_f32 v[60:61], v[184:185], v[24:25], v[60:61] op_sel:[0, 1, 0]
	v_mov_b32_e32 v24, v27
	v_pk_fma_f32 v[58:59], v[186:187], v[26:27], v[58:59] op_sel_hi:[1, 0, 1]
	v_pk_fma_f32 v[56:57], v[184:185], v[26:27], v[56:57] op_sel_hi:[1, 0, 1]
	v_pk_fma_f32 v[70:71], v[186:187], v[24:25], v[70:71] op_sel_hi:[1, 0, 1]
	v_pk_fma_f32 v[68:69], v[184:185], v[24:25], v[68:69] op_sel_hi:[1, 0, 1]
	ds_read_b128 v[24:27], v116 offset:256
	s_waitcnt lgkmcnt(0)
	v_pk_fma_f32 v[50:51], v[186:187], v[24:25], v[50:51] op_sel_hi:[1, 0, 1]
	v_pk_fma_f32 v[48:49], v[184:185], v[24:25], v[48:49] op_sel_hi:[1, 0, 1]
	v_pk_fma_f32 v[46:47], v[186:187], v[24:25], v[46:47] op_sel:[0, 1, 0]
	v_pk_fma_f32 v[44:45], v[184:185], v[24:25], v[44:45] op_sel:[0, 1, 0]
	v_mov_b32_e32 v24, v27
	v_pk_fma_f32 v[42:43], v[186:187], v[26:27], v[42:43] op_sel_hi:[1, 0, 1]
	v_pk_fma_f32 v[40:41], v[184:185], v[26:27], v[40:41] op_sel_hi:[1, 0, 1]
	v_pk_fma_f32 v[54:55], v[186:187], v[24:25], v[54:55] op_sel_hi:[1, 0, 1]
	v_pk_fma_f32 v[52:53], v[184:185], v[24:25], v[52:53] op_sel_hi:[1, 0, 1]
	ds_read_b128 v[24:27], v116 offset:272
	s_waitcnt lgkmcnt(0)
	v_pk_fma_f32 v[34:35], v[186:187], v[24:25], v[34:35] op_sel_hi:[1, 0, 1]
	v_pk_fma_f32 v[32:33], v[184:185], v[24:25], v[32:33] op_sel_hi:[1, 0, 1]
	v_pk_fma_f32 v[30:31], v[186:187], v[24:25], v[30:31] op_sel:[0, 1, 0]
	v_pk_fma_f32 v[28:29], v[184:185], v[24:25], v[28:29] op_sel:[0, 1, 0]
	v_mov_b32_e32 v24, v27
	v_pk_fma_f32 v[36:37], v[186:187], v[26:27], v[36:37] op_sel_hi:[1, 0, 1]
	v_pk_fma_f32 v[132:133], v[184:185], v[26:27], v[134:135] op_sel_hi:[1, 0, 1]
	v_pk_fma_f32 v[38:39], v[186:187], v[24:25], v[38:39] op_sel_hi:[1, 0, 1]
	v_pk_fma_f32 v[124:125], v[184:185], v[24:25], v[124:125] op_sel_hi:[1, 0, 1]
	global_load_dwordx4 v[184:187], v[208:209], off
	v_lshl_add_u64 v[208:209], v[208:209], 0, s[34:35]
	ds_read_b128 v[24:27], v116 offset:288
	v_lshl_add_u64 v[126:127], v[126:127], 0, s[34:35]
	s_waitcnt vmcnt(7) lgkmcnt(0)
; #define LAS __attribute__((address_space(3)))
; __device__ __forceinline__ void gemv24_item(const float* W, int N, int j0, LAS float* sc, LAS float* red, float (&res)[6], const int tid) {
;     ...
;     const float* w = W + (size_t)(ks * 64) * N + j0 + cg * 4;
; #pragma unroll 8
;     for (int kk = 0; kk < 64; ++kk) {
;         const f32x4 wv = *(const f32x4*)(w + (size_t)kk * N);
;         const LAS f32x4* s4 = (const LAS f32x4*)(sc + (ks * 64 + kk) * 24);
; #pragma unroll
;         for (int b4 = 0; b4 < 6; ++b4) { const f32x4 s = s4[b4]; acc[4 * b4] += wv * s[0]; acc[4 * b4 + 1] += wv * s[1]; acc[4 * b4 + 2] += wv * s[2]; acc[4 * b4 + 3] += wv * s[3]; }
;     }
	v_pk_fma_f32 v[114:115], v[190:191], v[24:25], v[114:115] op_sel_hi:[1, 0, 1]
	v_pk_fma_f32 v[112:113], v[188:189], v[24:25], v[112:113] op_sel_hi:[1, 0, 1]
	v_pk_fma_f32 v[110:111], v[190:191], v[24:25], v[110:111] op_sel:[0, 1, 0]
	v_pk_fma_f32 v[108:109], v[188:189], v[24:25], v[108:109] op_sel:[0, 1, 0]
	v_mov_b32_e32 v24, v27
	v_pk_fma_f32 v[106:107], v[190:191], v[26:27], v[106:107] op_sel_hi:[1, 0, 1]
	v_pk_fma_f32 v[104:105], v[188:189], v[26:27], v[104:105] op_sel_hi:[1, 0, 1]
	v_pk_fma_f32 v[130:131], v[190:191], v[24:25], v[130:131] op_sel_hi:[1, 0, 1]
	v_pk_fma_f32 v[128:129], v[188:189], v[24:25], v[128:129] op_sel_hi:[1, 0, 1]
	ds_read_b128 v[24:27], v116 offset:304
	s_waitcnt lgkmcnt(0)
	v_pk_fma_f32 v[98:99], v[190:191], v[24:25], v[98:99] op_sel_hi:[1, 0, 1]
	v_pk_fma_f32 v[96:97], v[188:189], v[24:25], v[96:97] op_sel_hi:[1, 0, 1]
	v_pk_fma_f32 v[94:95], v[190:191], v[24:25], v[94:95] op_sel:[0, 1, 0]
	v_pk_fma_f32 v[92:93], v[188:189], v[24:25], v[92:93] op_sel:[0, 1, 0]
	v_mov_b32_e32 v24, v27
	v_pk_fma_f32 v[90:91], v[190:191], v[26:27], v[90:91] op_sel_hi:[1, 0, 1]
	v_pk_fma_f32 v[88:89], v[188:189], v[26:27], v[88:89] op_sel_hi:[1, 0, 1]
	v_pk_fma_f32 v[102:103], v[190:191], v[24:25], v[102:103] op_sel_hi:[1, 0, 1]
	v_pk_fma_f32 v[100:101], v[188:189], v[24:25], v[100:101] op_sel_hi:[1, 0, 1]
	ds_read_b128 v[24:27], v116 offset:320
	s_waitcnt lgkmcnt(0)
	v_pk_fma_f32 v[82:83], v[190:191], v[24:25], v[82:83] op_sel_hi:[1, 0, 1]
	v_pk_fma_f32 v[80:81], v[188:189], v[24:25], v[80:81] op_sel_hi:[1, 0, 1]
	v_pk_fma_f32 v[78:79], v[190:191], v[24:25], v[78:79] op_sel:[0, 1, 0]
	v_pk_fma_f32 v[76:77], v[188:189], v[24:25], v[76:77] op_sel:[0, 1, 0]
	v_mov_b32_e32 v24, v27
	v_pk_fma_f32 v[74:75], v[190:191], v[26:27], v[74:75] op_sel_hi:[1, 0, 1]
	v_pk_fma_f32 v[72:73], v[188:189], v[26:27], v[72:73] op_sel_hi:[1, 0, 1]
	v_pk_fma_f32 v[86:87], v[190:191], v[24:25], v[86:87] op_sel_hi:[1, 0, 1]
	v_pk_fma_f32 v[84:85], v[188:189], v[24:25], v[84:85] op_sel_hi:[1, 0, 1]
	ds_read_b128 v[24:27], v116 offset:336
	s_waitcnt lgkmcnt(0)
	v_pk_fma_f32 v[66:67], v[190:191], v[24:25], v[66:67] op_sel_hi:[1, 0, 1]
	v_pk_fma_f32 v[64:65], v[188:189], v[24:25], v[64:65] op_sel_hi:[1, 0, 1]
	v_pk_fma_f32 v[62:63], v[190:191], v[24:25], v[62:63] op_sel:[0, 1, 0]
	v_pk_fma_f32 v[60:61], v[188:189], v[24:25], v[60:61] op_sel:[0, 1, 0]
	v_mov_b32_e32 v24, v27
	v_pk_fma_f32 v[58:59], v[190:191], v[26:27], v[58:59] op_sel_hi:[1, 0, 1]
	v_pk_fma_f32 v[56:57], v[188:189], v[26:27], v[56:57] op_sel_hi:[1, 0, 1]
	v_pk_fma_f32 v[70:71], v[190:191], v[24:25], v[70:71] op_sel_hi:[1, 0, 1]
	v_pk_fma_f32 v[68:69], v[188:189], v[24:25], v[68:69] op_sel_hi:[1, 0, 1]
	ds_read_b128 v[24:27], v116 offset:352
	s_waitcnt lgkmcnt(0)
	v_pk_fma_f32 v[50:51], v[190:191], v[24:25], v[50:51] op_sel_hi:[1, 0, 1]
	v_pk_fma_f32 v[48:49], v[188:189], v[24:25], v[48:49] op_sel_hi:[1, 0, 1]
	v_pk_fma_f32 v[46:47], v[190:191], v[24:25], v[46:47] op_sel:[0, 1, 0]
	v_pk_fma_f32 v[44:45], v[188:189], v[24:25], v[44:45] op_sel:[0, 1, 0]
	v_mov_b32_e32 v24, v27
	v_pk_fma_f32 v[42:43], v[190:191], v[26:27], v[42:43] op_sel_hi:[1, 0, 1]
	v_pk_fma_f32 v[40:41], v[188:189], v[26:27], v[40:41] op_sel_hi:[1, 0, 1]
	v_pk_fma_f32 v[54:55], v[190:191], v[24:25], v[54:55] op_sel_hi:[1, 0, 1]
	v_pk_fma_f32 v[52:53], v[188:189], v[24:25], v[52:53] op_sel_hi:[1, 0, 1]
	ds_read_b128 v[24:27], v116 offset:368
	s_waitcnt lgkmcnt(0)
	v_pk_fma_f32 v[34:35], v[190:191], v[24:25], v[34:35] op_sel_hi:[1, 0, 1]
	v_pk_fma_f32 v[32:33], v[188:189], v[24:25], v[32:33] op_sel_hi:[1, 0, 1]
	v_pk_fma_f32 v[30:31], v[190:191], v[24:25], v[30:31] op_sel:[0, 1, 0]
	v_pk_fma_f32 v[28:29], v[188:189], v[24:25], v[28:29] op_sel:[0, 1, 0]
	v_mov_b32_e32 v24, v27
	v_pk_fma_f32 v[36:37], v[190:191], v[26:27], v[36:37] op_sel_hi:[1, 0, 1]
	v_pk_fma_f32 v[132:133], v[188:189], v[26:27], v[132:133] op_sel_hi:[1, 0, 1]
	v_pk_fma_f32 v[38:39], v[190:191], v[24:25], v[38:39] op_sel_hi:[1, 0, 1]
	v_pk_fma_f32 v[124:125], v[188:189], v[24:25], v[124:125] op_sel_hi:[1, 0, 1]
	global_load_dwordx4 v[188:191], v[208:209], off
	v_lshl_add_u64 v[208:209], v[208:209], 0, s[34:35]
	ds_read_b128 v[24:27], v116 offset:384
	v_lshl_add_u64 v[126:127], v[126:127], 0, s[34:35]
	s_waitcnt vmcnt(7) lgkmcnt(0)
	v_pk_fma_f32 v[114:115], v[194:195], v[24:25], v[114:115] op_sel_hi:[1, 0, 1]
	v_pk_fma_f32 v[112:113], v[192:193], v[24:25], v[112:113] op_sel_hi:[1, 0, 1]
	v_pk_fma_f32 v[110:111], v[194:195], v[24:25], v[110:111] op_sel:[0, 1, 0]
	v_pk_fma_f32 v[108:109], v[192:193], v[24:25], v[108:109] op_sel:[0, 1, 0]
	v_mov_b32_e32 v24, v27
	v_pk_fma_f32 v[106:107], v[194:195], v[26:27], v[106:107] op_sel_hi:[1, 0, 1]
	v_pk_fma_f32 v[104:105], v[192:193], v[26:27], v[104:105] op_sel_hi:[1, 0, 1]
	v_pk_fma_f32 v[130:131], v[194:195], v[24:25], v[130:131] op_sel_hi:[1, 0, 1]
	v_pk_fma_f32 v[128:129], v[192:193], v[24:25], v[128:129] op_sel_hi:[1, 0, 1]
	ds_read_b128 v[24:27], v116 offset:400
	s_waitcnt lgkmcnt(0)
	v_pk_fma_f32 v[98:99], v[194:195], v[24:25], v[98:99] op_sel_hi:[1, 0, 1]
	v_pk_fma_f32 v[96:97], v[192:193], v[24:25], v[96:97] op_sel_hi:[1, 0, 1]
	v_pk_fma_f32 v[94:95], v[194:195], v[24:25], v[94:95] op_sel:[0, 1, 0]
	v_pk_fma_f32 v[92:93], v[192:193], v[24:25], v[92:93] op_sel:[0, 1, 0]
	v_mov_b32_e32 v24, v27
	v_pk_fma_f32 v[90:91], v[194:195], v[26:27], v[90:91] op_sel_hi:[1, 0, 1]
	v_pk_fma_f32 v[88:89], v[192:193], v[26:27], v[88:89] op_sel_hi:[1, 0, 1]
	v_pk_fma_f32 v[102:103], v[194:195], v[24:25], v[102:103] op_sel_hi:[1, 0, 1]
	v_pk_fma_f32 v[100:101], v[192:193], v[24:25], v[100:101] op_sel_hi:[1, 0, 1]
	ds_read_b128 v[24:27], v116 offset:416
	s_waitcnt lgkmcnt(0)
; #define LAS __attribute__((address_space(3)))
; __device__ __forceinline__ void gemv24_item(const float* W, int N, int j0, LAS float* sc, LAS float* red, float (&res)[6], const int tid) {
;     ...
;     const float* w = W + (size_t)(ks * 64) * N + j0 + cg * 4;
; #pragma unroll 8
;     for (int kk = 0; kk < 64; ++kk) {
;         const f32x4 wv = *(const f32x4*)(w + (size_t)kk * N);
;         const LAS f32x4* s4 = (const LAS f32x4*)(sc + (ks * 64 + kk) * 24);
; #pragma unroll
;         for (int b4 = 0; b4 < 6; ++b4) { const f32x4 s = s4[b4]; acc[4 * b4] += wv * s[0]; acc[4 * b4 + 1] += wv * s[1]; acc[4 * b4 + 2] += wv * s[2]; acc[4 * b4 + 3] += wv * s[3]; }
;     }
	v_pk_fma_f32 v[82:83], v[194:195], v[24:25], v[82:83] op_sel_hi:[1, 0, 1]
	v_pk_fma_f32 v[80:81], v[192:193], v[24:25], v[80:81] op_sel_hi:[1, 0, 1]
	v_pk_fma_f32 v[78:79], v[194:195], v[24:25], v[78:79] op_sel:[0, 1, 0]
	v_pk_fma_f32 v[76:77], v[192:193], v[24:25], v[76:77] op_sel:[0, 1, 0]
	v_mov_b32_e32 v24, v27
	v_pk_fma_f32 v[74:75], v[194:195], v[26:27], v[74:75] op_sel_hi:[1, 0, 1]
	v_pk_fma_f32 v[72:73], v[192:193], v[26:27], v[72:73] op_sel_hi:[1, 0, 1]
	v_pk_fma_f32 v[86:87], v[194:195], v[24:25], v[86:87] op_sel_hi:[1, 0, 1]
	v_pk_fma_f32 v[84:85], v[192:193], v[24:25], v[84:85] op_sel_hi:[1, 0, 1]
	ds_read_b128 v[24:27], v116 offset:432
	s_waitcnt lgkmcnt(0)
	v_pk_fma_f32 v[66:67], v[194:195], v[24:25], v[66:67] op_sel_hi:[1, 0, 1]
	v_pk_fma_f32 v[64:65], v[192:193], v[24:25], v[64:65] op_sel_hi:[1, 0, 1]
	v_pk_fma_f32 v[62:63], v[194:195], v[24:25], v[62:63] op_sel:[0, 1, 0]
	v_pk_fma_f32 v[60:61], v[192:193], v[24:25], v[60:61] op_sel:[0, 1, 0]
	v_mov_b32_e32 v24, v27
	v_pk_fma_f32 v[58:59], v[194:195], v[26:27], v[58:59] op_sel_hi:[1, 0, 1]
	v_pk_fma_f32 v[56:57], v[192:193], v[26:27], v[56:57] op_sel_hi:[1, 0, 1]
	v_pk_fma_f32 v[70:71], v[194:195], v[24:25], v[70:71] op_sel_hi:[1, 0, 1]
	v_pk_fma_f32 v[68:69], v[192:193], v[24:25], v[68:69] op_sel_hi:[1, 0, 1]
	ds_read_b128 v[24:27], v116 offset:448
	s_waitcnt lgkmcnt(0)
	v_pk_fma_f32 v[50:51], v[194:195], v[24:25], v[50:51] op_sel_hi:[1, 0, 1]
	v_pk_fma_f32 v[48:49], v[192:193], v[24:25], v[48:49] op_sel_hi:[1, 0, 1]
	v_pk_fma_f32 v[46:47], v[194:195], v[24:25], v[46:47] op_sel:[0, 1, 0]
	v_pk_fma_f32 v[44:45], v[192:193], v[24:25], v[44:45] op_sel:[0, 1, 0]
	v_mov_b32_e32 v24, v27
	v_pk_fma_f32 v[42:43], v[194:195], v[26:27], v[42:43] op_sel_hi:[1, 0, 1]
	v_pk_fma_f32 v[40:41], v[192:193], v[26:27], v[40:41] op_sel_hi:[1, 0, 1]
	v_pk_fma_f32 v[54:55], v[194:195], v[24:25], v[54:55] op_sel_hi:[1, 0, 1]
	v_pk_fma_f32 v[52:53], v[192:193], v[24:25], v[52:53] op_sel_hi:[1, 0, 1]
	ds_read_b128 v[24:27], v116 offset:464
	s_waitcnt lgkmcnt(0)
	v_pk_fma_f32 v[34:35], v[194:195], v[24:25], v[34:35] op_sel_hi:[1, 0, 1]
	v_pk_fma_f32 v[32:33], v[192:193], v[24:25], v[32:33] op_sel_hi:[1, 0, 1]
	v_pk_fma_f32 v[30:31], v[194:195], v[24:25], v[30:31] op_sel:[0, 1, 0]
	v_pk_fma_f32 v[28:29], v[192:193], v[24:25], v[28:29] op_sel:[0, 1, 0]
	v_mov_b32_e32 v24, v27
	v_pk_fma_f32 v[36:37], v[194:195], v[26:27], v[36:37] op_sel_hi:[1, 0, 1]
	v_pk_fma_f32 v[132:133], v[192:193], v[26:27], v[132:133] op_sel_hi:[1, 0, 1]
	v_pk_fma_f32 v[38:39], v[194:195], v[24:25], v[38:39] op_sel_hi:[1, 0, 1]
	v_pk_fma_f32 v[124:125], v[192:193], v[24:25], v[124:125] op_sel_hi:[1, 0, 1]
	global_load_dwordx4 v[192:195], v[208:209], off
	v_lshl_add_u64 v[208:209], v[208:209], 0, s[34:35]
	ds_read_b128 v[24:27], v116 offset:480
	v_lshl_add_u64 v[126:127], v[126:127], 0, s[34:35]
	s_waitcnt vmcnt(7) lgkmcnt(0)
	v_pk_fma_f32 v[114:115], v[198:199], v[24:25], v[114:115] op_sel_hi:[1, 0, 1]
	v_pk_fma_f32 v[112:113], v[196:197], v[24:25], v[112:113] op_sel_hi:[1, 0, 1]
	v_pk_fma_f32 v[110:111], v[198:199], v[24:25], v[110:111] op_sel:[0, 1, 0]
	v_pk_fma_f32 v[108:109], v[196:197], v[24:25], v[108:109] op_sel:[0, 1, 0]
	v_mov_b32_e32 v24, v27
	v_pk_fma_f32 v[106:107], v[198:199], v[26:27], v[106:107] op_sel_hi:[1, 0, 1]
	v_pk_fma_f32 v[104:105], v[196:197], v[26:27], v[104:105] op_sel_hi:[1, 0, 1]
	v_pk_fma_f32 v[130:131], v[198:199], v[24:25], v[130:131] op_sel_hi:[1, 0, 1]
	v_pk_fma_f32 v[128:129], v[196:197], v[24:25], v[128:129] op_sel_hi:[1, 0, 1]
	ds_read_b128 v[24:27], v116 offset:496
	s_waitcnt lgkmcnt(0)
	v_pk_fma_f32 v[98:99], v[198:199], v[24:25], v[98:99] op_sel_hi:[1, 0, 1]
	v_pk_fma_f32 v[96:97], v[196:197], v[24:25], v[96:97] op_sel_hi:[1, 0, 1]
	v_pk_fma_f32 v[94:95], v[198:199], v[24:25], v[94:95] op_sel:[0, 1, 0]
	v_pk_fma_f32 v[92:93], v[196:197], v[24:25], v[92:93] op_sel:[0, 1, 0]
	v_mov_b32_e32 v24, v27
	v_pk_fma_f32 v[90:91], v[198:199], v[26:27], v[90:91] op_sel_hi:[1, 0, 1]
	v_pk_fma_f32 v[88:89], v[196:197], v[26:27], v[88:89] op_sel_hi:[1, 0, 1]
	v_pk_fma_f32 v[102:103], v[198:199], v[24:25], v[102:103] op_sel_hi:[1, 0, 1]
	v_pk_fma_f32 v[100:101], v[196:197], v[24:25], v[100:101] op_sel_hi:[1, 0, 1]
	ds_read_b128 v[24:27], v116 offset:512
	s_waitcnt lgkmcnt(0)
	v_pk_fma_f32 v[82:83], v[198:199], v[24:25], v[82:83] op_sel_hi:[1, 0, 1]
	v_pk_fma_f32 v[80:81], v[196:197], v[24:25], v[80:81] op_sel_hi:[1, 0, 1]
	v_pk_fma_f32 v[78:79], v[198:199], v[24:25], v[78:79] op_sel:[0, 1, 0]
	v_pk_fma_f32 v[76:77], v[196:197], v[24:25], v[76:77] op_sel:[0, 1, 0]
	v_mov_b32_e32 v24, v27
	v_pk_fma_f32 v[74:75], v[198:199], v[26:27], v[74:75] op_sel_hi:[1, 0, 1]
	v_pk_fma_f32 v[72:73], v[196:197], v[26:27], v[72:73] op_sel_hi:[1, 0, 1]
	v_pk_fma_f32 v[86:87], v[198:199], v[24:25], v[86:87] op_sel_hi:[1, 0, 1]
	v_pk_fma_f32 v[84:85], v[196:197], v[24:25], v[84:85] op_sel_hi:[1, 0, 1]
	ds_read_b128 v[24:27], v116 offset:528
	s_waitcnt lgkmcnt(0)
	v_pk_fma_f32 v[66:67], v[198:199], v[24:25], v[66:67] op_sel_hi:[1, 0, 1]
	v_pk_fma_f32 v[64:65], v[196:197], v[24:25], v[64:65] op_sel_hi:[1, 0, 1]
	v_pk_fma_f32 v[62:63], v[198:199], v[24:25], v[62:63] op_sel:[0, 1, 0]
	v_pk_fma_f32 v[60:61], v[196:197], v[24:25], v[60:61] op_sel:[0, 1, 0]
	v_mov_b32_e32 v24, v27
	v_pk_fma_f32 v[58:59], v[198:199], v[26:27], v[58:59] op_sel_hi:[1, 0, 1]
	v_pk_fma_f32 v[56:57], v[196:197], v[26:27], v[56:57] op_sel_hi:[1, 0, 1]
	v_pk_fma_f32 v[70:71], v[198:199], v[24:25], v[70:71] op_sel_hi:[1, 0, 1]
	v_pk_fma_f32 v[68:69], v[196:197], v[24:25], v[68:69] op_sel_hi:[1, 0, 1]
	ds_read_b128 v[24:27], v116 offset:544
	s_waitcnt lgkmcnt(0)
; #define LAS __attribute__((address_space(3)))
; __device__ __forceinline__ void gemv24_item(const float* W, int N, int j0, LAS float* sc, LAS float* red, float (&res)[6], const int tid) {
;     ...
;     const float* w = W + (size_t)(ks * 64) * N + j0 + cg * 4;
; #pragma unroll 8
;     for (int kk = 0; kk < 64; ++kk) {
;         const f32x4 wv = *(const f32x4*)(w + (size_t)kk * N);
;         const LAS f32x4* s4 = (const LAS f32x4*)(sc + (ks * 64 + kk) * 24);
; #pragma unroll
;         for (int b4 = 0; b4 < 6; ++b4) { const f32x4 s = s4[b4]; acc[4 * b4] += wv * s[0]; acc[4 * b4 + 1] += wv * s[1]; acc[4 * b4 + 2] += wv * s[2]; acc[4 * b4 + 3] += wv * s[3]; }
;     }
	v_pk_fma_f32 v[50:51], v[198:199], v[24:25], v[50:51] op_sel_hi:[1, 0, 1]
	v_pk_fma_f32 v[48:49], v[196:197], v[24:25], v[48:49] op_sel_hi:[1, 0, 1]
	v_pk_fma_f32 v[46:47], v[198:199], v[24:25], v[46:47] op_sel:[0, 1, 0]
	v_pk_fma_f32 v[44:45], v[196:197], v[24:25], v[44:45] op_sel:[0, 1, 0]
	v_mov_b32_e32 v24, v27
	v_pk_fma_f32 v[42:43], v[198:199], v[26:27], v[42:43] op_sel_hi:[1, 0, 1]
	v_pk_fma_f32 v[40:41], v[196:197], v[26:27], v[40:41] op_sel_hi:[1, 0, 1]
	v_pk_fma_f32 v[54:55], v[198:199], v[24:25], v[54:55] op_sel_hi:[1, 0, 1]
	v_pk_fma_f32 v[52:53], v[196:197], v[24:25], v[52:53] op_sel_hi:[1, 0, 1]
	ds_read_b128 v[24:27], v116 offset:560
	s_waitcnt lgkmcnt(0)
	v_pk_fma_f32 v[34:35], v[198:199], v[24:25], v[34:35] op_sel_hi:[1, 0, 1]
	v_pk_fma_f32 v[32:33], v[196:197], v[24:25], v[32:33] op_sel_hi:[1, 0, 1]
	v_pk_fma_f32 v[30:31], v[198:199], v[24:25], v[30:31] op_sel:[0, 1, 0]
	v_pk_fma_f32 v[28:29], v[196:197], v[24:25], v[28:29] op_sel:[0, 1, 0]
	v_mov_b32_e32 v24, v27
	v_pk_fma_f32 v[36:37], v[198:199], v[26:27], v[36:37] op_sel_hi:[1, 0, 1]
	v_pk_fma_f32 v[132:133], v[196:197], v[26:27], v[132:133] op_sel_hi:[1, 0, 1]
	v_pk_fma_f32 v[38:39], v[198:199], v[24:25], v[38:39] op_sel_hi:[1, 0, 1]
	v_pk_fma_f32 v[124:125], v[196:197], v[24:25], v[124:125] op_sel_hi:[1, 0, 1]
	global_load_dwordx4 v[196:199], v[208:209], off
	v_lshl_add_u64 v[208:209], v[208:209], 0, s[34:35]
	ds_read_b128 v[24:27], v116 offset:576
	s_waitcnt vmcnt(7) lgkmcnt(0)
	v_pk_fma_f32 v[114:115], v[202:203], v[24:25], v[114:115] op_sel_hi:[1, 0, 1]
	v_pk_fma_f32 v[112:113], v[200:201], v[24:25], v[112:113] op_sel_hi:[1, 0, 1]
	v_pk_fma_f32 v[110:111], v[202:203], v[24:25], v[110:111] op_sel:[0, 1, 0]
	v_pk_fma_f32 v[108:109], v[200:201], v[24:25], v[108:109] op_sel:[0, 1, 0]
	v_mov_b32_e32 v24, v27
	v_pk_fma_f32 v[106:107], v[202:203], v[26:27], v[106:107] op_sel_hi:[1, 0, 1]
	v_pk_fma_f32 v[104:105], v[200:201], v[26:27], v[104:105] op_sel_hi:[1, 0, 1]
	v_pk_fma_f32 v[130:131], v[202:203], v[24:25], v[130:131] op_sel_hi:[1, 0, 1]
	v_pk_fma_f32 v[128:129], v[200:201], v[24:25], v[128:129] op_sel_hi:[1, 0, 1]
	ds_read_b128 v[24:27], v116 offset:592
	s_waitcnt lgkmcnt(0)
	v_pk_fma_f32 v[98:99], v[202:203], v[24:25], v[98:99] op_sel_hi:[1, 0, 1]
	v_pk_fma_f32 v[96:97], v[200:201], v[24:25], v[96:97] op_sel_hi:[1, 0, 1]
	v_pk_fma_f32 v[94:95], v[202:203], v[24:25], v[94:95] op_sel:[0, 1, 0]
	v_pk_fma_f32 v[92:93], v[200:201], v[24:25], v[92:93] op_sel:[0, 1, 0]
	v_mov_b32_e32 v24, v27
	v_pk_fma_f32 v[90:91], v[202:203], v[26:27], v[90:91] op_sel_hi:[1, 0, 1]
	v_pk_fma_f32 v[88:89], v[200:201], v[26:27], v[88:89] op_sel_hi:[1, 0, 1]
	v_pk_fma_f32 v[134:135], v[202:203], v[24:25], v[102:103] op_sel_hi:[1, 0, 1]
	v_pk_fma_f32 v[136:137], v[200:201], v[24:25], v[100:101] op_sel_hi:[1, 0, 1]
	ds_read_b128 v[24:27], v116 offset:608
	s_waitcnt lgkmcnt(0)
	v_pk_fma_f32 v[82:83], v[202:203], v[24:25], v[82:83] op_sel_hi:[1, 0, 1]
	v_pk_fma_f32 v[80:81], v[200:201], v[24:25], v[80:81] op_sel_hi:[1, 0, 1]
	v_pk_fma_f32 v[78:79], v[202:203], v[24:25], v[78:79] op_sel:[0, 1, 0]
	v_pk_fma_f32 v[76:77], v[200:201], v[24:25], v[76:77] op_sel:[0, 1, 0]
	v_mov_b32_e32 v24, v27
	v_pk_fma_f32 v[74:75], v[202:203], v[26:27], v[74:75] op_sel_hi:[1, 0, 1]
	v_pk_fma_f32 v[72:73], v[200:201], v[26:27], v[72:73] op_sel_hi:[1, 0, 1]
	v_pk_fma_f32 v[138:139], v[202:203], v[24:25], v[86:87] op_sel_hi:[1, 0, 1]
	v_pk_fma_f32 v[140:141], v[200:201], v[24:25], v[84:85] op_sel_hi:[1, 0, 1]
	ds_read_b128 v[24:27], v116 offset:624
	s_waitcnt lgkmcnt(0)
	v_pk_fma_f32 v[66:67], v[202:203], v[24:25], v[66:67] op_sel_hi:[1, 0, 1]
	v_pk_fma_f32 v[64:65], v[200:201], v[24:25], v[64:65] op_sel_hi:[1, 0, 1]
	v_pk_fma_f32 v[62:63], v[202:203], v[24:25], v[62:63] op_sel:[0, 1, 0]
	v_pk_fma_f32 v[60:61], v[200:201], v[24:25], v[60:61] op_sel:[0, 1, 0]
	v_mov_b32_e32 v24, v27
	v_pk_fma_f32 v[58:59], v[202:203], v[26:27], v[58:59] op_sel_hi:[1, 0, 1]
	v_pk_fma_f32 v[56:57], v[200:201], v[26:27], v[56:57] op_sel_hi:[1, 0, 1]
	v_pk_fma_f32 v[142:143], v[202:203], v[24:25], v[70:71] op_sel_hi:[1, 0, 1]
	v_pk_fma_f32 v[144:145], v[200:201], v[24:25], v[68:69] op_sel_hi:[1, 0, 1]
	ds_read_b128 v[24:27], v116 offset:640
	s_waitcnt lgkmcnt(0)
	v_pk_fma_f32 v[50:51], v[202:203], v[24:25], v[50:51] op_sel_hi:[1, 0, 1]
	v_pk_fma_f32 v[48:49], v[200:201], v[24:25], v[48:49] op_sel_hi:[1, 0, 1]
	v_pk_fma_f32 v[46:47], v[202:203], v[24:25], v[46:47] op_sel:[0, 1, 0]
	v_pk_fma_f32 v[44:45], v[200:201], v[24:25], v[44:45] op_sel:[0, 1, 0]
	v_mov_b32_e32 v24, v27
	v_pk_fma_f32 v[42:43], v[202:203], v[26:27], v[42:43] op_sel_hi:[1, 0, 1]
	v_pk_fma_f32 v[40:41], v[200:201], v[26:27], v[40:41] op_sel_hi:[1, 0, 1]
	v_pk_fma_f32 v[146:147], v[202:203], v[24:25], v[54:55] op_sel_hi:[1, 0, 1]
	v_pk_fma_f32 v[148:149], v[200:201], v[24:25], v[52:53] op_sel_hi:[1, 0, 1]
	ds_read_b128 v[24:27], v116 offset:656
	s_waitcnt lgkmcnt(0)
	v_pk_fma_f32 v[34:35], v[202:203], v[24:25], v[34:35] op_sel_hi:[1, 0, 1]
	v_pk_fma_f32 v[32:33], v[200:201], v[24:25], v[32:33] op_sel_hi:[1, 0, 1]
	v_pk_fma_f32 v[30:31], v[202:203], v[24:25], v[30:31] op_sel:[0, 1, 0]
	v_pk_fma_f32 v[28:29], v[200:201], v[24:25], v[28:29] op_sel:[0, 1, 0]
	v_mov_b32_e32 v24, v27
	v_pk_fma_f32 v[132:133], v[200:201], v[26:27], v[132:133] op_sel_hi:[1, 0, 1]
	v_pk_fma_f32 v[154:155], v[200:201], v[24:25], v[124:125] op_sel_hi:[1, 0, 1]
	v_lshl_add_u64 v[20:21], v[126:127], 0, s[34:35]
	v_pk_fma_f32 v[150:151], v[202:203], v[26:27], v[36:37] op_sel_hi:[1, 0, 1]
	v_pk_fma_f32 v[152:153], v[202:203], v[24:25], v[38:39] op_sel_hi:[1, 0, 1]
	global_load_dwordx4 v[200:203], v[208:209], off
	v_lshl_add_u64 v[208:209], v[208:209], 0, s[34:35]
	ds_read_b128 v[24:27], v116 offset:672
	ds_read_b128 v[124:127], v116 offset:752
	s_waitcnt vmcnt(7) lgkmcnt(1)
; #define LAS __attribute__((address_space(3)))
; __device__ __forceinline__ void gemv24_item(const float* W, int N, int j0, LAS float* sc, LAS float* red, float (&res)[6], const int tid) {
;     ...
;     const float* w = W + (size_t)(ks * 64) * N + j0 + cg * 4;
; #pragma unroll 8
;     for (int kk = 0; kk < 64; ++kk) {
;         const f32x4 wv = *(const f32x4*)(w + (size_t)kk * N);
;         const LAS f32x4* s4 = (const LAS f32x4*)(sc + (ks * 64 + kk) * 24);
; #pragma unroll
;         for (int b4 = 0; b4 < 6; ++b4) { const f32x4 s = s4[b4]; acc[4 * b4] += wv * s[0]; acc[4 * b4 + 1] += wv * s[1]; acc[4 * b4 + 2] += wv * s[2]; acc[4 * b4 + 3] += wv * s[3]; }
;     }
	v_pk_fma_f32 v[114:115], v[206:207], v[24:25], v[114:115] op_sel_hi:[1, 0, 1]
	v_pk_fma_f32 v[112:113], v[204:205], v[24:25], v[112:113] op_sel_hi:[1, 0, 1]
	v_pk_fma_f32 v[110:111], v[206:207], v[24:25], v[110:111] op_sel:[0, 1, 0]
	v_pk_fma_f32 v[108:109], v[204:205], v[24:25], v[108:109] op_sel:[0, 1, 0]
	v_mov_b32_e32 v24, v27
	v_pk_fma_f32 v[106:107], v[206:207], v[26:27], v[106:107] op_sel_hi:[1, 0, 1]
	v_pk_fma_f32 v[104:105], v[204:205], v[26:27], v[104:105] op_sel_hi:[1, 0, 1]
	v_pk_fma_f32 v[102:103], v[206:207], v[24:25], v[130:131] op_sel_hi:[1, 0, 1]
	v_pk_fma_f32 v[100:101], v[204:205], v[24:25], v[128:129] op_sel_hi:[1, 0, 1]
	ds_read_b128 v[24:27], v116 offset:688
	s_waitcnt lgkmcnt(1)
	v_pk_fma_f32 v[34:35], v[206:207], v[124:125], v[34:35] op_sel_hi:[1, 0, 1]
	v_pk_fma_f32 v[32:33], v[204:205], v[124:125], v[32:33] op_sel_hi:[1, 0, 1]
	v_pk_fma_f32 v[30:31], v[206:207], v[124:125], v[30:31] op_sel:[0, 1, 0]
	v_pk_fma_f32 v[28:29], v[204:205], v[124:125], v[28:29] op_sel:[0, 1, 0]
	s_waitcnt lgkmcnt(0)
	v_pk_fma_f32 v[98:99], v[206:207], v[24:25], v[98:99] op_sel_hi:[1, 0, 1]
	v_pk_fma_f32 v[96:97], v[204:205], v[24:25], v[96:97] op_sel_hi:[1, 0, 1]
	v_pk_fma_f32 v[94:95], v[206:207], v[24:25], v[94:95] op_sel:[0, 1, 0]
	v_pk_fma_f32 v[92:93], v[204:205], v[24:25], v[92:93] op_sel:[0, 1, 0]
	v_mov_b32_e32 v24, v27
	v_pk_fma_f32 v[90:91], v[206:207], v[26:27], v[90:91] op_sel_hi:[1, 0, 1]
	v_pk_fma_f32 v[88:89], v[204:205], v[26:27], v[88:89] op_sel_hi:[1, 0, 1]
	v_pk_fma_f32 v[86:87], v[206:207], v[24:25], v[134:135] op_sel_hi:[1, 0, 1]
	v_pk_fma_f32 v[84:85], v[204:205], v[24:25], v[136:137] op_sel_hi:[1, 0, 1]
	ds_read_b128 v[24:27], v116 offset:704
	s_waitcnt lgkmcnt(0)
	v_pk_fma_f32 v[82:83], v[206:207], v[24:25], v[82:83] op_sel_hi:[1, 0, 1]
	v_pk_fma_f32 v[80:81], v[204:205], v[24:25], v[80:81] op_sel_hi:[1, 0, 1]
	v_pk_fma_f32 v[78:79], v[206:207], v[24:25], v[78:79] op_sel:[0, 1, 0]
	v_pk_fma_f32 v[76:77], v[204:205], v[24:25], v[76:77] op_sel:[0, 1, 0]
	v_mov_b32_e32 v24, v27
	v_pk_fma_f32 v[74:75], v[206:207], v[26:27], v[74:75] op_sel_hi:[1, 0, 1]
	v_pk_fma_f32 v[72:73], v[204:205], v[26:27], v[72:73] op_sel_hi:[1, 0, 1]
	v_pk_fma_f32 v[70:71], v[206:207], v[24:25], v[138:139] op_sel_hi:[1, 0, 1]
	v_pk_fma_f32 v[68:69], v[204:205], v[24:25], v[140:141] op_sel_hi:[1, 0, 1]
	ds_read_b128 v[24:27], v116 offset:720
	s_waitcnt lgkmcnt(0)
	v_pk_fma_f32 v[66:67], v[206:207], v[24:25], v[66:67] op_sel_hi:[1, 0, 1]
	v_pk_fma_f32 v[64:65], v[204:205], v[24:25], v[64:65] op_sel_hi:[1, 0, 1]
	v_pk_fma_f32 v[62:63], v[206:207], v[24:25], v[62:63] op_sel:[0, 1, 0]
	v_pk_fma_f32 v[60:61], v[204:205], v[24:25], v[60:61] op_sel:[0, 1, 0]
	v_mov_b32_e32 v24, v27
	v_pk_fma_f32 v[58:59], v[206:207], v[26:27], v[58:59] op_sel_hi:[1, 0, 1]
	v_pk_fma_f32 v[56:57], v[204:205], v[26:27], v[56:57] op_sel_hi:[1, 0, 1]
	v_pk_fma_f32 v[54:55], v[206:207], v[24:25], v[142:143] op_sel_hi:[1, 0, 1]
	v_pk_fma_f32 v[52:53], v[204:205], v[24:25], v[144:145] op_sel_hi:[1, 0, 1]
	ds_read_b128 v[24:27], v116 offset:736
	v_mov_b32_e32 v116, v127
	s_waitcnt lgkmcnt(0)
	v_pk_fma_f32 v[50:51], v[206:207], v[24:25], v[50:51] op_sel_hi:[1, 0, 1]
	v_pk_fma_f32 v[48:49], v[204:205], v[24:25], v[48:49] op_sel_hi:[1, 0, 1]
	v_pk_fma_f32 v[46:47], v[206:207], v[24:25], v[46:47] op_sel:[0, 1, 0]
	v_pk_fma_f32 v[44:45], v[204:205], v[24:25], v[44:45] op_sel:[0, 1, 0]
	v_mov_b32_e32 v24, v27
	v_pk_fma_f32 v[42:43], v[206:207], v[26:27], v[42:43] op_sel_hi:[1, 0, 1]
	v_pk_fma_f32 v[40:41], v[204:205], v[26:27], v[40:41] op_sel_hi:[1, 0, 1]
	v_pk_fma_f32 v[38:39], v[206:207], v[24:25], v[146:147] op_sel_hi:[1, 0, 1]
	v_pk_fma_f32 v[36:37], v[204:205], v[24:25], v[148:149] op_sel_hi:[1, 0, 1]
	v_pk_fma_f32 v[26:27], v[206:207], v[126:127], v[150:151] op_sel_hi:[1, 0, 1]
	v_pk_fma_f32 v[24:25], v[204:205], v[126:127], v[132:133] op_sel_hi:[1, 0, 1]
	v_pk_fma_f32 v[22:23], v[206:207], v[116:117], v[152:153] op_sel_hi:[1, 0, 1]
	v_pk_fma_f32 v[20:21], v[204:205], v[116:117], v[154:155] op_sel_hi:[1, 0, 1]
	global_load_dwordx4 v[204:207], v[208:209], off
	v_lshl_add_u64 v[208:209], v[208:209], 0, s[34:35]
	s_cbranch_scc0 .LBB0_436
.Lgemv_last_shw:
	v_add_u32_e32 v116, s31, v122
	ds_read_b128 v[128:131], v116
	ds_read_b128 v[132:135], v116 offset:16
	ds_read_b128 v[136:139], v116 offset:32
	ds_read_b128 v[140:143], v116 offset:48
	s_addk_i32 s31, 0x300
	s_cmpk_eq_i32 s31, 0x1800
	s_waitcnt vmcnt(7) lgkmcnt(3)
	v_pk_fma_f32 v[114:115], v[178:179], v[128:129], v[114:115] op_sel_hi:[1, 0, 1]
	v_pk_fma_f32 v[112:113], v[176:177], v[128:129], v[112:113] op_sel_hi:[1, 0, 1]
	v_pk_fma_f32 v[110:111], v[178:179], v[128:129], v[110:111] op_sel:[0, 1, 0]
	v_pk_fma_f32 v[108:109], v[176:177], v[128:129], v[108:109] op_sel:[0, 1, 0]
	v_mov_b32_e32 v128, v131
	v_pk_fma_f32 v[102:103], v[178:179], v[128:129], v[102:103] op_sel_hi:[1, 0, 1]
	v_pk_fma_f32 v[100:101], v[176:177], v[128:129], v[100:101] op_sel_hi:[1, 0, 1]
	s_waitcnt lgkmcnt(2)
	v_mov_b32_e32 v128, v135
	v_pk_fma_f32 v[86:87], v[178:179], v[128:129], v[86:87] op_sel_hi:[1, 0, 1]
	v_pk_fma_f32 v[84:85], v[176:177], v[128:129], v[84:85] op_sel_hi:[1, 0, 1]
	s_waitcnt lgkmcnt(1)
	v_mov_b32_e32 v128, v139
	v_pk_fma_f32 v[70:71], v[178:179], v[128:129], v[70:71] op_sel_hi:[1, 0, 1]
	v_pk_fma_f32 v[68:69], v[176:177], v[128:129], v[68:69] op_sel_hi:[1, 0, 1]
	s_waitcnt lgkmcnt(0)
; #define LAS __attribute__((address_space(3)))
; __device__ __forceinline__ void gemv24_item(const float* W, int N, int j0, LAS float* sc, LAS float* red, float (&res)[6], const int tid) {
;     ...
;     for (int kk = 0; kk < 64; ++kk) {
;         const f32x4 wv = *(const f32x4*)(w + (size_t)kk * N);
;         const LAS f32x4* s4 = (const LAS f32x4*)(sc + (ks * 64 + kk) * 24);
; #pragma unroll
;         for (int b4 = 0; b4 < 6; ++b4) { const f32x4 s = s4[b4]; acc[4 * b4] += wv * s[0]; acc[4 * b4 + 1] += wv * s[1]; acc[4 * b4 + 2] += wv * s[2]; acc[4 * b4 + 3] += wv * s[3]; }
;     }
	v_mov_b32_e32 v128, v143
	v_pk_fma_f32 v[106:107], v[178:179], v[130:131], v[106:107] op_sel_hi:[1, 0, 1]
	v_pk_fma_f32 v[104:105], v[176:177], v[130:131], v[104:105] op_sel_hi:[1, 0, 1]
	v_pk_fma_f32 v[54:55], v[178:179], v[128:129], v[54:55] op_sel_hi:[1, 0, 1]
	v_pk_fma_f32 v[52:53], v[176:177], v[128:129], v[52:53] op_sel_hi:[1, 0, 1]
	ds_read_b128 v[128:131], v116 offset:64
	v_pk_fma_f32 v[98:99], v[178:179], v[132:133], v[98:99] op_sel_hi:[1, 0, 1]
	v_pk_fma_f32 v[96:97], v[176:177], v[132:133], v[96:97] op_sel_hi:[1, 0, 1]
	v_pk_fma_f32 v[94:95], v[178:179], v[132:133], v[94:95] op_sel:[0, 1, 0]
	v_pk_fma_f32 v[92:93], v[176:177], v[132:133], v[92:93] op_sel:[0, 1, 0]
	s_waitcnt lgkmcnt(0)
	v_pk_fma_f32 v[50:51], v[178:179], v[128:129], v[50:51] op_sel_hi:[1, 0, 1]
	v_pk_fma_f32 v[48:49], v[176:177], v[128:129], v[48:49] op_sel_hi:[1, 0, 1]
	v_pk_fma_f32 v[46:47], v[178:179], v[128:129], v[46:47] op_sel:[0, 1, 0]
	v_pk_fma_f32 v[44:45], v[176:177], v[128:129], v[44:45] op_sel:[0, 1, 0]
	v_mov_b32_e32 v128, v131
	v_pk_fma_f32 v[42:43], v[178:179], v[130:131], v[42:43] op_sel_hi:[1, 0, 1]
	v_pk_fma_f32 v[40:41], v[176:177], v[130:131], v[40:41] op_sel_hi:[1, 0, 1]
	v_pk_fma_f32 v[38:39], v[178:179], v[128:129], v[38:39] op_sel_hi:[1, 0, 1]
	v_pk_fma_f32 v[36:37], v[176:177], v[128:129], v[36:37] op_sel_hi:[1, 0, 1]
	ds_read_b128 v[128:131], v116 offset:80
	v_lshl_add_u64 v[132:133], v[18:19], 0, s[34:35]
	v_pk_fma_f32 v[90:91], v[178:179], v[134:135], v[90:91] op_sel_hi:[1, 0, 1]
	v_pk_fma_f32 v[88:89], v[176:177], v[134:135], v[88:89] op_sel_hi:[1, 0, 1]
	v_pk_fma_f32 v[82:83], v[178:179], v[136:137], v[82:83] op_sel_hi:[1, 0, 1]
	s_waitcnt lgkmcnt(0)
	v_pk_fma_f32 v[34:35], v[178:179], v[128:129], v[34:35] op_sel_hi:[1, 0, 1]
	v_pk_fma_f32 v[32:33], v[176:177], v[128:129], v[32:33] op_sel_hi:[1, 0, 1]
	v_pk_fma_f32 v[30:31], v[178:179], v[128:129], v[30:31] op_sel:[0, 1, 0]
	v_pk_fma_f32 v[28:29], v[176:177], v[128:129], v[28:29] op_sel:[0, 1, 0]
	v_mov_b32_e32 v128, v131
	v_pk_fma_f32 v[80:81], v[176:177], v[136:137], v[80:81] op_sel_hi:[1, 0, 1]
	v_pk_fma_f32 v[78:79], v[178:179], v[136:137], v[78:79] op_sel:[0, 1, 0]
	v_pk_fma_f32 v[76:77], v[176:177], v[136:137], v[76:77] op_sel:[0, 1, 0]
	v_pk_fma_f32 v[74:75], v[178:179], v[138:139], v[74:75] op_sel_hi:[1, 0, 1]
	v_pk_fma_f32 v[72:73], v[176:177], v[138:139], v[72:73] op_sel_hi:[1, 0, 1]
	v_pk_fma_f32 v[66:67], v[178:179], v[140:141], v[66:67] op_sel_hi:[1, 0, 1]
	v_pk_fma_f32 v[64:65], v[176:177], v[140:141], v[64:65] op_sel_hi:[1, 0, 1]
	v_pk_fma_f32 v[62:63], v[178:179], v[140:141], v[62:63] op_sel:[0, 1, 0]
	v_pk_fma_f32 v[60:61], v[176:177], v[140:141], v[60:61] op_sel:[0, 1, 0]
	v_pk_fma_f32 v[58:59], v[178:179], v[142:143], v[58:59] op_sel_hi:[1, 0, 1]
	v_pk_fma_f32 v[56:57], v[176:177], v[142:143], v[56:57] op_sel_hi:[1, 0, 1]
	v_pk_fma_f32 v[26:27], v[178:179], v[130:131], v[26:27] op_sel_hi:[1, 0, 1]
	v_pk_fma_f32 v[24:25], v[176:177], v[130:131], v[24:25] op_sel_hi:[1, 0, 1]
	v_pk_fma_f32 v[22:23], v[178:179], v[128:129], v[22:23] op_sel_hi:[1, 0, 1]
	v_pk_fma_f32 v[20:21], v[176:177], v[128:129], v[20:21] op_sel_hi:[1, 0, 1]
	ds_read_b128 v[128:131], v116 offset:96
	v_lshl_add_u64 v[18:19], v[18:19], 0, s[22:23]
	s_waitcnt vmcnt(6) lgkmcnt(0)
	v_pk_fma_f32 v[114:115], v[182:183], v[128:129], v[114:115] op_sel_hi:[1, 0, 1]
	v_pk_fma_f32 v[112:113], v[180:181], v[128:129], v[112:113] op_sel_hi:[1, 0, 1]
	v_pk_fma_f32 v[110:111], v[182:183], v[128:129], v[110:111] op_sel:[0, 1, 0]
	v_pk_fma_f32 v[108:109], v[180:181], v[128:129], v[108:109] op_sel:[0, 1, 0]
	v_mov_b32_e32 v128, v131
	v_pk_fma_f32 v[106:107], v[182:183], v[130:131], v[106:107] op_sel_hi:[1, 0, 1]
	v_pk_fma_f32 v[104:105], v[180:181], v[130:131], v[104:105] op_sel_hi:[1, 0, 1]
	v_pk_fma_f32 v[130:131], v[182:183], v[128:129], v[102:103] op_sel_hi:[1, 0, 1]
	v_pk_fma_f32 v[128:129], v[180:181], v[128:129], v[100:101] op_sel_hi:[1, 0, 1]
	ds_read_b128 v[100:103], v116 offset:112
	s_waitcnt lgkmcnt(0)
	v_pk_fma_f32 v[98:99], v[182:183], v[100:101], v[98:99] op_sel_hi:[1, 0, 1]
	v_pk_fma_f32 v[96:97], v[180:181], v[100:101], v[96:97] op_sel_hi:[1, 0, 1]
	v_pk_fma_f32 v[94:95], v[182:183], v[100:101], v[94:95] op_sel:[0, 1, 0]
	v_pk_fma_f32 v[92:93], v[180:181], v[100:101], v[92:93] op_sel:[0, 1, 0]
	v_mov_b32_e32 v100, v103
	v_pk_fma_f32 v[90:91], v[182:183], v[102:103], v[90:91] op_sel_hi:[1, 0, 1]
	v_pk_fma_f32 v[88:89], v[180:181], v[102:103], v[88:89] op_sel_hi:[1, 0, 1]
	v_pk_fma_f32 v[102:103], v[182:183], v[100:101], v[86:87] op_sel_hi:[1, 0, 1]
	v_pk_fma_f32 v[100:101], v[180:181], v[100:101], v[84:85] op_sel_hi:[1, 0, 1]
	ds_read_b128 v[84:87], v116 offset:128
	s_waitcnt lgkmcnt(0)
	v_pk_fma_f32 v[82:83], v[182:183], v[84:85], v[82:83] op_sel_hi:[1, 0, 1]
	v_pk_fma_f32 v[80:81], v[180:181], v[84:85], v[80:81] op_sel_hi:[1, 0, 1]
	v_pk_fma_f32 v[78:79], v[182:183], v[84:85], v[78:79] op_sel:[0, 1, 0]
	v_pk_fma_f32 v[76:77], v[180:181], v[84:85], v[76:77] op_sel:[0, 1, 0]
	v_mov_b32_e32 v84, v87
	v_pk_fma_f32 v[74:75], v[182:183], v[86:87], v[74:75] op_sel_hi:[1, 0, 1]
	v_pk_fma_f32 v[72:73], v[180:181], v[86:87], v[72:73] op_sel_hi:[1, 0, 1]
	v_pk_fma_f32 v[86:87], v[182:183], v[84:85], v[70:71] op_sel_hi:[1, 0, 1]
	v_pk_fma_f32 v[84:85], v[180:181], v[84:85], v[68:69] op_sel_hi:[1, 0, 1]
	ds_read_b128 v[68:71], v116 offset:144
	s_waitcnt lgkmcnt(0)
; #define LAS __attribute__((address_space(3)))
; __device__ __forceinline__ void gemv24_item(const float* W, int N, int j0, LAS float* sc, LAS float* red, float (&res)[6], const int tid) {
;     ...
;     for (int kk = 0; kk < 64; ++kk) {
;         const f32x4 wv = *(const f32x4*)(w + (size_t)kk * N);
;         const LAS f32x4* s4 = (const LAS f32x4*)(sc + (ks * 64 + kk) * 24);
; #pragma unroll
;         for (int b4 = 0; b4 < 6; ++b4) { const f32x4 s = s4[b4]; acc[4 * b4] += wv * s[0]; acc[4 * b4 + 1] += wv * s[1]; acc[4 * b4 + 2] += wv * s[2]; acc[4 * b4 + 3] += wv * s[3]; }
;     }
	v_pk_fma_f32 v[66:67], v[182:183], v[68:69], v[66:67] op_sel_hi:[1, 0, 1]
	v_pk_fma_f32 v[64:65], v[180:181], v[68:69], v[64:65] op_sel_hi:[1, 0, 1]
	v_pk_fma_f32 v[62:63], v[182:183], v[68:69], v[62:63] op_sel:[0, 1, 0]
	v_pk_fma_f32 v[60:61], v[180:181], v[68:69], v[60:61] op_sel:[0, 1, 0]
	v_mov_b32_e32 v68, v71
	v_pk_fma_f32 v[58:59], v[182:183], v[70:71], v[58:59] op_sel_hi:[1, 0, 1]
	v_pk_fma_f32 v[56:57], v[180:181], v[70:71], v[56:57] op_sel_hi:[1, 0, 1]
	v_pk_fma_f32 v[70:71], v[182:183], v[68:69], v[54:55] op_sel_hi:[1, 0, 1]
	v_pk_fma_f32 v[68:69], v[180:181], v[68:69], v[52:53] op_sel_hi:[1, 0, 1]
	ds_read_b128 v[52:55], v116 offset:160
	s_waitcnt lgkmcnt(0)
	v_pk_fma_f32 v[50:51], v[182:183], v[52:53], v[50:51] op_sel_hi:[1, 0, 1]
	v_pk_fma_f32 v[48:49], v[180:181], v[52:53], v[48:49] op_sel_hi:[1, 0, 1]
	v_pk_fma_f32 v[46:47], v[182:183], v[52:53], v[46:47] op_sel:[0, 1, 0]
	v_pk_fma_f32 v[44:45], v[180:181], v[52:53], v[44:45] op_sel:[0, 1, 0]
	v_mov_b32_e32 v52, v55
	v_pk_fma_f32 v[42:43], v[182:183], v[54:55], v[42:43] op_sel_hi:[1, 0, 1]
	v_pk_fma_f32 v[40:41], v[180:181], v[54:55], v[40:41] op_sel_hi:[1, 0, 1]
	v_pk_fma_f32 v[54:55], v[182:183], v[52:53], v[38:39] op_sel_hi:[1, 0, 1]
	v_pk_fma_f32 v[52:53], v[180:181], v[52:53], v[36:37] op_sel_hi:[1, 0, 1]
	ds_read_b128 v[36:39], v116 offset:176
	s_waitcnt lgkmcnt(0)
	v_pk_fma_f32 v[134:135], v[180:181], v[38:39], v[24:25] op_sel_hi:[1, 0, 1]
	v_mov_b32_e32 v24, v39
	v_pk_fma_f32 v[34:35], v[182:183], v[36:37], v[34:35] op_sel_hi:[1, 0, 1]
	v_pk_fma_f32 v[32:33], v[180:181], v[36:37], v[32:33] op_sel_hi:[1, 0, 1]
	v_pk_fma_f32 v[30:31], v[182:183], v[36:37], v[30:31] op_sel:[0, 1, 0]
	v_pk_fma_f32 v[28:29], v[180:181], v[36:37], v[28:29] op_sel:[0, 1, 0]
	v_pk_fma_f32 v[36:37], v[182:183], v[38:39], v[26:27] op_sel_hi:[1, 0, 1]
	v_pk_fma_f32 v[38:39], v[182:183], v[24:25], v[22:23] op_sel_hi:[1, 0, 1]
	v_lshl_add_u64 v[126:127], v[132:133], 0, s[34:35]
	v_pk_fma_f32 v[124:125], v[180:181], v[24:25], v[20:21] op_sel_hi:[1, 0, 1]
	ds_read_b128 v[24:27], v116 offset:192
	v_lshl_add_u64 v[126:127], v[126:127], 0, s[34:35]
	s_waitcnt vmcnt(5) lgkmcnt(0)
	v_pk_fma_f32 v[114:115], v[186:187], v[24:25], v[114:115] op_sel_hi:[1, 0, 1]
	v_pk_fma_f32 v[112:113], v[184:185], v[24:25], v[112:113] op_sel_hi:[1, 0, 1]
	v_pk_fma_f32 v[110:111], v[186:187], v[24:25], v[110:111] op_sel:[0, 1, 0]
	v_pk_fma_f32 v[108:109], v[184:185], v[24:25], v[108:109] op_sel:[0, 1, 0]
	v_mov_b32_e32 v24, v27
	v_pk_fma_f32 v[106:107], v[186:187], v[26:27], v[106:107] op_sel_hi:[1, 0, 1]
	v_pk_fma_f32 v[104:105], v[184:185], v[26:27], v[104:105] op_sel_hi:[1, 0, 1]
	v_pk_fma_f32 v[130:131], v[186:187], v[24:25], v[130:131] op_sel_hi:[1, 0, 1]
	v_pk_fma_f32 v[128:129], v[184:185], v[24:25], v[128:129] op_sel_hi:[1, 0, 1]
	ds_read_b128 v[24:27], v116 offset:208
	s_waitcnt lgkmcnt(0)
	v_pk_fma_f32 v[98:99], v[186:187], v[24:25], v[98:99] op_sel_hi:[1, 0, 1]
	v_pk_fma_f32 v[96:97], v[184:185], v[24:25], v[96:97] op_sel_hi:[1, 0, 1]
	v_pk_fma_f32 v[94:95], v[186:187], v[24:25], v[94:95] op_sel:[0, 1, 0]
	v_pk_fma_f32 v[92:93], v[184:185], v[24:25], v[92:93] op_sel:[0, 1, 0]
	v_mov_b32_e32 v24, v27
	v_pk_fma_f32 v[90:91], v[186:187], v[26:27], v[90:91] op_sel_hi:[1, 0, 1]
	v_pk_fma_f32 v[88:89], v[184:185], v[26:27], v[88:89] op_sel_hi:[1, 0, 1]
	v_pk_fma_f32 v[102:103], v[186:187], v[24:25], v[102:103] op_sel_hi:[1, 0, 1]
	v_pk_fma_f32 v[100:101], v[184:185], v[24:25], v[100:101] op_sel_hi:[1, 0, 1]
	ds_read_b128 v[24:27], v116 offset:224
	s_waitcnt lgkmcnt(0)
	v_pk_fma_f32 v[82:83], v[186:187], v[24:25], v[82:83] op_sel_hi:[1, 0, 1]
	v_pk_fma_f32 v[80:81], v[184:185], v[24:25], v[80:81] op_sel_hi:[1, 0, 1]
	v_pk_fma_f32 v[78:79], v[186:187], v[24:25], v[78:79] op_sel:[0, 1, 0]
	v_pk_fma_f32 v[76:77], v[184:185], v[24:25], v[76:77] op_sel:[0, 1, 0]
	v_mov_b32_e32 v24, v27
	v_pk_fma_f32 v[74:75], v[186:187], v[26:27], v[74:75] op_sel_hi:[1, 0, 1]
	v_pk_fma_f32 v[72:73], v[184:185], v[26:27], v[72:73] op_sel_hi:[1, 0, 1]
	v_pk_fma_f32 v[86:87], v[186:187], v[24:25], v[86:87] op_sel_hi:[1, 0, 1]
	v_pk_fma_f32 v[84:85], v[184:185], v[24:25], v[84:85] op_sel_hi:[1, 0, 1]
	ds_read_b128 v[24:27], v116 offset:240
	s_waitcnt lgkmcnt(0)
	v_pk_fma_f32 v[66:67], v[186:187], v[24:25], v[66:67] op_sel_hi:[1, 0, 1]
	v_pk_fma_f32 v[64:65], v[184:185], v[24:25], v[64:65] op_sel_hi:[1, 0, 1]
	v_pk_fma_f32 v[62:63], v[186:187], v[24:25], v[62:63] op_sel:[0, 1, 0]
	v_pk_fma_f32 v[60:61], v[184:185], v[24:25], v[60:61] op_sel:[0, 1, 0]
	v_mov_b32_e32 v24, v27
	v_pk_fma_f32 v[58:59], v[186:187], v[26:27], v[58:59] op_sel_hi:[1, 0, 1]
	v_pk_fma_f32 v[56:57], v[184:185], v[26:27], v[56:57] op_sel_hi:[1, 0, 1]
	v_pk_fma_f32 v[70:71], v[186:187], v[24:25], v[70:71] op_sel_hi:[1, 0, 1]
	v_pk_fma_f32 v[68:69], v[184:185], v[24:25], v[68:69] op_sel_hi:[1, 0, 1]
	ds_read_b128 v[24:27], v116 offset:256
	s_waitcnt lgkmcnt(0)
	v_pk_fma_f32 v[50:51], v[186:187], v[24:25], v[50:51] op_sel_hi:[1, 0, 1]
	v_pk_fma_f32 v[48:49], v[184:185], v[24:25], v[48:49] op_sel_hi:[1, 0, 1]
	v_pk_fma_f32 v[46:47], v[186:187], v[24:25], v[46:47] op_sel:[0, 1, 0]
	v_pk_fma_f32 v[44:45], v[184:185], v[24:25], v[44:45] op_sel:[0, 1, 0]
	v_mov_b32_e32 v24, v27
	v_pk_fma_f32 v[42:43], v[186:187], v[26:27], v[42:43] op_sel_hi:[1, 0, 1]
	v_pk_fma_f32 v[40:41], v[184:185], v[26:27], v[40:41] op_sel_hi:[1, 0, 1]
	v_pk_fma_f32 v[54:55], v[186:187], v[24:25], v[54:55] op_sel_hi:[1, 0, 1]
	v_pk_fma_f32 v[52:53], v[184:185], v[24:25], v[52:53] op_sel_hi:[1, 0, 1]
	ds_read_b128 v[24:27], v116 offset:272
	s_waitcnt lgkmcnt(0)
; #define LAS __attribute__((address_space(3)))
; __device__ __forceinline__ void gemv24_item(const float* W, int N, int j0, LAS float* sc, LAS float* red, float (&res)[6], const int tid) {
;     ...
;     for (int kk = 0; kk < 64; ++kk) {
;         const f32x4 wv = *(const f32x4*)(w + (size_t)kk * N);
;         const LAS f32x4* s4 = (const LAS f32x4*)(sc + (ks * 64 + kk) * 24);
; #pragma unroll
;         for (int b4 = 0; b4 < 6; ++b4) { const f32x4 s = s4[b4]; acc[4 * b4] += wv * s[0]; acc[4 * b4 + 1] += wv * s[1]; acc[4 * b4 + 2] += wv * s[2]; acc[4 * b4 + 3] += wv * s[3]; }
;     }
	v_pk_fma_f32 v[34:35], v[186:187], v[24:25], v[34:35] op_sel_hi:[1, 0, 1]
	v_pk_fma_f32 v[32:33], v[184:185], v[24:25], v[32:33] op_sel_hi:[1, 0, 1]
	v_pk_fma_f32 v[30:31], v[186:187], v[24:25], v[30:31] op_sel:[0, 1, 0]
	v_pk_fma_f32 v[28:29], v[184:185], v[24:25], v[28:29] op_sel:[0, 1, 0]
	v_mov_b32_e32 v24, v27
	v_pk_fma_f32 v[36:37], v[186:187], v[26:27], v[36:37] op_sel_hi:[1, 0, 1]
	v_pk_fma_f32 v[132:133], v[184:185], v[26:27], v[134:135] op_sel_hi:[1, 0, 1]
	v_pk_fma_f32 v[38:39], v[186:187], v[24:25], v[38:39] op_sel_hi:[1, 0, 1]
	v_pk_fma_f32 v[124:125], v[184:185], v[24:25], v[124:125] op_sel_hi:[1, 0, 1]
	ds_read_b128 v[24:27], v116 offset:288
	v_lshl_add_u64 v[126:127], v[126:127], 0, s[34:35]
	s_waitcnt vmcnt(4) lgkmcnt(0)
	v_pk_fma_f32 v[114:115], v[190:191], v[24:25], v[114:115] op_sel_hi:[1, 0, 1]
	v_pk_fma_f32 v[112:113], v[188:189], v[24:25], v[112:113] op_sel_hi:[1, 0, 1]
	v_pk_fma_f32 v[110:111], v[190:191], v[24:25], v[110:111] op_sel:[0, 1, 0]
	v_pk_fma_f32 v[108:109], v[188:189], v[24:25], v[108:109] op_sel:[0, 1, 0]
	v_mov_b32_e32 v24, v27
	v_pk_fma_f32 v[106:107], v[190:191], v[26:27], v[106:107] op_sel_hi:[1, 0, 1]
	v_pk_fma_f32 v[104:105], v[188:189], v[26:27], v[104:105] op_sel_hi:[1, 0, 1]
	v_pk_fma_f32 v[130:131], v[190:191], v[24:25], v[130:131] op_sel_hi:[1, 0, 1]
	v_pk_fma_f32 v[128:129], v[188:189], v[24:25], v[128:129] op_sel_hi:[1, 0, 1]
	ds_read_b128 v[24:27], v116 offset:304
	s_waitcnt lgkmcnt(0)
	v_pk_fma_f32 v[98:99], v[190:191], v[24:25], v[98:99] op_sel_hi:[1, 0, 1]
	v_pk_fma_f32 v[96:97], v[188:189], v[24:25], v[96:97] op_sel_hi:[1, 0, 1]
	v_pk_fma_f32 v[94:95], v[190:191], v[24:25], v[94:95] op_sel:[0, 1, 0]
	v_pk_fma_f32 v[92:93], v[188:189], v[24:25], v[92:93] op_sel:[0, 1, 0]
	v_mov_b32_e32 v24, v27
	v_pk_fma_f32 v[90:91], v[190:191], v[26:27], v[90:91] op_sel_hi:[1, 0, 1]
	v_pk_fma_f32 v[88:89], v[188:189], v[26:27], v[88:89] op_sel_hi:[1, 0, 1]
	v_pk_fma_f32 v[102:103], v[190:191], v[24:25], v[102:103] op_sel_hi:[1, 0, 1]
	v_pk_fma_f32 v[100:101], v[188:189], v[24:25], v[100:101] op_sel_hi:[1, 0, 1]
	ds_read_b128 v[24:27], v116 offset:320
	s_waitcnt lgkmcnt(0)
	v_pk_fma_f32 v[82:83], v[190:191], v[24:25], v[82:83] op_sel_hi:[1, 0, 1]
	v_pk_fma_f32 v[80:81], v[188:189], v[24:25], v[80:81] op_sel_hi:[1, 0, 1]
	v_pk_fma_f32 v[78:79], v[190:191], v[24:25], v[78:79] op_sel:[0, 1, 0]
	v_pk_fma_f32 v[76:77], v[188:189], v[24:25], v[76:77] op_sel:[0, 1, 0]
	v_mov_b32_e32 v24, v27
	v_pk_fma_f32 v[74:75], v[190:191], v[26:27], v[74:75] op_sel_hi:[1, 0, 1]
	v_pk_fma_f32 v[72:73], v[188:189], v[26:27], v[72:73] op_sel_hi:[1, 0, 1]
	v_pk_fma_f32 v[86:87], v[190:191], v[24:25], v[86:87] op_sel_hi:[1, 0, 1]
	v_pk_fma_f32 v[84:85], v[188:189], v[24:25], v[84:85] op_sel_hi:[1, 0, 1]
	ds_read_b128 v[24:27], v116 offset:336
	s_waitcnt lgkmcnt(0)
	v_pk_fma_f32 v[66:67], v[190:191], v[24:25], v[66:67] op_sel_hi:[1, 0, 1]
	v_pk_fma_f32 v[64:65], v[188:189], v[24:25], v[64:65] op_sel_hi:[1, 0, 1]
	v_pk_fma_f32 v[62:63], v[190:191], v[24:25], v[62:63] op_sel:[0, 1, 0]
	v_pk_fma_f32 v[60:61], v[188:189], v[24:25], v[60:61] op_sel:[0, 1, 0]
	v_mov_b32_e32 v24, v27
	v_pk_fma_f32 v[58:59], v[190:191], v[26:27], v[58:59] op_sel_hi:[1, 0, 1]
	v_pk_fma_f32 v[56:57], v[188:189], v[26:27], v[56:57] op_sel_hi:[1, 0, 1]
	v_pk_fma_f32 v[70:71], v[190:191], v[24:25], v[70:71] op_sel_hi:[1, 0, 1]
	v_pk_fma_f32 v[68:69], v[188:189], v[24:25], v[68:69] op_sel_hi:[1, 0, 1]
	ds_read_b128 v[24:27], v116 offset:352
	s_waitcnt lgkmcnt(0)
	v_pk_fma_f32 v[50:51], v[190:191], v[24:25], v[50:51] op_sel_hi:[1, 0, 1]
	v_pk_fma_f32 v[48:49], v[188:189], v[24:25], v[48:49] op_sel_hi:[1, 0, 1]
	v_pk_fma_f32 v[46:47], v[190:191], v[24:25], v[46:47] op_sel:[0, 1, 0]
	v_pk_fma_f32 v[44:45], v[188:189], v[24:25], v[44:45] op_sel:[0, 1, 0]
	v_mov_b32_e32 v24, v27
	v_pk_fma_f32 v[42:43], v[190:191], v[26:27], v[42:43] op_sel_hi:[1, 0, 1]
	v_pk_fma_f32 v[40:41], v[188:189], v[26:27], v[40:41] op_sel_hi:[1, 0, 1]
	v_pk_fma_f32 v[54:55], v[190:191], v[24:25], v[54:55] op_sel_hi:[1, 0, 1]
	v_pk_fma_f32 v[52:53], v[188:189], v[24:25], v[52:53] op_sel_hi:[1, 0, 1]
	ds_read_b128 v[24:27], v116 offset:368
	s_waitcnt lgkmcnt(0)
	v_pk_fma_f32 v[34:35], v[190:191], v[24:25], v[34:35] op_sel_hi:[1, 0, 1]
	v_pk_fma_f32 v[32:33], v[188:189], v[24:25], v[32:33] op_sel_hi:[1, 0, 1]
	v_pk_fma_f32 v[30:31], v[190:191], v[24:25], v[30:31] op_sel:[0, 1, 0]
	v_pk_fma_f32 v[28:29], v[188:189], v[24:25], v[28:29] op_sel:[0, 1, 0]
	v_mov_b32_e32 v24, v27
	v_pk_fma_f32 v[36:37], v[190:191], v[26:27], v[36:37] op_sel_hi:[1, 0, 1]
	v_pk_fma_f32 v[132:133], v[188:189], v[26:27], v[132:133] op_sel_hi:[1, 0, 1]
	v_pk_fma_f32 v[38:39], v[190:191], v[24:25], v[38:39] op_sel_hi:[1, 0, 1]
	v_pk_fma_f32 v[124:125], v[188:189], v[24:25], v[124:125] op_sel_hi:[1, 0, 1]
	ds_read_b128 v[24:27], v116 offset:384
	v_lshl_add_u64 v[126:127], v[126:127], 0, s[34:35]
	s_waitcnt vmcnt(3) lgkmcnt(0)
	v_pk_fma_f32 v[114:115], v[194:195], v[24:25], v[114:115] op_sel_hi:[1, 0, 1]
	v_pk_fma_f32 v[112:113], v[192:193], v[24:25], v[112:113] op_sel_hi:[1, 0, 1]
	v_pk_fma_f32 v[110:111], v[194:195], v[24:25], v[110:111] op_sel:[0, 1, 0]
	v_pk_fma_f32 v[108:109], v[192:193], v[24:25], v[108:109] op_sel:[0, 1, 0]
	v_mov_b32_e32 v24, v27
	v_pk_fma_f32 v[106:107], v[194:195], v[26:27], v[106:107] op_sel_hi:[1, 0, 1]
	v_pk_fma_f32 v[104:105], v[192:193], v[26:27], v[104:105] op_sel_hi:[1, 0, 1]
	v_pk_fma_f32 v[130:131], v[194:195], v[24:25], v[130:131] op_sel_hi:[1, 0, 1]
	v_pk_fma_f32 v[128:129], v[192:193], v[24:25], v[128:129] op_sel_hi:[1, 0, 1]
	ds_read_b128 v[24:27], v116 offset:400
	s_waitcnt lgkmcnt(0)
; #define LAS __attribute__((address_space(3)))
; __device__ __forceinline__ void gemv24_item(const float* W, int N, int j0, LAS float* sc, LAS float* red, float (&res)[6], const int tid) {
;     ...
;     for (int kk = 0; kk < 64; ++kk) {
;         const f32x4 wv = *(const f32x4*)(w + (size_t)kk * N);
;         const LAS f32x4* s4 = (const LAS f32x4*)(sc + (ks * 64 + kk) * 24);
; #pragma unroll
;         for (int b4 = 0; b4 < 6; ++b4) { const f32x4 s = s4[b4]; acc[4 * b4] += wv * s[0]; acc[4 * b4 + 1] += wv * s[1]; acc[4 * b4 + 2] += wv * s[2]; acc[4 * b4 + 3] += wv * s[3]; }
;     }
	v_pk_fma_f32 v[98:99], v[194:195], v[24:25], v[98:99] op_sel_hi:[1, 0, 1]
	v_pk_fma_f32 v[96:97], v[192:193], v[24:25], v[96:97] op_sel_hi:[1, 0, 1]
	v_pk_fma_f32 v[94:95], v[194:195], v[24:25], v[94:95] op_sel:[0, 1, 0]
	v_pk_fma_f32 v[92:93], v[192:193], v[24:25], v[92:93] op_sel:[0, 1, 0]
	v_mov_b32_e32 v24, v27
	v_pk_fma_f32 v[90:91], v[194:195], v[26:27], v[90:91] op_sel_hi:[1, 0, 1]
	v_pk_fma_f32 v[88:89], v[192:193], v[26:27], v[88:89] op_sel_hi:[1, 0, 1]
	v_pk_fma_f32 v[102:103], v[194:195], v[24:25], v[102:103] op_sel_hi:[1, 0, 1]
	v_pk_fma_f32 v[100:101], v[192:193], v[24:25], v[100:101] op_sel_hi:[1, 0, 1]
	ds_read_b128 v[24:27], v116 offset:416
	s_waitcnt lgkmcnt(0)
	v_pk_fma_f32 v[82:83], v[194:195], v[24:25], v[82:83] op_sel_hi:[1, 0, 1]
	v_pk_fma_f32 v[80:81], v[192:193], v[24:25], v[80:81] op_sel_hi:[1, 0, 1]
	v_pk_fma_f32 v[78:79], v[194:195], v[24:25], v[78:79] op_sel:[0, 1, 0]
	v_pk_fma_f32 v[76:77], v[192:193], v[24:25], v[76:77] op_sel:[0, 1, 0]
	v_mov_b32_e32 v24, v27
	v_pk_fma_f32 v[74:75], v[194:195], v[26:27], v[74:75] op_sel_hi:[1, 0, 1]
	v_pk_fma_f32 v[72:73], v[192:193], v[26:27], v[72:73] op_sel_hi:[1, 0, 1]
	v_pk_fma_f32 v[86:87], v[194:195], v[24:25], v[86:87] op_sel_hi:[1, 0, 1]
	v_pk_fma_f32 v[84:85], v[192:193], v[24:25], v[84:85] op_sel_hi:[1, 0, 1]
	ds_read_b128 v[24:27], v116 offset:432
	s_waitcnt lgkmcnt(0)
	v_pk_fma_f32 v[66:67], v[194:195], v[24:25], v[66:67] op_sel_hi:[1, 0, 1]
	v_pk_fma_f32 v[64:65], v[192:193], v[24:25], v[64:65] op_sel_hi:[1, 0, 1]
	v_pk_fma_f32 v[62:63], v[194:195], v[24:25], v[62:63] op_sel:[0, 1, 0]
	v_pk_fma_f32 v[60:61], v[192:193], v[24:25], v[60:61] op_sel:[0, 1, 0]
	v_mov_b32_e32 v24, v27
	v_pk_fma_f32 v[58:59], v[194:195], v[26:27], v[58:59] op_sel_hi:[1, 0, 1]
	v_pk_fma_f32 v[56:57], v[192:193], v[26:27], v[56:57] op_sel_hi:[1, 0, 1]
	v_pk_fma_f32 v[70:71], v[194:195], v[24:25], v[70:71] op_sel_hi:[1, 0, 1]
	v_pk_fma_f32 v[68:69], v[192:193], v[24:25], v[68:69] op_sel_hi:[1, 0, 1]
	ds_read_b128 v[24:27], v116 offset:448
	s_waitcnt lgkmcnt(0)
	v_pk_fma_f32 v[50:51], v[194:195], v[24:25], v[50:51] op_sel_hi:[1, 0, 1]
	v_pk_fma_f32 v[48:49], v[192:193], v[24:25], v[48:49] op_sel_hi:[1, 0, 1]
	v_pk_fma_f32 v[46:47], v[194:195], v[24:25], v[46:47] op_sel:[0, 1, 0]
	v_pk_fma_f32 v[44:45], v[192:193], v[24:25], v[44:45] op_sel:[0, 1, 0]
	v_mov_b32_e32 v24, v27
	v_pk_fma_f32 v[42:43], v[194:195], v[26:27], v[42:43] op_sel_hi:[1, 0, 1]
	v_pk_fma_f32 v[40:41], v[192:193], v[26:27], v[40:41] op_sel_hi:[1, 0, 1]
	v_pk_fma_f32 v[54:55], v[194:195], v[24:25], v[54:55] op_sel_hi:[1, 0, 1]
	v_pk_fma_f32 v[52:53], v[192:193], v[24:25], v[52:53] op_sel_hi:[1, 0, 1]
	ds_read_b128 v[24:27], v116 offset:464
	s_waitcnt lgkmcnt(0)
	v_pk_fma_f32 v[34:35], v[194:195], v[24:25], v[34:35] op_sel_hi:[1, 0, 1]
	v_pk_fma_f32 v[32:33], v[192:193], v[24:25], v[32:33] op_sel_hi:[1, 0, 1]
	v_pk_fma_f32 v[30:31], v[194:195], v[24:25], v[30:31] op_sel:[0, 1, 0]
	v_pk_fma_f32 v[28:29], v[192:193], v[24:25], v[28:29] op_sel:[0, 1, 0]
	v_mov_b32_e32 v24, v27
	v_pk_fma_f32 v[36:37], v[194:195], v[26:27], v[36:37] op_sel_hi:[1, 0, 1]
	v_pk_fma_f32 v[132:133], v[192:193], v[26:27], v[132:133] op_sel_hi:[1, 0, 1]
	v_pk_fma_f32 v[38:39], v[194:195], v[24:25], v[38:39] op_sel_hi:[1, 0, 1]
	v_pk_fma_f32 v[124:125], v[192:193], v[24:25], v[124:125] op_sel_hi:[1, 0, 1]
	ds_read_b128 v[24:27], v116 offset:480
	v_lshl_add_u64 v[126:127], v[126:127], 0, s[34:35]
	s_waitcnt vmcnt(2) lgkmcnt(0)
	v_pk_fma_f32 v[114:115], v[198:199], v[24:25], v[114:115] op_sel_hi:[1, 0, 1]
	v_pk_fma_f32 v[112:113], v[196:197], v[24:25], v[112:113] op_sel_hi:[1, 0, 1]
	v_pk_fma_f32 v[110:111], v[198:199], v[24:25], v[110:111] op_sel:[0, 1, 0]
	v_pk_fma_f32 v[108:109], v[196:197], v[24:25], v[108:109] op_sel:[0, 1, 0]
	v_mov_b32_e32 v24, v27
	v_pk_fma_f32 v[106:107], v[198:199], v[26:27], v[106:107] op_sel_hi:[1, 0, 1]
	v_pk_fma_f32 v[104:105], v[196:197], v[26:27], v[104:105] op_sel_hi:[1, 0, 1]
	v_pk_fma_f32 v[130:131], v[198:199], v[24:25], v[130:131] op_sel_hi:[1, 0, 1]
	v_pk_fma_f32 v[128:129], v[196:197], v[24:25], v[128:129] op_sel_hi:[1, 0, 1]
	ds_read_b128 v[24:27], v116 offset:496
	s_waitcnt lgkmcnt(0)
	v_pk_fma_f32 v[98:99], v[198:199], v[24:25], v[98:99] op_sel_hi:[1, 0, 1]
	v_pk_fma_f32 v[96:97], v[196:197], v[24:25], v[96:97] op_sel_hi:[1, 0, 1]
	v_pk_fma_f32 v[94:95], v[198:199], v[24:25], v[94:95] op_sel:[0, 1, 0]
	v_pk_fma_f32 v[92:93], v[196:197], v[24:25], v[92:93] op_sel:[0, 1, 0]
	v_mov_b32_e32 v24, v27
	v_pk_fma_f32 v[90:91], v[198:199], v[26:27], v[90:91] op_sel_hi:[1, 0, 1]
	v_pk_fma_f32 v[88:89], v[196:197], v[26:27], v[88:89] op_sel_hi:[1, 0, 1]
	v_pk_fma_f32 v[102:103], v[198:199], v[24:25], v[102:103] op_sel_hi:[1, 0, 1]
	v_pk_fma_f32 v[100:101], v[196:197], v[24:25], v[100:101] op_sel_hi:[1, 0, 1]
	ds_read_b128 v[24:27], v116 offset:512
	s_waitcnt lgkmcnt(0)
	v_pk_fma_f32 v[82:83], v[198:199], v[24:25], v[82:83] op_sel_hi:[1, 0, 1]
	v_pk_fma_f32 v[80:81], v[196:197], v[24:25], v[80:81] op_sel_hi:[1, 0, 1]
	v_pk_fma_f32 v[78:79], v[198:199], v[24:25], v[78:79] op_sel:[0, 1, 0]
	v_pk_fma_f32 v[76:77], v[196:197], v[24:25], v[76:77] op_sel:[0, 1, 0]
	v_mov_b32_e32 v24, v27
	v_pk_fma_f32 v[74:75], v[198:199], v[26:27], v[74:75] op_sel_hi:[1, 0, 1]
	v_pk_fma_f32 v[72:73], v[196:197], v[26:27], v[72:73] op_sel_hi:[1, 0, 1]
	v_pk_fma_f32 v[86:87], v[198:199], v[24:25], v[86:87] op_sel_hi:[1, 0, 1]
	v_pk_fma_f32 v[84:85], v[196:197], v[24:25], v[84:85] op_sel_hi:[1, 0, 1]
	ds_read_b128 v[24:27], v116 offset:528
	s_waitcnt lgkmcnt(0)
; #define LAS __attribute__((address_space(3)))
; __device__ __forceinline__ void gemv24_item(const float* W, int N, int j0, LAS float* sc, LAS float* red, float (&res)[6], const int tid) {
;     ...
;     for (int kk = 0; kk < 64; ++kk) {
;         const f32x4 wv = *(const f32x4*)(w + (size_t)kk * N);
;         const LAS f32x4* s4 = (const LAS f32x4*)(sc + (ks * 64 + kk) * 24);
; #pragma unroll
;         for (int b4 = 0; b4 < 6; ++b4) { const f32x4 s = s4[b4]; acc[4 * b4] += wv * s[0]; acc[4 * b4 + 1] += wv * s[1]; acc[4 * b4 + 2] += wv * s[2]; acc[4 * b4 + 3] += wv * s[3]; }
;     }
	v_pk_fma_f32 v[66:67], v[198:199], v[24:25], v[66:67] op_sel_hi:[1, 0, 1]
	v_pk_fma_f32 v[64:65], v[196:197], v[24:25], v[64:65] op_sel_hi:[1, 0, 1]
	v_pk_fma_f32 v[62:63], v[198:199], v[24:25], v[62:63] op_sel:[0, 1, 0]
	v_pk_fma_f32 v[60:61], v[196:197], v[24:25], v[60:61] op_sel:[0, 1, 0]
	v_mov_b32_e32 v24, v27
	v_pk_fma_f32 v[58:59], v[198:199], v[26:27], v[58:59] op_sel_hi:[1, 0, 1]
	v_pk_fma_f32 v[56:57], v[196:197], v[26:27], v[56:57] op_sel_hi:[1, 0, 1]
	v_pk_fma_f32 v[70:71], v[198:199], v[24:25], v[70:71] op_sel_hi:[1, 0, 1]
	v_pk_fma_f32 v[68:69], v[196:197], v[24:25], v[68:69] op_sel_hi:[1, 0, 1]
	ds_read_b128 v[24:27], v116 offset:544
	s_waitcnt lgkmcnt(0)
	v_pk_fma_f32 v[50:51], v[198:199], v[24:25], v[50:51] op_sel_hi:[1, 0, 1]
	v_pk_fma_f32 v[48:49], v[196:197], v[24:25], v[48:49] op_sel_hi:[1, 0, 1]
	v_pk_fma_f32 v[46:47], v[198:199], v[24:25], v[46:47] op_sel:[0, 1, 0]
	v_pk_fma_f32 v[44:45], v[196:197], v[24:25], v[44:45] op_sel:[0, 1, 0]
	v_mov_b32_e32 v24, v27
	v_pk_fma_f32 v[42:43], v[198:199], v[26:27], v[42:43] op_sel_hi:[1, 0, 1]
	v_pk_fma_f32 v[40:41], v[196:197], v[26:27], v[40:41] op_sel_hi:[1, 0, 1]
	v_pk_fma_f32 v[54:55], v[198:199], v[24:25], v[54:55] op_sel_hi:[1, 0, 1]
	v_pk_fma_f32 v[52:53], v[196:197], v[24:25], v[52:53] op_sel_hi:[1, 0, 1]
	ds_read_b128 v[24:27], v116 offset:560
	s_waitcnt lgkmcnt(0)
	v_pk_fma_f32 v[34:35], v[198:199], v[24:25], v[34:35] op_sel_hi:[1, 0, 1]
	v_pk_fma_f32 v[32:33], v[196:197], v[24:25], v[32:33] op_sel_hi:[1, 0, 1]
	v_pk_fma_f32 v[30:31], v[198:199], v[24:25], v[30:31] op_sel:[0, 1, 0]
	v_pk_fma_f32 v[28:29], v[196:197], v[24:25], v[28:29] op_sel:[0, 1, 0]
	v_mov_b32_e32 v24, v27
	v_pk_fma_f32 v[36:37], v[198:199], v[26:27], v[36:37] op_sel_hi:[1, 0, 1]
	v_pk_fma_f32 v[132:133], v[196:197], v[26:27], v[132:133] op_sel_hi:[1, 0, 1]
	v_pk_fma_f32 v[38:39], v[198:199], v[24:25], v[38:39] op_sel_hi:[1, 0, 1]
	v_pk_fma_f32 v[124:125], v[196:197], v[24:25], v[124:125] op_sel_hi:[1, 0, 1]
	ds_read_b128 v[24:27], v116 offset:576
	s_waitcnt vmcnt(1) lgkmcnt(0)
	v_pk_fma_f32 v[114:115], v[202:203], v[24:25], v[114:115] op_sel_hi:[1, 0, 1]
	v_pk_fma_f32 v[112:113], v[200:201], v[24:25], v[112:113] op_sel_hi:[1, 0, 1]
	v_pk_fma_f32 v[110:111], v[202:203], v[24:25], v[110:111] op_sel:[0, 1, 0]
	v_pk_fma_f32 v[108:109], v[200:201], v[24:25], v[108:109] op_sel:[0, 1, 0]
	v_mov_b32_e32 v24, v27
	v_pk_fma_f32 v[106:107], v[202:203], v[26:27], v[106:107] op_sel_hi:[1, 0, 1]
	v_pk_fma_f32 v[104:105], v[200:201], v[26:27], v[104:105] op_sel_hi:[1, 0, 1]
	v_pk_fma_f32 v[130:131], v[202:203], v[24:25], v[130:131] op_sel_hi:[1, 0, 1]
	v_pk_fma_f32 v[128:129], v[200:201], v[24:25], v[128:129] op_sel_hi:[1, 0, 1]
	ds_read_b128 v[24:27], v116 offset:592
	s_waitcnt lgkmcnt(0)
	v_pk_fma_f32 v[98:99], v[202:203], v[24:25], v[98:99] op_sel_hi:[1, 0, 1]
	v_pk_fma_f32 v[96:97], v[200:201], v[24:25], v[96:97] op_sel_hi:[1, 0, 1]
	v_pk_fma_f32 v[94:95], v[202:203], v[24:25], v[94:95] op_sel:[0, 1, 0]
	v_pk_fma_f32 v[92:93], v[200:201], v[24:25], v[92:93] op_sel:[0, 1, 0]
	v_mov_b32_e32 v24, v27
	v_pk_fma_f32 v[90:91], v[202:203], v[26:27], v[90:91] op_sel_hi:[1, 0, 1]
	v_pk_fma_f32 v[88:89], v[200:201], v[26:27], v[88:89] op_sel_hi:[1, 0, 1]
	v_pk_fma_f32 v[134:135], v[202:203], v[24:25], v[102:103] op_sel_hi:[1, 0, 1]
	v_pk_fma_f32 v[136:137], v[200:201], v[24:25], v[100:101] op_sel_hi:[1, 0, 1]
	ds_read_b128 v[24:27], v116 offset:608
	s_waitcnt lgkmcnt(0)
	v_pk_fma_f32 v[82:83], v[202:203], v[24:25], v[82:83] op_sel_hi:[1, 0, 1]
	v_pk_fma_f32 v[80:81], v[200:201], v[24:25], v[80:81] op_sel_hi:[1, 0, 1]
	v_pk_fma_f32 v[78:79], v[202:203], v[24:25], v[78:79] op_sel:[0, 1, 0]
	v_pk_fma_f32 v[76:77], v[200:201], v[24:25], v[76:77] op_sel:[0, 1, 0]
	v_mov_b32_e32 v24, v27
	v_pk_fma_f32 v[74:75], v[202:203], v[26:27], v[74:75] op_sel_hi:[1, 0, 1]
	v_pk_fma_f32 v[72:73], v[200:201], v[26:27], v[72:73] op_sel_hi:[1, 0, 1]
	v_pk_fma_f32 v[138:139], v[202:203], v[24:25], v[86:87] op_sel_hi:[1, 0, 1]
	v_pk_fma_f32 v[140:141], v[200:201], v[24:25], v[84:85] op_sel_hi:[1, 0, 1]
	ds_read_b128 v[24:27], v116 offset:624
	s_waitcnt lgkmcnt(0)
	v_pk_fma_f32 v[66:67], v[202:203], v[24:25], v[66:67] op_sel_hi:[1, 0, 1]
	v_pk_fma_f32 v[64:65], v[200:201], v[24:25], v[64:65] op_sel_hi:[1, 0, 1]
	v_pk_fma_f32 v[62:63], v[202:203], v[24:25], v[62:63] op_sel:[0, 1, 0]
	v_pk_fma_f32 v[60:61], v[200:201], v[24:25], v[60:61] op_sel:[0, 1, 0]
	v_mov_b32_e32 v24, v27
	v_pk_fma_f32 v[58:59], v[202:203], v[26:27], v[58:59] op_sel_hi:[1, 0, 1]
	v_pk_fma_f32 v[56:57], v[200:201], v[26:27], v[56:57] op_sel_hi:[1, 0, 1]
	v_pk_fma_f32 v[142:143], v[202:203], v[24:25], v[70:71] op_sel_hi:[1, 0, 1]
	v_pk_fma_f32 v[144:145], v[200:201], v[24:25], v[68:69] op_sel_hi:[1, 0, 1]
	ds_read_b128 v[24:27], v116 offset:640
	s_waitcnt lgkmcnt(0)
	v_pk_fma_f32 v[50:51], v[202:203], v[24:25], v[50:51] op_sel_hi:[1, 0, 1]
	v_pk_fma_f32 v[48:49], v[200:201], v[24:25], v[48:49] op_sel_hi:[1, 0, 1]
	v_pk_fma_f32 v[46:47], v[202:203], v[24:25], v[46:47] op_sel:[0, 1, 0]
	v_pk_fma_f32 v[44:45], v[200:201], v[24:25], v[44:45] op_sel:[0, 1, 0]
	v_mov_b32_e32 v24, v27
	v_pk_fma_f32 v[42:43], v[202:203], v[26:27], v[42:43] op_sel_hi:[1, 0, 1]
	v_pk_fma_f32 v[40:41], v[200:201], v[26:27], v[40:41] op_sel_hi:[1, 0, 1]
	v_pk_fma_f32 v[146:147], v[202:203], v[24:25], v[54:55] op_sel_hi:[1, 0, 1]
	v_pk_fma_f32 v[148:149], v[200:201], v[24:25], v[52:53] op_sel_hi:[1, 0, 1]
	ds_read_b128 v[24:27], v116 offset:656
	s_waitcnt lgkmcnt(0)
; #define LAS __attribute__((address_space(3)))
; __device__ __forceinline__ void gemv24_item(const float* W, int N, int j0, LAS float* sc, LAS float* red, float (&res)[6], const int tid) {
;     ...
;     for (int kk = 0; kk < 64; ++kk) {
;         const f32x4 wv = *(const f32x4*)(w + (size_t)kk * N);
;         const LAS f32x4* s4 = (const LAS f32x4*)(sc + (ks * 64 + kk) * 24);
; #pragma unroll
;         for (int b4 = 0; b4 < 6; ++b4) { const f32x4 s = s4[b4]; acc[4 * b4] += wv * s[0]; acc[4 * b4 + 1] += wv * s[1]; acc[4 * b4 + 2] += wv * s[2]; acc[4 * b4 + 3] += wv * s[3]; }
;     }
; #pragma unroll
;     for (int bg = 0; bg < 3; ++bg) {
; #pragma unroll
;         for (int bb = 0; bb < 8; ++bb) {
;             f32x4 a = acc[8 * bg + bb];
;             a[0] += __shfl_xor(a[0], 32); a[1] += __shfl_xor(a[1], 32); a[2] += __shfl_xor(a[2], 32); a[3] += __shfl_xor(a[3], 32);
;             if (lane < 32) *(LAS f32x4*)(red + ((wave * 8 + bb) * 128 + cg * 4)) = a;
;         }
	v_pk_fma_f32 v[34:35], v[202:203], v[24:25], v[34:35] op_sel_hi:[1, 0, 1]
	v_pk_fma_f32 v[32:33], v[200:201], v[24:25], v[32:33] op_sel_hi:[1, 0, 1]
	v_pk_fma_f32 v[30:31], v[202:203], v[24:25], v[30:31] op_sel:[0, 1, 0]
	v_pk_fma_f32 v[28:29], v[200:201], v[24:25], v[28:29] op_sel:[0, 1, 0]
	v_mov_b32_e32 v24, v27
	v_pk_fma_f32 v[132:133], v[200:201], v[26:27], v[132:133] op_sel_hi:[1, 0, 1]
	v_pk_fma_f32 v[154:155], v[200:201], v[24:25], v[124:125] op_sel_hi:[1, 0, 1]
	v_lshl_add_u64 v[20:21], v[126:127], 0, s[34:35]
	v_pk_fma_f32 v[150:151], v[202:203], v[26:27], v[36:37] op_sel_hi:[1, 0, 1]
	v_pk_fma_f32 v[152:153], v[202:203], v[24:25], v[38:39] op_sel_hi:[1, 0, 1]
	ds_read_b128 v[24:27], v116 offset:672
	ds_read_b128 v[124:127], v116 offset:752
	s_waitcnt vmcnt(0) lgkmcnt(1)
	v_pk_fma_f32 v[114:115], v[206:207], v[24:25], v[114:115] op_sel_hi:[1, 0, 1]
	v_pk_fma_f32 v[112:113], v[204:205], v[24:25], v[112:113] op_sel_hi:[1, 0, 1]
	v_pk_fma_f32 v[110:111], v[206:207], v[24:25], v[110:111] op_sel:[0, 1, 0]
	v_pk_fma_f32 v[108:109], v[204:205], v[24:25], v[108:109] op_sel:[0, 1, 0]
	v_mov_b32_e32 v24, v27
	v_pk_fma_f32 v[106:107], v[206:207], v[26:27], v[106:107] op_sel_hi:[1, 0, 1]
	v_pk_fma_f32 v[104:105], v[204:205], v[26:27], v[104:105] op_sel_hi:[1, 0, 1]
	v_pk_fma_f32 v[102:103], v[206:207], v[24:25], v[130:131] op_sel_hi:[1, 0, 1]
	v_pk_fma_f32 v[100:101], v[204:205], v[24:25], v[128:129] op_sel_hi:[1, 0, 1]
	ds_read_b128 v[24:27], v116 offset:688
	s_waitcnt lgkmcnt(1)
	v_pk_fma_f32 v[34:35], v[206:207], v[124:125], v[34:35] op_sel_hi:[1, 0, 1]
	v_pk_fma_f32 v[32:33], v[204:205], v[124:125], v[32:33] op_sel_hi:[1, 0, 1]
	v_pk_fma_f32 v[30:31], v[206:207], v[124:125], v[30:31] op_sel:[0, 1, 0]
	v_pk_fma_f32 v[28:29], v[204:205], v[124:125], v[28:29] op_sel:[0, 1, 0]
	s_waitcnt lgkmcnt(0)
	v_pk_fma_f32 v[98:99], v[206:207], v[24:25], v[98:99] op_sel_hi:[1, 0, 1]
	v_pk_fma_f32 v[96:97], v[204:205], v[24:25], v[96:97] op_sel_hi:[1, 0, 1]
	v_pk_fma_f32 v[94:95], v[206:207], v[24:25], v[94:95] op_sel:[0, 1, 0]
	v_pk_fma_f32 v[92:93], v[204:205], v[24:25], v[92:93] op_sel:[0, 1, 0]
	v_mov_b32_e32 v24, v27
	v_pk_fma_f32 v[90:91], v[206:207], v[26:27], v[90:91] op_sel_hi:[1, 0, 1]
	v_pk_fma_f32 v[88:89], v[204:205], v[26:27], v[88:89] op_sel_hi:[1, 0, 1]
	v_pk_fma_f32 v[86:87], v[206:207], v[24:25], v[134:135] op_sel_hi:[1, 0, 1]
	v_pk_fma_f32 v[84:85], v[204:205], v[24:25], v[136:137] op_sel_hi:[1, 0, 1]
	ds_read_b128 v[24:27], v116 offset:704
	s_waitcnt lgkmcnt(0)
	v_pk_fma_f32 v[82:83], v[206:207], v[24:25], v[82:83] op_sel_hi:[1, 0, 1]
	v_pk_fma_f32 v[80:81], v[204:205], v[24:25], v[80:81] op_sel_hi:[1, 0, 1]
	v_pk_fma_f32 v[78:79], v[206:207], v[24:25], v[78:79] op_sel:[0, 1, 0]
	v_pk_fma_f32 v[76:77], v[204:205], v[24:25], v[76:77] op_sel:[0, 1, 0]
	v_mov_b32_e32 v24, v27
	v_pk_fma_f32 v[74:75], v[206:207], v[26:27], v[74:75] op_sel_hi:[1, 0, 1]
	v_pk_fma_f32 v[72:73], v[204:205], v[26:27], v[72:73] op_sel_hi:[1, 0, 1]
	v_pk_fma_f32 v[70:71], v[206:207], v[24:25], v[138:139] op_sel_hi:[1, 0, 1]
	v_pk_fma_f32 v[68:69], v[204:205], v[24:25], v[140:141] op_sel_hi:[1, 0, 1]
	ds_read_b128 v[24:27], v116 offset:720
	s_waitcnt lgkmcnt(0)
	v_pk_fma_f32 v[66:67], v[206:207], v[24:25], v[66:67] op_sel_hi:[1, 0, 1]
	v_pk_fma_f32 v[64:65], v[204:205], v[24:25], v[64:65] op_sel_hi:[1, 0, 1]
	v_pk_fma_f32 v[62:63], v[206:207], v[24:25], v[62:63] op_sel:[0, 1, 0]
	v_pk_fma_f32 v[60:61], v[204:205], v[24:25], v[60:61] op_sel:[0, 1, 0]
	v_mov_b32_e32 v24, v27
	v_pk_fma_f32 v[58:59], v[206:207], v[26:27], v[58:59] op_sel_hi:[1, 0, 1]
	v_pk_fma_f32 v[56:57], v[204:205], v[26:27], v[56:57] op_sel_hi:[1, 0, 1]
	v_pk_fma_f32 v[54:55], v[206:207], v[24:25], v[142:143] op_sel_hi:[1, 0, 1]
	v_pk_fma_f32 v[52:53], v[204:205], v[24:25], v[144:145] op_sel_hi:[1, 0, 1]
	ds_read_b128 v[24:27], v116 offset:736
	v_mov_b32_e32 v116, v127
	s_waitcnt lgkmcnt(0)
	v_pk_fma_f32 v[50:51], v[206:207], v[24:25], v[50:51] op_sel_hi:[1, 0, 1]
	v_pk_fma_f32 v[48:49], v[204:205], v[24:25], v[48:49] op_sel_hi:[1, 0, 1]
	v_pk_fma_f32 v[46:47], v[206:207], v[24:25], v[46:47] op_sel:[0, 1, 0]
	v_pk_fma_f32 v[44:45], v[204:205], v[24:25], v[44:45] op_sel:[0, 1, 0]
	v_mov_b32_e32 v24, v27
	v_pk_fma_f32 v[42:43], v[206:207], v[26:27], v[42:43] op_sel_hi:[1, 0, 1]
	v_pk_fma_f32 v[40:41], v[204:205], v[26:27], v[40:41] op_sel_hi:[1, 0, 1]
	v_pk_fma_f32 v[38:39], v[206:207], v[24:25], v[146:147] op_sel_hi:[1, 0, 1]
	v_pk_fma_f32 v[36:37], v[204:205], v[24:25], v[148:149] op_sel_hi:[1, 0, 1]
	v_pk_fma_f32 v[26:27], v[206:207], v[126:127], v[150:151] op_sel_hi:[1, 0, 1]
	v_pk_fma_f32 v[24:25], v[204:205], v[126:127], v[132:133] op_sel_hi:[1, 0, 1]
	v_pk_fma_f32 v[22:23], v[206:207], v[116:117], v[152:153] op_sel_hi:[1, 0, 1]
	v_pk_fma_f32 v[20:21], v[204:205], v[116:117], v[154:155] op_sel_hi:[1, 0, 1]
	v_xor_b32_e32 v18, 32, v226
	v_cmp_lt_i32_e32 vcc, v18, v228
	s_nop 1
	v_cndmask_b32_e32 v18, v226, v18, vcc
	v_lshlrev_b32_e32 v123, 2, v18
	ds_bpermute_b32 v18, v123, v112
	ds_bpermute_b32 v19, v123, v113
	ds_bpermute_b32 v116, v123, v114
	ds_bpermute_b32 v117, v123, v115
	s_and_saveexec_b64 s[34:35], s[44:45]
	s_cbranch_execz .LBB0_439
	s_waitcnt lgkmcnt(0)
	v_pk_add_f32 v[114:115], v[114:115], v[116:117]
	v_pk_add_f32 v[112:113], v[112:113], v[18:19]
	ds_write_b128 v118, v[112:115]

; __device__ __forceinline__ void gemv24_item(const float* W, int N, int j0, LAS float* sc, LAS float* red, float (&res)[6], const int tid) {
;     ...
;     f32x4 acc[24];
; #pragma unroll
;     for (int b = 0; b < 24; ++b) acc[b] = (f32x4){0.f, 0.f, 0.f, 0.f};
;     const float* w = W + (size_t)(ks * 64) * N + j0 + cg * 4;
; #pragma unroll 8
;     for (int kk = 0; kk < 64; ++kk) {
;         const f32x4 wv = *(const f32x4*)(w + (size_t)kk * N);
; __device__ __forceinline__ void phase_mod(const Params& p, LAS unsigned char* lds, const int tid) {
;     ...
;     for (int item = blockIdx.x; item < 288; item += gridDim.x) {
;         const int l = item / 72, j0 = (item % 72) * 128;
;         float res[6];
;         gemv24_item(p.w_mod + (size_t)l * 1024 * 9216, 9216, j0, sc, red, res, tid);
.LBB0_522:
	s_mul_hi_i32 s0, s22, 0x38e38e39
	s_lshr_b32 s1, s0, 31
	s_ashr_i32 s0, s0, 4
	s_add_i32 s36, s0, s1
	s_mul_i32 s0, s36, 0x48
	s_sub_i32 s0, s22, s0
	s_lshl_b32 s28, s0, 7
	s_ashr_i32 s29, s28, 31
	s_mul_i32 s16, s36, 0x2400000
	s_lshl_b64 s[0:1], s[28:29], 2
	s_mul_hi_i32 s9, s36, 0x2400000
	s_add_u32 s34, s16, s0
	s_addc_u32 s35, s9, s1
	v_mov_b32_e32 v24, 0
	s_mov_b64 s[30:31], 0
	v_mov_b32_e32 v25, v24
	v_mov_b32_e32 v26, v24
	v_mov_b32_e32 v27, v24
	v_mov_b32_e32 v28, v24
	v_mov_b32_e32 v29, v24
	v_mov_b32_e32 v30, v24
	v_mov_b32_e32 v31, v24
	v_mov_b32_e32 v32, v24
	v_mov_b32_e32 v33, v24
	v_mov_b32_e32 v34, v24
	v_mov_b32_e32 v35, v24
	v_mov_b32_e32 v40, v24
	v_mov_b32_e32 v41, v24
	v_mov_b32_e32 v42, v24
	v_mov_b32_e32 v43, v24
	v_mov_b32_e32 v36, v24
	v_mov_b32_e32 v37, v24
	v_mov_b32_e32 v38, v24
	v_mov_b32_e32 v39, v24
	v_mov_b32_e32 v44, v24
	v_mov_b32_e32 v45, v24
	v_mov_b32_e32 v46, v24
	v_mov_b32_e32 v47, v24
	v_mov_b32_e32 v48, v24
	v_mov_b32_e32 v49, v24
	v_mov_b32_e32 v50, v24
	v_mov_b32_e32 v51, v24
	v_mov_b32_e32 v52, v24
	v_mov_b32_e32 v53, v24
	v_mov_b32_e32 v54, v24
	v_mov_b32_e32 v55, v24
	v_mov_b32_e32 v56, v24
	v_mov_b32_e32 v57, v24
	v_mov_b32_e32 v58, v24
	v_mov_b32_e32 v59, v24
	v_mov_b32_e32 v64, v24
	v_mov_b32_e32 v65, v24
	v_mov_b32_e32 v66, v24
	v_mov_b32_e32 v67, v24
	v_mov_b32_e32 v70, v24
	v_mov_b32_e32 v71, v24
	v_mov_b32_e32 v76, v24
	v_mov_b32_e32 v77, v24
	v_mov_b32_e32 v86, v24
	v_mov_b32_e32 v87, v24
	v_mov_b32_e32 v92, v24
	v_mov_b32_e32 v93, v24
	v_mov_b32_e32 v60, v24
	v_mov_b32_e32 v61, v24
	v_mov_b32_e32 v62, v24
	v_mov_b32_e32 v63, v24
	v_mov_b32_e32 v68, v24
	v_mov_b32_e32 v69, v24
	v_mov_b32_e32 v72, v24
	v_mov_b32_e32 v73, v24
	v_mov_b32_e32 v82, v24
	v_mov_b32_e32 v83, v24
	v_mov_b32_e32 v88, v24
	v_mov_b32_e32 v89, v24
	v_mov_b32_e32 v98, v24
	v_mov_b32_e32 v99, v24
	v_mov_b32_e32 v104, v24
	v_mov_b32_e32 v105, v24
	v_mov_b32_e32 v74, v24
	v_mov_b32_e32 v75, v24
	v_mov_b32_e32 v78, v24
	v_mov_b32_e32 v79, v24
	v_mov_b32_e32 v90, v24
	v_mov_b32_e32 v91, v24
	v_mov_b32_e32 v94, v24
	v_mov_b32_e32 v95, v24
	v_mov_b32_e32 v102, v24
	v_mov_b32_e32 v103, v24
	v_mov_b32_e32 v106, v24
	v_mov_b32_e32 v107, v24
	v_mov_b32_e32 v112, v24
	v_mov_b32_e32 v113, v24
	v_mov_b32_e32 v114, v24
	v_mov_b32_e32 v115, v24
	v_mov_b32_e32 v80, v24
	v_mov_b32_e32 v81, v24
	v_mov_b32_e32 v84, v24
	v_mov_b32_e32 v85, v24
	v_mov_b32_e32 v96, v24
	v_mov_b32_e32 v97, v24
	v_mov_b32_e32 v100, v24
	v_mov_b32_e32 v101, v24
	v_mov_b32_e32 v108, v24
	v_mov_b32_e32 v109, v24
	v_mov_b32_e32 v110, v24
	v_mov_b32_e32 v111, v24
	v_mov_b32_e32 v116, v24
	v_mov_b32_e32 v117, v24
	v_mov_b32_e32 v118, v24
	v_mov_b32_e32 v119, v24
	v_mov_b32_e32 v174, v160
	v_lshl_add_u64 v[20:21], v[18:19], 0, s[34:35]
	v_lshl_add_u64 v[208:209], v[20:21], 0, s[30:31]
	global_load_dwordx4 v[176:179], v[208:209], off
	v_add_co_u32_e64 v208, s[42:43], s67, v208
	s_nop 1
	v_addc_co_u32_e64 v209, s[42:43], 0, v209, s[42:43]
	global_load_dwordx4 v[180:183], v[208:209], off
	v_add_co_u32_e64 v208, s[42:43], s67, v208
	s_nop 1
	v_addc_co_u32_e64 v209, s[42:43], 0, v209, s[42:43]
	global_load_dwordx4 v[184:187], v[208:209], off
	v_add_co_u32_e64 v208, s[42:43], s67, v208
	s_nop 1
	v_addc_co_u32_e64 v209, s[42:43], 0, v209, s[42:43]
	global_load_dwordx4 v[188:191], v[208:209], off
	v_add_co_u32_e64 v208, s[42:43], s67, v208
	s_nop 1
	v_addc_co_u32_e64 v209, s[42:43], 0, v209, s[42:43]
	global_load_dwordx4 v[192:195], v[208:209], off
	v_add_co_u32_e64 v208, s[42:43], s67, v208
	s_nop 1
	v_addc_co_u32_e64 v209, s[42:43], 0, v209, s[42:43]
	global_load_dwordx4 v[196:199], v[208:209], off
	v_add_co_u32_e64 v208, s[42:43], s67, v208
	s_nop 1
	v_addc_co_u32_e64 v209, s[42:43], 0, v209, s[42:43]
	global_load_dwordx4 v[200:203], v[208:209], off
	v_add_co_u32_e64 v208, s[42:43], s67, v208
	s_nop 1
	v_addc_co_u32_e64 v209, s[42:43], 0, v209, s[42:43]
	global_load_dwordx4 v[204:207], v[208:209], off
	v_add_co_u32_e64 v208, s[42:43], s67, v208
	s_nop 1
	v_addc_co_u32_e64 v209, s[42:43], 0, v209, s[42:43]
.LBB0_523:
	v_lshl_add_u64 v[22:23], v[20:21], 0, s[30:31]
	ds_read_b128 v[122:125], v174
	ds_read_b128 v[132:135], v174 offset:16
	ds_read_b128 v[136:139], v174 offset:32
	ds_read_b128 v[140:143], v174 offset:48
	s_mov_b32 s0, 0x24000
	s_add_u32 s30, s30, 0x48000
	s_addc_u32 s31, s31, 0
	s_cmp_eq_u32 s30, 0x1f8000
	s_waitcnt vmcnt(7) lgkmcnt(3)
	v_pk_fma_f32 v[120:121], v[176:177], v[124:125], v[96:97] op_sel_hi:[1, 0, 1]
	v_mov_b32_e32 v96, v125
	v_pk_fma_f32 v[118:119], v[178:179], v[122:123], v[118:119] op_sel_hi:[1, 0, 1]
	v_pk_fma_f32 v[128:129], v[176:177], v[122:123], v[116:117] op_sel_hi:[1, 0, 1]
	v_pk_fma_f32 v[116:117], v[178:179], v[122:123], v[110:111] op_sel:[0, 1, 0]
	v_pk_fma_f32 v[130:131], v[176:177], v[122:123], v[108:109] op_sel:[0, 1, 0]
	v_pk_fma_f32 v[122:123], v[178:179], v[124:125], v[100:101] op_sel_hi:[1, 0, 1]
	v_pk_fma_f32 v[124:125], v[176:177], v[96:97], v[80:81] op_sel_hi:[1, 0, 1]
	v_pk_fma_f32 v[126:127], v[178:179], v[96:97], v[84:85] op_sel_hi:[1, 0, 1]
	s_waitcnt lgkmcnt(2)
	v_pk_fma_f32 v[96:97], v[178:179], v[132:133], v[114:115] op_sel_hi:[1, 0, 1]
	v_pk_fma_f32 v[110:111], v[176:177], v[132:133], v[112:113] op_sel_hi:[1, 0, 1]
	v_pk_fma_f32 v[100:101], v[178:179], v[132:133], v[106:107] op_sel:[0, 1, 0]
	v_pk_fma_f32 v[112:113], v[176:177], v[132:133], v[102:103] op_sel:[0, 1, 0]
	v_pk_fma_f32 v[102:103], v[176:177], v[134:135], v[90:91] op_sel_hi:[1, 0, 1]
	v_pk_fma_f32 v[94:95], v[178:179], v[134:135], v[94:95] op_sel_hi:[1, 0, 1]
	v_mov_b32_e32 v80, v135
	ds_read_b128 v[132:135], v174 offset:64
	v_pk_fma_f32 v[106:107], v[176:177], v[80:81], v[74:75] op_sel_hi:[1, 0, 1]
	v_pk_fma_f32 v[108:109], v[178:179], v[80:81], v[78:79] op_sel_hi:[1, 0, 1]
	s_waitcnt lgkmcnt(2)
; #define LAS __attribute__((address_space(3)))
; __device__ __forceinline__ void gemv24_item(const float* W, int N, int j0, LAS float* sc, LAS float* red, float (&res)[6], const int tid) {
;     ...
;     const float* w = W + (size_t)(ks * 64) * N + j0 + cg * 4;
; #pragma unroll 8
;     for (int kk = 0; kk < 64; ++kk) {
;         const f32x4 wv = *(const f32x4*)(w + (size_t)kk * N);
;         const LAS f32x4* s4 = (const LAS f32x4*)(sc + (ks * 64 + kk) * 24);
; #pragma unroll
;         for (int b4 = 0; b4 < 6; ++b4) { const f32x4 s = s4[b4]; acc[4 * b4] += wv * s[0]; acc[4 * b4 + 1] += wv * s[1]; acc[4 * b4 + 2] += wv * s[2]; acc[4 * b4 + 3] += wv * s[3]; }
;     }
	v_pk_fma_f32 v[80:81], v[176:177], v[138:139], v[68:69] op_sel_hi:[1, 0, 1]
	v_mov_b32_e32 v68, v139
	v_pk_fma_f32 v[84:85], v[178:179], v[68:69], v[62:63] op_sel_hi:[1, 0, 1]
	s_waitcnt lgkmcnt(1)
	v_pk_fma_f32 v[62:63], v[178:179], v[140:141], v[76:77] op_sel:[0, 1, 0]
	v_mov_b32_e32 v76, v143
	v_pk_fma_f32 v[56:57], v[176:177], v[76:77], v[56:57] op_sel_hi:[1, 0, 1]
	v_pk_fma_f32 v[58:59], v[178:179], v[76:77], v[58:59] op_sel_hi:[1, 0, 1]
	s_waitcnt lgkmcnt(0)
	v_pk_fma_f32 v[54:55], v[178:179], v[132:133], v[54:55] op_sel_hi:[1, 0, 1]
	v_pk_fma_f32 v[52:53], v[176:177], v[132:133], v[52:53] op_sel_hi:[1, 0, 1]
	v_pk_fma_f32 v[50:51], v[178:179], v[132:133], v[50:51] op_sel:[0, 1, 0]
	v_pk_fma_f32 v[48:49], v[176:177], v[132:133], v[48:49] op_sel:[0, 1, 0]
	v_pk_fma_f32 v[44:45], v[176:177], v[134:135], v[44:45] op_sel_hi:[1, 0, 1]
	v_pk_fma_f32 v[46:47], v[178:179], v[134:135], v[46:47] op_sel_hi:[1, 0, 1]
	v_mov_b32_e32 v76, v135
	ds_read_b128 v[132:135], v174 offset:80
	v_pk_fma_f32 v[90:91], v[176:177], v[136:137], v[98:99] op_sel_hi:[1, 0, 1]
	v_pk_fma_f32 v[78:79], v[178:179], v[136:137], v[88:89] op_sel:[0, 1, 0]
	v_pk_fma_f32 v[88:89], v[176:177], v[136:137], v[82:83] op_sel:[0, 1, 0]
	v_pk_fma_f32 v[82:83], v[176:177], v[68:69], v[60:61] op_sel_hi:[1, 0, 1]
	s_waitcnt lgkmcnt(0)
	v_pk_fma_f32 v[98:99], v[176:177], v[132:133], v[40:41] op_sel_hi:[1, 0, 1]
	v_mov_b32_e32 v40, v135
	v_pk_fma_f32 v[68:69], v[176:177], v[140:141], v[86:87] op_sel_hi:[1, 0, 1]
	v_pk_fma_f32 v[70:71], v[176:177], v[140:141], v[70:71] op_sel:[0, 1, 0]
	v_pk_fma_f32 v[64:65], v[176:177], v[142:143], v[64:65] op_sel_hi:[1, 0, 1]
	v_pk_fma_f32 v[36:37], v[176:177], v[76:77], v[36:37] op_sel_hi:[1, 0, 1]
	v_pk_fma_f32 v[32:33], v[176:177], v[132:133], v[32:33] op_sel:[0, 1, 0]
	v_pk_fma_f32 v[28:29], v[176:177], v[134:135], v[28:29] op_sel_hi:[1, 0, 1]
	v_pk_fma_f32 v[24:25], v[176:177], v[40:41], v[24:25] op_sel_hi:[1, 0, 1]
	v_add_co_u32_e64 v0, s[42:43], s67, v22
	v_pk_fma_f32 v[74:75], v[178:179], v[136:137], v[104:105] op_sel_hi:[1, 0, 1]
	s_nop 0
	v_addc_co_u32_e64 v1, s[42:43], 0, v23, s[42:43]
	v_pk_fma_f32 v[72:73], v[178:179], v[138:139], v[72:73] op_sel_hi:[1, 0, 1]
	v_pk_fma_f32 v[60:61], v[178:179], v[140:141], v[92:93] op_sel_hi:[1, 0, 1]
	v_pk_fma_f32 v[66:67], v[178:179], v[142:143], v[66:67] op_sel_hi:[1, 0, 1]
	v_pk_fma_f32 v[38:39], v[178:179], v[76:77], v[38:39] op_sel_hi:[1, 0, 1]
	v_pk_fma_f32 v[92:93], v[178:179], v[132:133], v[42:43] op_sel_hi:[1, 0, 1]
	v_pk_fma_f32 v[34:35], v[178:179], v[132:133], v[34:35] op_sel:[0, 1, 0]
	v_pk_fma_f32 v[30:31], v[178:179], v[134:135], v[30:31] op_sel_hi:[1, 0, 1]
	v_pk_fma_f32 v[26:27], v[178:179], v[40:41], v[26:27] op_sel_hi:[1, 0, 1]
	global_load_dwordx4 v[176:179], v[208:209], off
	v_add_co_u32_e64 v208, s[42:43], s67, v208
	s_nop 1
	v_addc_co_u32_e64 v209, s[42:43], 0, v209, s[42:43]
	ds_read_b128 v[40:43], v174 offset:96
	s_waitcnt vmcnt(7) lgkmcnt(0)
	v_pk_fma_f32 v[148:149], v[182:183], v[40:41], v[116:117] op_sel:[0, 1, 0]
	ds_read_b128 v[114:117], v174 offset:112
	v_pk_fma_f32 v[138:139], v[180:181], v[40:41], v[128:129] op_sel_hi:[1, 0, 1]
	v_pk_fma_f32 v[146:147], v[182:183], v[40:41], v[118:119] op_sel_hi:[1, 0, 1]
	v_pk_fma_f32 v[140:141], v[180:181], v[40:41], v[130:131] op_sel:[0, 1, 0]
	v_mov_b32_e32 v40, v43
	v_pk_fma_f32 v[144:145], v[180:181], v[40:41], v[124:125] op_sel_hi:[1, 0, 1]
	v_pk_fma_f32 v[152:153], v[182:183], v[40:41], v[126:127] op_sel_hi:[1, 0, 1]
	s_waitcnt lgkmcnt(0)
	v_pk_fma_f32 v[40:41], v[182:183], v[114:115], v[96:97] op_sel_hi:[1, 0, 1]
	v_pk_fma_f32 v[134:135], v[182:183], v[116:117], v[94:95] op_sel_hi:[1, 0, 1]
	ds_read_b128 v[94:97], v174 offset:128
	v_mov_b32_e32 v76, v117
	v_pk_fma_f32 v[126:127], v[180:181], v[76:77], v[106:107] op_sel_hi:[1, 0, 1]
	v_pk_fma_f32 v[124:125], v[180:181], v[116:117], v[102:103] op_sel_hi:[1, 0, 1]
	v_pk_fma_f32 v[142:143], v[180:181], v[42:43], v[120:121] op_sel_hi:[1, 0, 1]
	s_waitcnt lgkmcnt(0)
	v_pk_fma_f32 v[128:129], v[182:183], v[96:97], v[72:73] op_sel_hi:[1, 0, 1]
	v_mov_b32_e32 v72, v97
	v_pk_fma_f32 v[106:107], v[182:183], v[94:95], v[74:75] op_sel_hi:[1, 0, 1]
	v_pk_fma_f32 v[118:119], v[180:181], v[72:73], v[82:83] op_sel_hi:[1, 0, 1]
	v_pk_fma_f32 v[132:133], v[182:183], v[72:73], v[84:85] op_sel_hi:[1, 0, 1]
	ds_read_b128 v[72:75], v174 offset:144
	v_pk_fma_f32 v[116:117], v[180:181], v[96:97], v[80:81] op_sel_hi:[1, 0, 1]
	v_pk_fma_f32 v[150:151], v[182:183], v[42:43], v[122:123] op_sel_hi:[1, 0, 1]
	v_pk_fma_f32 v[42:43], v[180:181], v[114:115], v[110:111] op_sel_hi:[1, 0, 1]
	v_pk_fma_f32 v[136:137], v[182:183], v[76:77], v[108:109] op_sel_hi:[1, 0, 1]
	s_waitcnt lgkmcnt(0)
	v_pk_fma_f32 v[96:97], v[180:181], v[74:75], v[64:65] op_sel_hi:[1, 0, 1]
	v_pk_fma_f32 v[64:65], v[182:183], v[74:75], v[66:67] op_sel_hi:[1, 0, 1]
	v_mov_b32_e32 v66, v75
	v_pk_fma_f32 v[108:109], v[180:181], v[66:67], v[56:57] op_sel_hi:[1, 0, 1]
	v_pk_fma_f32 v[110:111], v[182:183], v[66:67], v[58:59] op_sel_hi:[1, 0, 1]
	ds_read_b128 v[56:59], v174 offset:160
	v_pk_fma_f32 v[130:131], v[182:183], v[114:115], v[100:101] op_sel:[0, 1, 0]
	v_pk_fma_f32 v[122:123], v[180:181], v[114:115], v[112:113] op_sel:[0, 1, 0]
	v_pk_fma_f32 v[112:113], v[180:181], v[94:95], v[90:91] op_sel_hi:[1, 0, 1]
	v_pk_fma_f32 v[114:115], v[180:181], v[94:95], v[88:89] op_sel:[0, 1, 0]
	s_waitcnt lgkmcnt(0)
; #define LAS __attribute__((address_space(3)))
; __device__ __forceinline__ void gemv24_item(const float* W, int N, int j0, LAS float* sc, LAS float* red, float (&res)[6], const int tid) {
;     ...
;     const float* w = W + (size_t)(ks * 64) * N + j0 + cg * 4;
; #pragma unroll 8
;     for (int kk = 0; kk < 64; ++kk) {
;         const f32x4 wv = *(const f32x4*)(w + (size_t)kk * N);
;         const LAS f32x4* s4 = (const LAS f32x4*)(sc + (ks * 64 + kk) * 24);
; #pragma unroll
;         for (int b4 = 0; b4 < 6; ++b4) { const f32x4 s = s4[b4]; acc[4 * b4] += wv * s[0]; acc[4 * b4 + 1] += wv * s[1]; acc[4 * b4 + 2] += wv * s[2]; acc[4 * b4 + 3] += wv * s[3]; }
;     }
	v_pk_fma_f32 v[82:83], v[180:181], v[58:59], v[44:45] op_sel_hi:[1, 0, 1]
	v_mov_b32_e32 v44, v59
	v_pk_fma_f32 v[86:87], v[180:181], v[44:45], v[36:37] op_sel_hi:[1, 0, 1]
	v_pk_fma_f32 v[84:85], v[182:183], v[44:45], v[38:39] op_sel_hi:[1, 0, 1]
	ds_read_b128 v[36:39], v174 offset:176
	v_pk_fma_f32 v[74:75], v[180:181], v[56:57], v[52:53] op_sel_hi:[1, 0, 1]
	v_pk_fma_f32 v[76:77], v[182:183], v[56:57], v[50:51] op_sel:[0, 1, 0]
	ds_read_b128 v[50:53], v174 offset:208
	v_pk_fma_f32 v[120:121], v[182:183], v[94:95], v[78:79] op_sel:[0, 1, 0]
	s_waitcnt lgkmcnt(1)
	v_pk_fma_f32 v[100:101], v[180:181], v[38:39], v[28:29] op_sel_hi:[1, 0, 1]
	v_mov_b32_e32 v28, v39
	v_pk_fma_f32 v[68:69], v[180:181], v[72:73], v[68:69] op_sel_hi:[1, 0, 1]
	v_pk_fma_f32 v[70:71], v[180:181], v[72:73], v[70:71] op_sel:[0, 1, 0]
	v_pk_fma_f32 v[78:79], v[180:181], v[56:57], v[48:49] op_sel:[0, 1, 0]
	v_pk_fma_f32 v[90:91], v[180:181], v[36:37], v[98:99] op_sel_hi:[1, 0, 1]
	v_pk_fma_f32 v[94:95], v[180:181], v[36:37], v[32:33] op_sel:[0, 1, 0]
	v_pk_fma_f32 v[104:105], v[180:181], v[28:29], v[24:25] op_sel_hi:[1, 0, 1]
	v_add_co_u32_e64 v0, s[42:43], s8, v22
	v_pk_fma_f32 v[60:61], v[182:183], v[72:73], v[60:61] op_sel_hi:[1, 0, 1]
	s_nop 0
	v_addc_co_u32_e64 v1, s[42:43], 0, v23, s[42:43]
	v_pk_fma_f32 v[62:63], v[182:183], v[72:73], v[62:63] op_sel:[0, 1, 0]
	v_pk_fma_f32 v[72:73], v[182:183], v[56:57], v[54:55] op_sel_hi:[1, 0, 1]
	v_pk_fma_f32 v[80:81], v[182:183], v[58:59], v[46:47] op_sel_hi:[1, 0, 1]
	v_pk_fma_f32 v[88:89], v[182:183], v[36:37], v[92:93] op_sel_hi:[1, 0, 1]
	v_pk_fma_f32 v[92:93], v[182:183], v[36:37], v[34:35] op_sel:[0, 1, 0]
	v_pk_fma_f32 v[98:99], v[182:183], v[38:39], v[30:31] op_sel_hi:[1, 0, 1]
	v_pk_fma_f32 v[102:103], v[182:183], v[28:29], v[26:27] op_sel_hi:[1, 0, 1]
	global_load_dwordx4 v[180:183], v[208:209], off
	v_add_co_u32_e64 v208, s[42:43], s67, v208
	s_nop 1
	v_addc_co_u32_e64 v209, s[42:43], 0, v209, s[42:43]
	ds_read_b128 v[34:37], v174 offset:192
	ds_read_b128 v[56:59], v174 offset:224
	s_waitcnt lgkmcnt(2)
	v_mov_b32_e32 v54, v53
	s_waitcnt lgkmcnt(1)
	v_mov_b32_e32 v38, v37
	s_waitcnt vmcnt(7)
	v_pk_fma_f32 v[40:41], v[186:187], v[50:51], v[40:41] op_sel_hi:[1, 0, 1]
	v_pk_fma_f32 v[42:43], v[184:185], v[50:51], v[42:43] op_sel_hi:[1, 0, 1]
	v_pk_fma_f32 v[44:45], v[186:187], v[50:51], v[130:131] op_sel:[0, 1, 0]
	v_pk_fma_f32 v[46:47], v[184:185], v[50:51], v[122:123] op_sel:[0, 1, 0]
	v_pk_fma_f32 v[48:49], v[186:187], v[52:53], v[134:135] op_sel_hi:[1, 0, 1]
	v_pk_fma_f32 v[50:51], v[184:185], v[52:53], v[124:125] op_sel_hi:[1, 0, 1]
	v_pk_fma_f32 v[52:53], v[186:187], v[54:55], v[136:137] op_sel_hi:[1, 0, 1]
	v_pk_fma_f32 v[54:55], v[184:185], v[54:55], v[126:127] op_sel_hi:[1, 0, 1]
	s_waitcnt lgkmcnt(0)
	v_pk_fma_f32 v[122:123], v[184:185], v[56:57], v[112:113] op_sel_hi:[1, 0, 1]
	v_pk_fma_f32 v[126:127], v[184:185], v[56:57], v[114:115] op_sel:[0, 1, 0]
	ds_read_b128 v[112:115], v174 offset:240
	v_pk_fma_f32 v[106:107], v[186:187], v[56:57], v[106:107] op_sel_hi:[1, 0, 1]
	v_pk_fma_f32 v[124:125], v[186:187], v[56:57], v[120:121] op_sel:[0, 1, 0]
	v_mov_b32_e32 v56, v59
	v_pk_fma_f32 v[130:131], v[184:185], v[58:59], v[116:117] op_sel_hi:[1, 0, 1]
	v_pk_fma_f32 v[132:133], v[186:187], v[56:57], v[132:133] op_sel_hi:[1, 0, 1]
	v_pk_fma_f32 v[134:135], v[184:185], v[56:57], v[118:119] op_sel_hi:[1, 0, 1]
	ds_read_b128 v[116:119], v174 offset:288
	s_waitcnt lgkmcnt(1)
	v_pk_fma_f32 v[56:57], v[186:187], v[112:113], v[60:61] op_sel_hi:[1, 0, 1]
	v_pk_fma_f32 v[60:61], v[186:187], v[112:113], v[62:63] op_sel:[0, 1, 0]
	v_pk_fma_f32 v[62:63], v[184:185], v[112:113], v[70:71] op_sel:[0, 1, 0]
	v_mov_b32_e32 v70, v115
	v_pk_fma_f32 v[128:129], v[186:187], v[58:59], v[128:129] op_sel_hi:[1, 0, 1]
	v_pk_fma_f32 v[58:59], v[184:185], v[112:113], v[68:69] op_sel_hi:[1, 0, 1]
	v_pk_fma_f32 v[68:69], v[186:187], v[70:71], v[110:111] op_sel_hi:[1, 0, 1]
	v_pk_fma_f32 v[70:71], v[184:185], v[70:71], v[108:109] op_sel_hi:[1, 0, 1]
	ds_read_b128 v[108:111], v174 offset:256
	v_pk_fma_f32 v[66:67], v[184:185], v[114:115], v[96:97] op_sel_hi:[1, 0, 1]
	v_pk_fma_f32 v[24:25], v[186:187], v[34:35], v[146:147] op_sel_hi:[1, 0, 1]
	v_pk_fma_f32 v[26:27], v[184:185], v[34:35], v[138:139] op_sel_hi:[1, 0, 1]
	v_pk_fma_f32 v[28:29], v[186:187], v[34:35], v[148:149] op_sel:[0, 1, 0]
	s_waitcnt lgkmcnt(0)
	v_pk_fma_f32 v[72:73], v[186:187], v[108:109], v[72:73] op_sel_hi:[1, 0, 1]
	v_pk_fma_f32 v[74:75], v[184:185], v[108:109], v[74:75] op_sel_hi:[1, 0, 1]
	v_pk_fma_f32 v[76:77], v[186:187], v[108:109], v[76:77] op_sel:[0, 1, 0]
	v_pk_fma_f32 v[78:79], v[184:185], v[108:109], v[78:79] op_sel:[0, 1, 0]
	v_pk_fma_f32 v[80:81], v[186:187], v[110:111], v[80:81] op_sel_hi:[1, 0, 1]
	v_pk_fma_f32 v[82:83], v[184:185], v[110:111], v[82:83] op_sel_hi:[1, 0, 1]
	v_mov_b32_e32 v96, v111
	ds_read_b128 v[108:111], v174 offset:272
	v_pk_fma_f32 v[84:85], v[186:187], v[96:97], v[84:85] op_sel_hi:[1, 0, 1]
	v_pk_fma_f32 v[86:87], v[184:185], v[96:97], v[86:87] op_sel_hi:[1, 0, 1]
	v_pk_fma_f32 v[30:31], v[184:185], v[34:35], v[140:141] op_sel:[0, 1, 0]
	v_pk_fma_f32 v[32:33], v[186:187], v[36:37], v[150:151] op_sel_hi:[1, 0, 1]
	s_waitcnt lgkmcnt(0)
; #define LAS __attribute__((address_space(3)))
; __device__ __forceinline__ void gemv24_item(const float* W, int N, int j0, LAS float* sc, LAS float* red, float (&res)[6], const int tid) {
;     ...
;     const float* w = W + (size_t)(ks * 64) * N + j0 + cg * 4;
; #pragma unroll 8
;     for (int kk = 0; kk < 64; ++kk) {
;         const f32x4 wv = *(const f32x4*)(w + (size_t)kk * N);
;         const LAS f32x4* s4 = (const LAS f32x4*)(sc + (ks * 64 + kk) * 24);
; #pragma unroll
;         for (int b4 = 0; b4 < 6; ++b4) { const f32x4 s = s4[b4]; acc[4 * b4] += wv * s[0]; acc[4 * b4 + 1] += wv * s[1]; acc[4 * b4 + 2] += wv * s[2]; acc[4 * b4 + 3] += wv * s[3]; }
;     }
	v_pk_fma_f32 v[96:97], v[184:185], v[108:109], v[94:95] op_sel:[0, 1, 0]
	v_mov_b32_e32 v94, v111
	v_pk_fma_f32 v[34:35], v[184:185], v[36:37], v[142:143] op_sel_hi:[1, 0, 1]
	v_pk_fma_f32 v[36:37], v[186:187], v[38:39], v[152:153] op_sel_hi:[1, 0, 1]
	v_pk_fma_f32 v[38:39], v[184:185], v[38:39], v[144:145] op_sel_hi:[1, 0, 1]
	v_pk_fma_f32 v[90:91], v[184:185], v[108:109], v[90:91] op_sel_hi:[1, 0, 1]
	v_pk_fma_f32 v[100:101], v[184:185], v[110:111], v[100:101] op_sel_hi:[1, 0, 1]
	v_pk_fma_f32 v[104:105], v[184:185], v[94:95], v[104:105] op_sel_hi:[1, 0, 1]
	v_add_co_u32_e64 v0, s[42:43], s3, v22
	v_pk_fma_f32 v[64:65], v[186:187], v[114:115], v[64:65] op_sel_hi:[1, 0, 1]
	s_nop 0
	v_addc_co_u32_e64 v1, s[42:43], 0, v23, s[42:43]
	v_pk_fma_f32 v[88:89], v[186:187], v[108:109], v[88:89] op_sel_hi:[1, 0, 1]
	v_pk_fma_f32 v[92:93], v[186:187], v[108:109], v[92:93] op_sel:[0, 1, 0]
	v_pk_fma_f32 v[98:99], v[186:187], v[110:111], v[98:99] op_sel_hi:[1, 0, 1]
	v_pk_fma_f32 v[102:103], v[186:187], v[94:95], v[102:103] op_sel_hi:[1, 0, 1]
	global_load_dwordx4 v[184:187], v[208:209], off
	v_add_co_u32_e64 v208, s[42:43], s67, v208
	s_nop 1
	v_addc_co_u32_e64 v209, s[42:43], 0, v209, s[42:43]
	s_waitcnt vmcnt(7)
	v_pk_fma_f32 v[94:95], v[190:191], v[116:117], v[24:25] op_sel_hi:[1, 0, 1]
	v_mov_b32_e32 v24, v119
	v_pk_fma_f32 v[108:109], v[188:189], v[116:117], v[26:27] op_sel_hi:[1, 0, 1]
	v_pk_fma_f32 v[110:111], v[190:191], v[116:117], v[28:29] op_sel:[0, 1, 0]
	v_pk_fma_f32 v[112:113], v[188:189], v[116:117], v[30:31] op_sel:[0, 1, 0]
	v_pk_fma_f32 v[114:115], v[190:191], v[118:119], v[32:33] op_sel_hi:[1, 0, 1]
	v_pk_fma_f32 v[116:117], v[188:189], v[118:119], v[34:35] op_sel_hi:[1, 0, 1]
	v_pk_fma_f32 v[118:119], v[190:191], v[24:25], v[36:37] op_sel_hi:[1, 0, 1]
	v_pk_fma_f32 v[120:121], v[188:189], v[24:25], v[38:39] op_sel_hi:[1, 0, 1]
	ds_read_b128 v[24:27], v174 offset:304
	ds_read_b128 v[34:37], v174 offset:320
	s_waitcnt lgkmcnt(1)
	v_pk_fma_f32 v[40:41], v[190:191], v[24:25], v[40:41] op_sel_hi:[1, 0, 1]
	v_pk_fma_f32 v[42:43], v[188:189], v[24:25], v[42:43] op_sel_hi:[1, 0, 1]
	v_pk_fma_f32 v[44:45], v[190:191], v[24:25], v[44:45] op_sel:[0, 1, 0]
	v_pk_fma_f32 v[46:47], v[188:189], v[24:25], v[46:47] op_sel:[0, 1, 0]
	v_pk_fma_f32 v[48:49], v[190:191], v[26:27], v[48:49] op_sel_hi:[1, 0, 1]
	v_pk_fma_f32 v[50:51], v[188:189], v[26:27], v[50:51] op_sel_hi:[1, 0, 1]
	v_mov_b32_e32 v24, v27
	s_waitcnt lgkmcnt(0)
	v_pk_fma_f32 v[26:27], v[188:189], v[34:35], v[122:123] op_sel_hi:[1, 0, 1]
	v_pk_fma_f32 v[28:29], v[190:191], v[34:35], v[124:125] op_sel:[0, 1, 0]
	ds_read_b128 v[122:125], v174 offset:336
	v_pk_fma_f32 v[52:53], v[190:191], v[24:25], v[52:53] op_sel_hi:[1, 0, 1]
	v_pk_fma_f32 v[54:55], v[188:189], v[24:25], v[54:55] op_sel_hi:[1, 0, 1]
	v_pk_fma_f32 v[24:25], v[190:191], v[34:35], v[106:107] op_sel_hi:[1, 0, 1]
	v_mov_b32_e32 v38, v37
	s_waitcnt lgkmcnt(0)
	v_pk_fma_f32 v[56:57], v[190:191], v[122:123], v[56:57] op_sel_hi:[1, 0, 1]
	v_pk_fma_f32 v[58:59], v[188:189], v[122:123], v[58:59] op_sel_hi:[1, 0, 1]
	v_pk_fma_f32 v[60:61], v[190:191], v[122:123], v[60:61] op_sel:[0, 1, 0]
	v_pk_fma_f32 v[62:63], v[188:189], v[122:123], v[62:63] op_sel:[0, 1, 0]
	v_pk_fma_f32 v[64:65], v[190:191], v[124:125], v[64:65] op_sel_hi:[1, 0, 1]
	v_pk_fma_f32 v[66:67], v[188:189], v[124:125], v[66:67] op_sel_hi:[1, 0, 1]
	v_mov_b32_e32 v106, v125
	ds_read_b128 v[122:125], v174 offset:352
	v_pk_fma_f32 v[68:69], v[190:191], v[106:107], v[68:69] op_sel_hi:[1, 0, 1]
	v_pk_fma_f32 v[70:71], v[188:189], v[106:107], v[70:71] op_sel_hi:[1, 0, 1]
	v_pk_fma_f32 v[30:31], v[188:189], v[34:35], v[126:127] op_sel:[0, 1, 0]
	v_pk_fma_f32 v[32:33], v[190:191], v[36:37], v[128:129] op_sel_hi:[1, 0, 1]
	s_waitcnt lgkmcnt(0)
	v_pk_fma_f32 v[72:73], v[190:191], v[122:123], v[72:73] op_sel_hi:[1, 0, 1]
	v_pk_fma_f32 v[74:75], v[188:189], v[122:123], v[74:75] op_sel_hi:[1, 0, 1]
	v_pk_fma_f32 v[76:77], v[190:191], v[122:123], v[76:77] op_sel:[0, 1, 0]
	v_pk_fma_f32 v[78:79], v[188:189], v[122:123], v[78:79] op_sel:[0, 1, 0]
	v_pk_fma_f32 v[80:81], v[190:191], v[124:125], v[80:81] op_sel_hi:[1, 0, 1]
	v_pk_fma_f32 v[82:83], v[188:189], v[124:125], v[82:83] op_sel_hi:[1, 0, 1]
	v_mov_b32_e32 v106, v125
	ds_read_b128 v[122:125], v174 offset:368
	v_pk_fma_f32 v[84:85], v[190:191], v[106:107], v[84:85] op_sel_hi:[1, 0, 1]
	v_pk_fma_f32 v[86:87], v[188:189], v[106:107], v[86:87] op_sel_hi:[1, 0, 1]
	v_pk_fma_f32 v[34:35], v[188:189], v[36:37], v[130:131] op_sel_hi:[1, 0, 1]
	v_pk_fma_f32 v[36:37], v[190:191], v[38:39], v[132:133] op_sel_hi:[1, 0, 1]
	s_waitcnt lgkmcnt(0)
	v_mov_b32_e32 v106, v125
	v_pk_fma_f32 v[38:39], v[188:189], v[38:39], v[134:135] op_sel_hi:[1, 0, 1]
	v_pk_fma_f32 v[90:91], v[188:189], v[122:123], v[90:91] op_sel_hi:[1, 0, 1]
	v_pk_fma_f32 v[96:97], v[188:189], v[122:123], v[96:97] op_sel:[0, 1, 0]
	v_pk_fma_f32 v[100:101], v[188:189], v[124:125], v[100:101] op_sel_hi:[1, 0, 1]
	v_pk_fma_f32 v[104:105], v[188:189], v[106:107], v[104:105] op_sel_hi:[1, 0, 1]
	v_add_co_u32_e64 v0, s[42:43], s0, v22
	v_pk_fma_f32 v[88:89], v[190:191], v[122:123], v[88:89] op_sel_hi:[1, 0, 1]
	s_nop 0
	v_addc_co_u32_e64 v1, s[42:43], 0, v23, s[42:43]
	v_pk_fma_f32 v[92:93], v[190:191], v[122:123], v[92:93] op_sel:[0, 1, 0]
	v_pk_fma_f32 v[98:99], v[190:191], v[124:125], v[98:99] op_sel_hi:[1, 0, 1]
	v_pk_fma_f32 v[102:103], v[190:191], v[106:107], v[102:103] op_sel_hi:[1, 0, 1]
	global_load_dwordx4 v[188:191], v[208:209], off
	v_add_co_u32_e64 v208, s[42:43], s67, v208
	s_nop 1
	v_addc_co_u32_e64 v209, s[42:43], 0, v209, s[42:43]
	ds_read_b128 v[122:125], v174 offset:384
	s_mov_b32 s0, 0x2d000
	s_waitcnt vmcnt(7) lgkmcnt(0)
; #define LAS __attribute__((address_space(3)))
; __device__ __forceinline__ void gemv24_item(const float* W, int N, int j0, LAS float* sc, LAS float* red, float (&res)[6], const int tid) {
;     ...
;     const float* w = W + (size_t)(ks * 64) * N + j0 + cg * 4;
; #pragma unroll 8
;     for (int kk = 0; kk < 64; ++kk) {
;         const f32x4 wv = *(const f32x4*)(w + (size_t)kk * N);
;         const LAS f32x4* s4 = (const LAS f32x4*)(sc + (ks * 64 + kk) * 24);
; #pragma unroll
;         for (int b4 = 0; b4 < 6; ++b4) { const f32x4 s = s4[b4]; acc[4 * b4] += wv * s[0]; acc[4 * b4 + 1] += wv * s[1]; acc[4 * b4 + 2] += wv * s[2]; acc[4 * b4 + 3] += wv * s[3]; }
;     }
	v_pk_fma_f32 v[106:107], v[194:195], v[122:123], v[94:95] op_sel_hi:[1, 0, 1]
	v_mov_b32_e32 v94, v125
	v_pk_fma_f32 v[108:109], v[192:193], v[122:123], v[108:109] op_sel_hi:[1, 0, 1]
	v_pk_fma_f32 v[110:111], v[194:195], v[122:123], v[110:111] op_sel:[0, 1, 0]
	v_pk_fma_f32 v[112:113], v[192:193], v[122:123], v[112:113] op_sel:[0, 1, 0]
	v_pk_fma_f32 v[128:129], v[192:193], v[94:95], v[120:121] op_sel_hi:[1, 0, 1]
	ds_read_b128 v[120:123], v174 offset:400
	v_pk_fma_f32 v[118:119], v[194:195], v[94:95], v[118:119] op_sel_hi:[1, 0, 1]
	v_pk_fma_f32 v[116:117], v[192:193], v[124:125], v[116:117] op_sel_hi:[1, 0, 1]
	v_pk_fma_f32 v[114:115], v[194:195], v[124:125], v[114:115] op_sel_hi:[1, 0, 1]
	s_waitcnt lgkmcnt(0)
	v_pk_fma_f32 v[144:145], v[194:195], v[120:121], v[40:41] op_sel_hi:[1, 0, 1]
	v_mov_b32_e32 v40, v123
	v_pk_fma_f32 v[146:147], v[192:193], v[120:121], v[42:43] op_sel_hi:[1, 0, 1]
	v_pk_fma_f32 v[44:45], v[194:195], v[120:121], v[44:45] op_sel:[0, 1, 0]
	v_pk_fma_f32 v[46:47], v[192:193], v[120:121], v[46:47] op_sel:[0, 1, 0]
	v_pk_fma_f32 v[48:49], v[194:195], v[122:123], v[48:49] op_sel_hi:[1, 0, 1]
	v_pk_fma_f32 v[50:51], v[192:193], v[122:123], v[50:51] op_sel_hi:[1, 0, 1]
	v_pk_fma_f32 v[52:53], v[194:195], v[40:41], v[52:53] op_sel_hi:[1, 0, 1]
	v_pk_fma_f32 v[54:55], v[192:193], v[40:41], v[54:55] op_sel_hi:[1, 0, 1]
	ds_read_b128 v[40:43], v174 offset:416
	ds_read_b128 v[120:123], v174 offset:432
	s_waitcnt lgkmcnt(1)
	v_pk_fma_f32 v[148:149], v[194:195], v[40:41], v[24:25] op_sel_hi:[1, 0, 1]
	v_pk_fma_f32 v[150:151], v[192:193], v[40:41], v[26:27] op_sel_hi:[1, 0, 1]
	v_mov_b32_e32 v24, v43
	s_waitcnt lgkmcnt(0)
	v_pk_fma_f32 v[26:27], v[192:193], v[120:121], v[58:59] op_sel_hi:[1, 0, 1]
	v_mov_b32_e32 v58, v123
	v_pk_fma_f32 v[152:153], v[194:195], v[40:41], v[28:29] op_sel:[0, 1, 0]
	v_pk_fma_f32 v[36:37], v[194:195], v[24:25], v[36:37] op_sel_hi:[1, 0, 1]
	v_pk_fma_f32 v[38:39], v[192:193], v[24:25], v[38:39] op_sel_hi:[1, 0, 1]
	v_pk_fma_f32 v[24:25], v[194:195], v[120:121], v[56:57] op_sel_hi:[1, 0, 1]
	v_pk_fma_f32 v[28:29], v[194:195], v[120:121], v[60:61] op_sel:[0, 1, 0]
	v_pk_fma_f32 v[56:57], v[194:195], v[58:59], v[68:69] op_sel_hi:[1, 0, 1]
	v_pk_fma_f32 v[130:131], v[192:193], v[58:59], v[70:71] op_sel_hi:[1, 0, 1]
	ds_read_b128 v[58:61], v174 offset:448
	v_pk_fma_f32 v[154:155], v[192:193], v[40:41], v[30:31] op_sel:[0, 1, 0]
	v_pk_fma_f32 v[32:33], v[194:195], v[42:43], v[32:33] op_sel_hi:[1, 0, 1]
	v_pk_fma_f32 v[34:35], v[192:193], v[42:43], v[34:35] op_sel_hi:[1, 0, 1]
	v_pk_fma_f32 v[40:41], v[194:195], v[122:123], v[64:65] op_sel_hi:[1, 0, 1]
	v_pk_fma_f32 v[42:43], v[192:193], v[122:123], v[66:67] op_sel_hi:[1, 0, 1]
	ds_read_b128 v[64:67], v174 offset:496
	s_waitcnt lgkmcnt(1)
	v_pk_fma_f32 v[72:73], v[194:195], v[58:59], v[72:73] op_sel_hi:[1, 0, 1]
	v_pk_fma_f32 v[74:75], v[192:193], v[58:59], v[74:75] op_sel_hi:[1, 0, 1]
	v_pk_fma_f32 v[132:133], v[194:195], v[58:59], v[76:77] op_sel:[0, 1, 0]
	v_pk_fma_f32 v[134:135], v[192:193], v[58:59], v[78:79] op_sel:[0, 1, 0]
	v_mov_b32_e32 v58, v61
	v_pk_fma_f32 v[136:137], v[194:195], v[60:61], v[80:81] op_sel_hi:[1, 0, 1]
	v_pk_fma_f32 v[138:139], v[192:193], v[60:61], v[82:83] op_sel_hi:[1, 0, 1]
	v_pk_fma_f32 v[140:141], v[194:195], v[58:59], v[84:85] op_sel_hi:[1, 0, 1]
	v_pk_fma_f32 v[142:143], v[192:193], v[58:59], v[86:87] op_sel_hi:[1, 0, 1]
	ds_read_b128 v[58:61], v174 offset:464
	v_pk_fma_f32 v[30:31], v[192:193], v[120:121], v[62:63] op_sel:[0, 1, 0]
	s_waitcnt lgkmcnt(0)
	v_pk_fma_f32 v[80:81], v[194:195], v[58:59], v[88:89] op_sel_hi:[1, 0, 1]
	v_pk_fma_f32 v[84:85], v[192:193], v[58:59], v[90:91] op_sel_hi:[1, 0, 1]
	v_pk_fma_f32 v[94:95], v[194:195], v[58:59], v[92:93] op_sel:[0, 1, 0]
	v_pk_fma_f32 v[96:97], v[192:193], v[58:59], v[96:97] op_sel:[0, 1, 0]
	v_mov_b32_e32 v58, v61
	v_pk_fma_f32 v[122:123], v[192:193], v[60:61], v[100:101] op_sel_hi:[1, 0, 1]
	v_pk_fma_f32 v[126:127], v[192:193], v[58:59], v[104:105] op_sel_hi:[1, 0, 1]
	v_add_co_u32_e64 v0, s[42:43], s0, v22
	v_pk_fma_f32 v[120:121], v[194:195], v[60:61], v[98:99] op_sel_hi:[1, 0, 1]
	s_nop 0
	v_addc_co_u32_e64 v1, s[42:43], 0, v23, s[42:43]
	v_pk_fma_f32 v[124:125], v[194:195], v[58:59], v[102:103] op_sel_hi:[1, 0, 1]
	global_load_dwordx4 v[192:195], v[208:209], off
	v_add_co_u32_e64 v208, s[42:43], s67, v208
	s_nop 1
	v_addc_co_u32_e64 v209, s[42:43], 0, v209, s[42:43]
	ds_read_b128 v[58:61], v174 offset:480
	s_mov_b32 s0, 0x36000
	s_waitcnt vmcnt(7)
	v_pk_fma_f32 v[62:63], v[198:199], v[64:65], v[44:45] op_sel:[0, 1, 0]
	v_mov_b32_e32 v44, v67
	v_pk_fma_f32 v[92:93], v[196:197], v[66:67], v[50:51] op_sel_hi:[1, 0, 1]
	v_pk_fma_f32 v[98:99], v[198:199], v[44:45], v[52:53] op_sel_hi:[1, 0, 1]
	ds_read_b128 v[50:53], v174 offset:512
	s_waitcnt lgkmcnt(1)
	v_pk_fma_f32 v[82:83], v[196:197], v[58:59], v[108:109] op_sel_hi:[1, 0, 1]
	v_pk_fma_f32 v[86:87], v[198:199], v[58:59], v[110:111] op_sel:[0, 1, 0]
	ds_read_b128 v[108:111], v174 offset:528
	v_pk_fma_f32 v[90:91], v[198:199], v[66:67], v[48:49] op_sel_hi:[1, 0, 1]
	s_waitcnt lgkmcnt(1)
	v_pk_fma_f32 v[66:67], v[198:199], v[52:53], v[32:33] op_sel_hi:[1, 0, 1]
	v_mov_b32_e32 v32, v53
	v_pk_fma_f32 v[78:79], v[198:199], v[58:59], v[106:107] op_sel_hi:[1, 0, 1]
	v_pk_fma_f32 v[88:89], v[196:197], v[58:59], v[112:113] op_sel:[0, 1, 0]
	v_pk_fma_f32 v[100:101], v[198:199], v[60:61], v[114:115] op_sel_hi:[1, 0, 1]
	v_pk_fma_f32 v[102:103], v[196:197], v[60:61], v[116:117] op_sel_hi:[1, 0, 1]
	v_mov_b32_e32 v58, v61
	v_pk_fma_f32 v[70:71], v[198:199], v[32:33], v[36:37] op_sel_hi:[1, 0, 1]
	v_pk_fma_f32 v[76:77], v[196:197], v[32:33], v[38:39] op_sel_hi:[1, 0, 1]
	ds_read_b128 v[114:117], v174 offset:544
	s_waitcnt lgkmcnt(1)
; #define LAS __attribute__((address_space(3)))
; __device__ __forceinline__ void gemv24_item(const float* W, int N, int j0, LAS float* sc, LAS float* red, float (&res)[6], const int tid) {
;     ...
;     const float* w = W + (size_t)(ks * 64) * N + j0 + cg * 4;
; #pragma unroll 8
;     for (int kk = 0; kk < 64; ++kk) {
;         const f32x4 wv = *(const f32x4*)(w + (size_t)kk * N);
;         const LAS f32x4* s4 = (const LAS f32x4*)(sc + (ks * 64 + kk) * 24);
; #pragma unroll
;         for (int b4 = 0; b4 < 6; ++b4) { const f32x4 s = s4[b4]; acc[4 * b4] += wv * s[0]; acc[4 * b4 + 1] += wv * s[1]; acc[4 * b4 + 2] += wv * s[2]; acc[4 * b4 + 3] += wv * s[3]; }
;     }
	v_pk_fma_f32 v[32:33], v[198:199], v[108:109], v[24:25] op_sel_hi:[1, 0, 1]
	v_mov_b32_e32 v24, v111
	v_pk_fma_f32 v[112:113], v[196:197], v[58:59], v[128:129] op_sel_hi:[1, 0, 1]
	v_pk_fma_f32 v[68:69], v[196:197], v[52:53], v[34:35] op_sel_hi:[1, 0, 1]
	v_pk_fma_f32 v[34:35], v[196:197], v[108:109], v[26:27] op_sel_hi:[1, 0, 1]
	v_pk_fma_f32 v[36:37], v[198:199], v[108:109], v[28:29] op_sel:[0, 1, 0]
	v_pk_fma_f32 v[38:39], v[196:197], v[108:109], v[30:31] op_sel:[0, 1, 0]
	v_pk_fma_f32 v[108:109], v[196:197], v[24:25], v[130:131] op_sel_hi:[1, 0, 1]
	ds_read_b128 v[128:131], v174 offset:560
	v_pk_fma_f32 v[104:105], v[196:197], v[44:45], v[54:55] op_sel_hi:[1, 0, 1]
	v_pk_fma_f32 v[52:53], v[198:199], v[110:111], v[40:41] op_sel_hi:[1, 0, 1]
	v_pk_fma_f32 v[54:55], v[196:197], v[110:111], v[42:43] op_sel_hi:[1, 0, 1]
	s_waitcnt lgkmcnt(1)
	v_pk_fma_f32 v[26:27], v[196:197], v[114:115], v[74:75] op_sel_hi:[1, 0, 1]
	v_pk_fma_f32 v[30:31], v[196:197], v[114:115], v[134:135] op_sel:[0, 1, 0]
	v_pk_fma_f32 v[40:41], v[198:199], v[116:117], v[136:137] op_sel_hi:[1, 0, 1]
	v_mov_b32_e32 v74, v117
	ds_read_b128 v[134:137], v174 offset:704
	s_waitcnt lgkmcnt(1)
	v_pk_fma_f32 v[110:111], v[198:199], v[128:129], v[80:81] op_sel_hi:[1, 0, 1]
	v_mov_b32_e32 v80, v131
	v_pk_fma_f32 v[106:107], v[198:199], v[58:59], v[118:119] op_sel_hi:[1, 0, 1]
	v_pk_fma_f32 v[58:59], v[198:199], v[64:65], v[144:145] op_sel_hi:[1, 0, 1]
	v_pk_fma_f32 v[60:61], v[196:197], v[64:65], v[146:147] op_sel_hi:[1, 0, 1]
	v_pk_fma_f32 v[64:65], v[196:197], v[64:65], v[46:47] op_sel:[0, 1, 0]
	v_pk_fma_f32 v[44:45], v[198:199], v[50:51], v[148:149] op_sel_hi:[1, 0, 1]
	v_pk_fma_f32 v[46:47], v[196:197], v[50:51], v[150:151] op_sel_hi:[1, 0, 1]
	v_pk_fma_f32 v[48:49], v[198:199], v[50:51], v[152:153] op_sel:[0, 1, 0]
	v_pk_fma_f32 v[50:51], v[196:197], v[50:51], v[154:155] op_sel:[0, 1, 0]
	v_pk_fma_f32 v[56:57], v[198:199], v[24:25], v[56:57] op_sel_hi:[1, 0, 1]
	v_pk_fma_f32 v[24:25], v[198:199], v[114:115], v[72:73] op_sel_hi:[1, 0, 1]
	v_pk_fma_f32 v[28:29], v[198:199], v[114:115], v[132:133] op_sel:[0, 1, 0]
	v_pk_fma_f32 v[42:43], v[196:197], v[116:117], v[138:139] op_sel_hi:[1, 0, 1]
	v_pk_fma_f32 v[72:73], v[198:199], v[74:75], v[140:141] op_sel_hi:[1, 0, 1]
	v_pk_fma_f32 v[74:75], v[196:197], v[74:75], v[142:143] op_sel_hi:[1, 0, 1]
	v_pk_fma_f32 v[114:115], v[196:197], v[128:129], v[84:85] op_sel_hi:[1, 0, 1]
	v_pk_fma_f32 v[118:119], v[196:197], v[128:129], v[96:97] op_sel:[0, 1, 0]
	v_pk_fma_f32 v[122:123], v[196:197], v[130:131], v[122:123] op_sel_hi:[1, 0, 1]
	v_pk_fma_f32 v[126:127], v[196:197], v[80:81], v[126:127] op_sel_hi:[1, 0, 1]
	v_add_co_u32_e64 v0, s[42:43], s0, v22
	v_pk_fma_f32 v[116:117], v[198:199], v[128:129], v[94:95] op_sel:[0, 1, 0]
	s_nop 0
	v_addc_co_u32_e64 v1, s[42:43], 0, v23, s[42:43]
	v_pk_fma_f32 v[120:121], v[198:199], v[130:131], v[120:121] op_sel_hi:[1, 0, 1]
	v_pk_fma_f32 v[124:125], v[198:199], v[80:81], v[124:125] op_sel_hi:[1, 0, 1]
	global_load_dwordx4 v[196:199], v[208:209], off
	v_add_co_u32_e64 v208, s[42:43], s67, v208
	s_nop 1
	v_addc_co_u32_e64 v209, s[42:43], 0, v209, s[42:43]
	ds_read_b128 v[128:131], v174 offset:576
	s_mov_b32 s0, 0x3f000
	s_waitcnt vmcnt(7) lgkmcnt(0)
	v_pk_fma_f32 v[80:81], v[202:203], v[128:129], v[78:79] op_sel_hi:[1, 0, 1]
	v_pk_fma_f32 v[84:85], v[200:201], v[128:129], v[82:83] op_sel_hi:[1, 0, 1]
	v_pk_fma_f32 v[94:95], v[202:203], v[128:129], v[86:87] op_sel:[0, 1, 0]
	v_pk_fma_f32 v[96:97], v[200:201], v[128:129], v[88:89] op_sel:[0, 1, 0]
	v_pk_fma_f32 v[100:101], v[202:203], v[130:131], v[100:101] op_sel_hi:[1, 0, 1]
	v_pk_fma_f32 v[102:103], v[200:201], v[130:131], v[102:103] op_sel_hi:[1, 0, 1]
	v_mov_b32_e32 v78, v131
	ds_read_b128 v[128:131], v174 offset:592
	v_pk_fma_f32 v[106:107], v[202:203], v[78:79], v[106:107] op_sel_hi:[1, 0, 1]
	v_pk_fma_f32 v[112:113], v[200:201], v[78:79], v[112:113] op_sel_hi:[1, 0, 1]
	s_waitcnt lgkmcnt(0)
	v_pk_fma_f32 v[78:79], v[202:203], v[128:129], v[58:59] op_sel_hi:[1, 0, 1]
	v_pk_fma_f32 v[82:83], v[200:201], v[128:129], v[60:61] op_sel_hi:[1, 0, 1]
	v_pk_fma_f32 v[86:87], v[202:203], v[128:129], v[62:63] op_sel:[0, 1, 0]
	v_pk_fma_f32 v[88:89], v[200:201], v[128:129], v[64:65] op_sel:[0, 1, 0]
	v_pk_fma_f32 v[90:91], v[202:203], v[130:131], v[90:91] op_sel_hi:[1, 0, 1]
	v_pk_fma_f32 v[92:93], v[200:201], v[130:131], v[92:93] op_sel_hi:[1, 0, 1]
	v_mov_b32_e32 v58, v131
	ds_read_b128 v[128:131], v174 offset:608
	v_pk_fma_f32 v[98:99], v[202:203], v[58:59], v[98:99] op_sel_hi:[1, 0, 1]
	v_pk_fma_f32 v[104:105], v[200:201], v[58:59], v[104:105] op_sel_hi:[1, 0, 1]
	s_waitcnt lgkmcnt(0)
	v_pk_fma_f32 v[58:59], v[202:203], v[128:129], v[44:45] op_sel_hi:[1, 0, 1]
	v_pk_fma_f32 v[60:61], v[200:201], v[128:129], v[46:47] op_sel_hi:[1, 0, 1]
	v_pk_fma_f32 v[62:63], v[202:203], v[128:129], v[48:49] op_sel:[0, 1, 0]
	v_pk_fma_f32 v[64:65], v[200:201], v[128:129], v[50:51] op_sel:[0, 1, 0]
	v_pk_fma_f32 v[66:67], v[202:203], v[130:131], v[66:67] op_sel_hi:[1, 0, 1]
	v_pk_fma_f32 v[68:69], v[200:201], v[130:131], v[68:69] op_sel_hi:[1, 0, 1]
	v_mov_b32_e32 v44, v131
	ds_read_b128 v[128:131], v174 offset:624
	v_pk_fma_f32 v[70:71], v[202:203], v[44:45], v[70:71] op_sel_hi:[1, 0, 1]
	v_pk_fma_f32 v[76:77], v[200:201], v[44:45], v[76:77] op_sel_hi:[1, 0, 1]
	s_waitcnt lgkmcnt(0)
; #define LAS __attribute__((address_space(3)))
; __device__ __forceinline__ void gemv24_item(const float* W, int N, int j0, LAS float* sc, LAS float* red, float (&res)[6], const int tid) {
;     ...
;     const float* w = W + (size_t)(ks * 64) * N + j0 + cg * 4;
; #pragma unroll 8
;     for (int kk = 0; kk < 64; ++kk) {
;         const f32x4 wv = *(const f32x4*)(w + (size_t)kk * N);
;         const LAS f32x4* s4 = (const LAS f32x4*)(sc + (ks * 64 + kk) * 24);
; #pragma unroll
;         for (int b4 = 0; b4 < 6; ++b4) { const f32x4 s = s4[b4]; acc[4 * b4] += wv * s[0]; acc[4 * b4 + 1] += wv * s[1]; acc[4 * b4 + 2] += wv * s[2]; acc[4 * b4 + 3] += wv * s[3]; }
;     }
	v_pk_fma_f32 v[44:45], v[202:203], v[128:129], v[32:33] op_sel_hi:[1, 0, 1]
	v_pk_fma_f32 v[46:47], v[200:201], v[128:129], v[34:35] op_sel_hi:[1, 0, 1]
	v_pk_fma_f32 v[48:49], v[202:203], v[128:129], v[36:37] op_sel:[0, 1, 0]
	v_pk_fma_f32 v[50:51], v[200:201], v[128:129], v[38:39] op_sel:[0, 1, 0]
	v_pk_fma_f32 v[52:53], v[202:203], v[130:131], v[52:53] op_sel_hi:[1, 0, 1]
	v_pk_fma_f32 v[54:55], v[200:201], v[130:131], v[54:55] op_sel_hi:[1, 0, 1]
	v_mov_b32_e32 v32, v131
	ds_read_b128 v[128:131], v174 offset:640
	v_pk_fma_f32 v[56:57], v[202:203], v[32:33], v[56:57] op_sel_hi:[1, 0, 1]
	v_pk_fma_f32 v[132:133], v[200:201], v[32:33], v[108:109] op_sel_hi:[1, 0, 1]
	s_waitcnt lgkmcnt(0)
	v_pk_fma_f32 v[32:33], v[202:203], v[128:129], v[24:25] op_sel_hi:[1, 0, 1]
	v_mov_b32_e32 v24, v131
	v_pk_fma_f32 v[34:35], v[200:201], v[128:129], v[26:27] op_sel_hi:[1, 0, 1]
	v_pk_fma_f32 v[36:37], v[202:203], v[128:129], v[28:29] op_sel:[0, 1, 0]
	v_pk_fma_f32 v[38:39], v[200:201], v[128:129], v[30:31] op_sel:[0, 1, 0]
	v_pk_fma_f32 v[40:41], v[202:203], v[130:131], v[40:41] op_sel_hi:[1, 0, 1]
	v_pk_fma_f32 v[42:43], v[200:201], v[130:131], v[42:43] op_sel_hi:[1, 0, 1]
	v_pk_fma_f32 v[128:129], v[202:203], v[24:25], v[72:73] op_sel_hi:[1, 0, 1]
	v_pk_fma_f32 v[130:131], v[200:201], v[24:25], v[74:75] op_sel_hi:[1, 0, 1]
	ds_read_b128 v[72:75], v174 offset:656
	s_waitcnt lgkmcnt(0)
	v_pk_fma_f32 v[24:25], v[202:203], v[72:73], v[110:111] op_sel_hi:[1, 0, 1]
	v_pk_fma_f32 v[26:27], v[200:201], v[72:73], v[114:115] op_sel_hi:[1, 0, 1]
	v_pk_fma_f32 v[28:29], v[202:203], v[72:73], v[116:117] op_sel:[0, 1, 0]
	v_pk_fma_f32 v[30:31], v[200:201], v[72:73], v[118:119] op_sel:[0, 1, 0]
	v_mov_b32_e32 v72, v75
	v_pk_fma_f32 v[122:123], v[200:201], v[74:75], v[122:123] op_sel_hi:[1, 0, 1]
	v_pk_fma_f32 v[126:127], v[200:201], v[72:73], v[126:127] op_sel_hi:[1, 0, 1]
	v_add_co_u32_e64 v0, s[42:43], s0, v22
	v_pk_fma_f32 v[120:121], v[202:203], v[74:75], v[120:121] op_sel_hi:[1, 0, 1]
	s_nop 0
	v_addc_co_u32_e64 v1, s[42:43], 0, v23, s[42:43]
	v_pk_fma_f32 v[124:125], v[202:203], v[72:73], v[124:125] op_sel_hi:[1, 0, 1]
	global_load_dwordx4 v[200:203], v[208:209], off
	v_add_co_u32_e64 v208, s[42:43], s67, v208
	s_nop 1
	v_addc_co_u32_e64 v209, s[42:43], 0, v209, s[42:43]
	ds_read_b128 v[72:75], v174 offset:672
	s_waitcnt lgkmcnt(0)
	v_mov_b32_e32 v22, v75
	s_waitcnt vmcnt(7)
	v_pk_fma_f32 v[118:119], v[206:207], v[72:73], v[80:81] op_sel_hi:[1, 0, 1]
	v_pk_fma_f32 v[116:117], v[204:205], v[72:73], v[84:85] op_sel_hi:[1, 0, 1]
	v_pk_fma_f32 v[110:111], v[206:207], v[72:73], v[94:95] op_sel:[0, 1, 0]
	v_pk_fma_f32 v[108:109], v[204:205], v[72:73], v[96:97] op_sel:[0, 1, 0]
	v_pk_fma_f32 v[100:101], v[206:207], v[74:75], v[100:101] op_sel_hi:[1, 0, 1]
	v_pk_fma_f32 v[96:97], v[204:205], v[74:75], v[102:103] op_sel_hi:[1, 0, 1]
	ds_read_b128 v[72:75], v174 offset:688
	v_pk_fma_f32 v[84:85], v[206:207], v[22:23], v[106:107] op_sel_hi:[1, 0, 1]
	v_pk_fma_f32 v[80:81], v[204:205], v[22:23], v[112:113] op_sel_hi:[1, 0, 1]
	v_pk_fma_f32 v[68:69], v[204:205], v[136:137], v[68:69] op_sel_hi:[1, 0, 1]
	s_waitcnt lgkmcnt(0)
	v_mov_b32_e32 v22, v75
	v_pk_fma_f32 v[114:115], v[206:207], v[72:73], v[78:79] op_sel_hi:[1, 0, 1]
	v_pk_fma_f32 v[112:113], v[204:205], v[72:73], v[82:83] op_sel_hi:[1, 0, 1]
	v_pk_fma_f32 v[106:107], v[206:207], v[72:73], v[86:87] op_sel:[0, 1, 0]
	v_pk_fma_f32 v[102:103], v[204:205], v[72:73], v[88:89] op_sel:[0, 1, 0]
	v_pk_fma_f32 v[94:95], v[206:207], v[74:75], v[90:91] op_sel_hi:[1, 0, 1]
	v_pk_fma_f32 v[90:91], v[204:205], v[74:75], v[92:93] op_sel_hi:[1, 0, 1]
	v_pk_fma_f32 v[78:79], v[206:207], v[22:23], v[98:99] op_sel_hi:[1, 0, 1]
	v_pk_fma_f32 v[74:75], v[204:205], v[22:23], v[104:105] op_sel_hi:[1, 0, 1]
	v_pk_fma_f32 v[104:105], v[206:207], v[134:135], v[58:59] op_sel_hi:[1, 0, 1]
	v_pk_fma_f32 v[98:99], v[204:205], v[134:135], v[60:61] op_sel_hi:[1, 0, 1]
	v_pk_fma_f32 v[88:89], v[206:207], v[134:135], v[62:63] op_sel:[0, 1, 0]
	v_pk_fma_f32 v[82:83], v[204:205], v[134:135], v[64:65] op_sel:[0, 1, 0]
	v_pk_fma_f32 v[72:73], v[206:207], v[136:137], v[66:67] op_sel_hi:[1, 0, 1]
	v_mov_b32_e32 v22, v137
	ds_read_b128 v[134:137], v174 offset:720
	v_pk_fma_f32 v[62:63], v[206:207], v[22:23], v[70:71] op_sel_hi:[1, 0, 1]
	v_pk_fma_f32 v[60:61], v[204:205], v[22:23], v[76:77] op_sel_hi:[1, 0, 1]
	s_waitcnt lgkmcnt(0)
	v_mov_b32_e32 v22, v137
	v_pk_fma_f32 v[92:93], v[206:207], v[134:135], v[44:45] op_sel_hi:[1, 0, 1]
	v_pk_fma_f32 v[86:87], v[204:205], v[134:135], v[46:47] op_sel_hi:[1, 0, 1]
	v_pk_fma_f32 v[76:77], v[206:207], v[134:135], v[48:49] op_sel:[0, 1, 0]
	v_pk_fma_f32 v[70:71], v[204:205], v[134:135], v[50:51] op_sel:[0, 1, 0]
	v_pk_fma_f32 v[58:59], v[206:207], v[22:23], v[56:57] op_sel_hi:[1, 0, 1]
	v_pk_fma_f32 v[56:57], v[204:205], v[22:23], v[132:133] op_sel_hi:[1, 0, 1]
	ds_read_b128 v[132:135], v174 offset:736
	v_pk_fma_f32 v[66:67], v[206:207], v[136:137], v[52:53] op_sel_hi:[1, 0, 1]
	v_pk_fma_f32 v[64:65], v[204:205], v[136:137], v[54:55] op_sel_hi:[1, 0, 1]
	s_waitcnt lgkmcnt(0)
	v_mov_b32_e32 v22, v135
	v_pk_fma_f32 v[50:51], v[206:207], v[132:133], v[36:37] op_sel:[0, 1, 0]
	v_pk_fma_f32 v[48:49], v[204:205], v[132:133], v[38:39] op_sel:[0, 1, 0]
	v_pk_fma_f32 v[38:39], v[206:207], v[22:23], v[128:129] op_sel_hi:[1, 0, 1]
	v_pk_fma_f32 v[36:37], v[204:205], v[22:23], v[130:131] op_sel_hi:[1, 0, 1]
	ds_read_b128 v[128:131], v174 offset:752
	v_pk_fma_f32 v[54:55], v[206:207], v[132:133], v[32:33] op_sel_hi:[1, 0, 1]
	v_pk_fma_f32 v[52:53], v[204:205], v[132:133], v[34:35] op_sel_hi:[1, 0, 1]
	v_pk_fma_f32 v[46:47], v[206:207], v[134:135], v[40:41] op_sel_hi:[1, 0, 1]
	v_pk_fma_f32 v[44:45], v[204:205], v[134:135], v[42:43] op_sel_hi:[1, 0, 1]
	s_waitcnt lgkmcnt(0)
	v_mov_b32_e32 v22, v131
	v_pk_fma_f32 v[42:43], v[206:207], v[128:129], v[24:25] op_sel_hi:[1, 0, 1]
	v_pk_fma_f32 v[40:41], v[204:205], v[128:129], v[26:27] op_sel_hi:[1, 0, 1]
	v_pk_fma_f32 v[34:35], v[206:207], v[128:129], v[28:29] op_sel:[0, 1, 0]
	v_pk_fma_f32 v[32:33], v[204:205], v[128:129], v[30:31] op_sel:[0, 1, 0]
	v_pk_fma_f32 v[30:31], v[206:207], v[130:131], v[120:121] op_sel_hi:[1, 0, 1]
	v_pk_fma_f32 v[28:29], v[204:205], v[130:131], v[122:123] op_sel_hi:[1, 0, 1]
	v_pk_fma_f32 v[26:27], v[206:207], v[22:23], v[124:125] op_sel_hi:[1, 0, 1]
	v_pk_fma_f32 v[24:25], v[204:205], v[22:23], v[126:127] op_sel_hi:[1, 0, 1]
	global_load_dwordx4 v[204:207], v[208:209], off
	v_add_co_u32_e64 v208, s[42:43], s67, v208
	s_nop 1
	v_addc_co_u32_e64 v209, s[42:43], 0, v209, s[42:43]
	v_add_u32_e32 v174, 0x300, v174
	s_cbranch_scc0 .LBB0_523
; #define LAS __attribute__((address_space(3)))
; __device__ __forceinline__ void gemv24_item(const float* W, int N, int j0, LAS float* sc, LAS float* red, float (&res)[6], const int tid) {
;     ...
;     for (int kk = 0; kk < 64; ++kk) {
;         const f32x4 wv = *(const f32x4*)(w + (size_t)kk * N);
;         const LAS f32x4* s4 = (const LAS f32x4*)(sc + (ks * 64 + kk) * 24);
; #pragma unroll
;         for (int b4 = 0; b4 < 6; ++b4) { const f32x4 s = s4[b4]; acc[4 * b4] += wv * s[0]; acc[4 * b4 + 1] += wv * s[1]; acc[4 * b4 + 2] += wv * s[2]; acc[4 * b4 + 3] += wv * s[3]; }
;     }
.Lgemv_last_mod:
	v_lshl_add_u64 v[22:23], v[20:21], 0, s[30:31]
	ds_read_b128 v[122:125], v174
	ds_read_b128 v[132:135], v174 offset:16
	ds_read_b128 v[136:139], v174 offset:32
	ds_read_b128 v[140:143], v174 offset:48
	s_mov_b32 s0, 0x24000
	s_add_u32 s30, s30, 0x48000
	s_addc_u32 s31, s31, 0
	s_cmp_eq_u32 s30, 0x240000
	s_waitcnt vmcnt(7) lgkmcnt(3)
	v_pk_fma_f32 v[120:121], v[176:177], v[124:125], v[96:97] op_sel_hi:[1, 0, 1]
	v_mov_b32_e32 v96, v125
	v_pk_fma_f32 v[118:119], v[178:179], v[122:123], v[118:119] op_sel_hi:[1, 0, 1]
	v_pk_fma_f32 v[128:129], v[176:177], v[122:123], v[116:117] op_sel_hi:[1, 0, 1]
	v_pk_fma_f32 v[116:117], v[178:179], v[122:123], v[110:111] op_sel:[0, 1, 0]
	v_pk_fma_f32 v[130:131], v[176:177], v[122:123], v[108:109] op_sel:[0, 1, 0]
	v_pk_fma_f32 v[122:123], v[178:179], v[124:125], v[100:101] op_sel_hi:[1, 0, 1]
	v_pk_fma_f32 v[124:125], v[176:177], v[96:97], v[80:81] op_sel_hi:[1, 0, 1]
	v_pk_fma_f32 v[126:127], v[178:179], v[96:97], v[84:85] op_sel_hi:[1, 0, 1]
	s_waitcnt lgkmcnt(2)
	v_pk_fma_f32 v[96:97], v[178:179], v[132:133], v[114:115] op_sel_hi:[1, 0, 1]
	v_pk_fma_f32 v[110:111], v[176:177], v[132:133], v[112:113] op_sel_hi:[1, 0, 1]
	v_pk_fma_f32 v[100:101], v[178:179], v[132:133], v[106:107] op_sel:[0, 1, 0]
	v_pk_fma_f32 v[112:113], v[176:177], v[132:133], v[102:103] op_sel:[0, 1, 0]
	v_pk_fma_f32 v[102:103], v[176:177], v[134:135], v[90:91] op_sel_hi:[1, 0, 1]
	v_pk_fma_f32 v[94:95], v[178:179], v[134:135], v[94:95] op_sel_hi:[1, 0, 1]
	v_mov_b32_e32 v80, v135
	ds_read_b128 v[132:135], v174 offset:64
	v_pk_fma_f32 v[106:107], v[176:177], v[80:81], v[74:75] op_sel_hi:[1, 0, 1]
	v_pk_fma_f32 v[108:109], v[178:179], v[80:81], v[78:79] op_sel_hi:[1, 0, 1]
	s_waitcnt lgkmcnt(2)
	v_pk_fma_f32 v[80:81], v[176:177], v[138:139], v[68:69] op_sel_hi:[1, 0, 1]
	v_mov_b32_e32 v68, v139
	v_pk_fma_f32 v[84:85], v[178:179], v[68:69], v[62:63] op_sel_hi:[1, 0, 1]
	s_waitcnt lgkmcnt(1)
	v_pk_fma_f32 v[62:63], v[178:179], v[140:141], v[76:77] op_sel:[0, 1, 0]
	v_mov_b32_e32 v76, v143
	v_pk_fma_f32 v[56:57], v[176:177], v[76:77], v[56:57] op_sel_hi:[1, 0, 1]
	v_pk_fma_f32 v[58:59], v[178:179], v[76:77], v[58:59] op_sel_hi:[1, 0, 1]
	s_waitcnt lgkmcnt(0)
	v_pk_fma_f32 v[54:55], v[178:179], v[132:133], v[54:55] op_sel_hi:[1, 0, 1]
	v_pk_fma_f32 v[52:53], v[176:177], v[132:133], v[52:53] op_sel_hi:[1, 0, 1]
	v_pk_fma_f32 v[50:51], v[178:179], v[132:133], v[50:51] op_sel:[0, 1, 0]
	v_pk_fma_f32 v[48:49], v[176:177], v[132:133], v[48:49] op_sel:[0, 1, 0]
	v_pk_fma_f32 v[44:45], v[176:177], v[134:135], v[44:45] op_sel_hi:[1, 0, 1]
	v_pk_fma_f32 v[46:47], v[178:179], v[134:135], v[46:47] op_sel_hi:[1, 0, 1]
	v_mov_b32_e32 v76, v135
	ds_read_b128 v[132:135], v174 offset:80
	v_pk_fma_f32 v[90:91], v[176:177], v[136:137], v[98:99] op_sel_hi:[1, 0, 1]
	v_pk_fma_f32 v[78:79], v[178:179], v[136:137], v[88:89] op_sel:[0, 1, 0]
	v_pk_fma_f32 v[88:89], v[176:177], v[136:137], v[82:83] op_sel:[0, 1, 0]
	v_pk_fma_f32 v[82:83], v[176:177], v[68:69], v[60:61] op_sel_hi:[1, 0, 1]
	s_waitcnt lgkmcnt(0)
	v_pk_fma_f32 v[98:99], v[176:177], v[132:133], v[40:41] op_sel_hi:[1, 0, 1]
	v_mov_b32_e32 v40, v135
	v_pk_fma_f32 v[68:69], v[176:177], v[140:141], v[86:87] op_sel_hi:[1, 0, 1]
	v_pk_fma_f32 v[70:71], v[176:177], v[140:141], v[70:71] op_sel:[0, 1, 0]
	v_pk_fma_f32 v[64:65], v[176:177], v[142:143], v[64:65] op_sel_hi:[1, 0, 1]
	v_pk_fma_f32 v[36:37], v[176:177], v[76:77], v[36:37] op_sel_hi:[1, 0, 1]
	v_pk_fma_f32 v[32:33], v[176:177], v[132:133], v[32:33] op_sel:[0, 1, 0]
	v_pk_fma_f32 v[28:29], v[176:177], v[134:135], v[28:29] op_sel_hi:[1, 0, 1]
	v_pk_fma_f32 v[24:25], v[176:177], v[40:41], v[24:25] op_sel_hi:[1, 0, 1]
	v_add_co_u32_e64 v0, s[42:43], s67, v22
	v_pk_fma_f32 v[74:75], v[178:179], v[136:137], v[104:105] op_sel_hi:[1, 0, 1]
	s_nop 0
	v_addc_co_u32_e64 v1, s[42:43], 0, v23, s[42:43]
	v_pk_fma_f32 v[72:73], v[178:179], v[138:139], v[72:73] op_sel_hi:[1, 0, 1]
	v_pk_fma_f32 v[60:61], v[178:179], v[140:141], v[92:93] op_sel_hi:[1, 0, 1]
	v_pk_fma_f32 v[66:67], v[178:179], v[142:143], v[66:67] op_sel_hi:[1, 0, 1]
	v_pk_fma_f32 v[38:39], v[178:179], v[76:77], v[38:39] op_sel_hi:[1, 0, 1]
	v_pk_fma_f32 v[92:93], v[178:179], v[132:133], v[42:43] op_sel_hi:[1, 0, 1]
	v_pk_fma_f32 v[34:35], v[178:179], v[132:133], v[34:35] op_sel:[0, 1, 0]
	v_pk_fma_f32 v[30:31], v[178:179], v[134:135], v[30:31] op_sel_hi:[1, 0, 1]
	v_pk_fma_f32 v[26:27], v[178:179], v[40:41], v[26:27] op_sel_hi:[1, 0, 1]
	ds_read_b128 v[40:43], v174 offset:96
	s_waitcnt vmcnt(6) lgkmcnt(0)
	v_pk_fma_f32 v[148:149], v[182:183], v[40:41], v[116:117] op_sel:[0, 1, 0]
	ds_read_b128 v[114:117], v174 offset:112
	v_pk_fma_f32 v[138:139], v[180:181], v[40:41], v[128:129] op_sel_hi:[1, 0, 1]
	v_pk_fma_f32 v[146:147], v[182:183], v[40:41], v[118:119] op_sel_hi:[1, 0, 1]
	v_pk_fma_f32 v[140:141], v[180:181], v[40:41], v[130:131] op_sel:[0, 1, 0]
	v_mov_b32_e32 v40, v43
	v_pk_fma_f32 v[144:145], v[180:181], v[40:41], v[124:125] op_sel_hi:[1, 0, 1]
	v_pk_fma_f32 v[152:153], v[182:183], v[40:41], v[126:127] op_sel_hi:[1, 0, 1]
	s_waitcnt lgkmcnt(0)
	v_pk_fma_f32 v[40:41], v[182:183], v[114:115], v[96:97] op_sel_hi:[1, 0, 1]
	v_pk_fma_f32 v[134:135], v[182:183], v[116:117], v[94:95] op_sel_hi:[1, 0, 1]
	ds_read_b128 v[94:97], v174 offset:128
	v_mov_b32_e32 v76, v117
	v_pk_fma_f32 v[126:127], v[180:181], v[76:77], v[106:107] op_sel_hi:[1, 0, 1]
	v_pk_fma_f32 v[124:125], v[180:181], v[116:117], v[102:103] op_sel_hi:[1, 0, 1]
	v_pk_fma_f32 v[142:143], v[180:181], v[42:43], v[120:121] op_sel_hi:[1, 0, 1]
	s_waitcnt lgkmcnt(0)
; #define LAS __attribute__((address_space(3)))
; __device__ __forceinline__ void gemv24_item(const float* W, int N, int j0, LAS float* sc, LAS float* red, float (&res)[6], const int tid) {
;     ...
;     for (int kk = 0; kk < 64; ++kk) {
;         const f32x4 wv = *(const f32x4*)(w + (size_t)kk * N);
;         const LAS f32x4* s4 = (const LAS f32x4*)(sc + (ks * 64 + kk) * 24);
; #pragma unroll
;         for (int b4 = 0; b4 < 6; ++b4) { const f32x4 s = s4[b4]; acc[4 * b4] += wv * s[0]; acc[4 * b4 + 1] += wv * s[1]; acc[4 * b4 + 2] += wv * s[2]; acc[4 * b4 + 3] += wv * s[3]; }
;     }
	v_pk_fma_f32 v[128:129], v[182:183], v[96:97], v[72:73] op_sel_hi:[1, 0, 1]
	v_mov_b32_e32 v72, v97
	v_pk_fma_f32 v[106:107], v[182:183], v[94:95], v[74:75] op_sel_hi:[1, 0, 1]
	v_pk_fma_f32 v[118:119], v[180:181], v[72:73], v[82:83] op_sel_hi:[1, 0, 1]
	v_pk_fma_f32 v[132:133], v[182:183], v[72:73], v[84:85] op_sel_hi:[1, 0, 1]
	ds_read_b128 v[72:75], v174 offset:144
	v_pk_fma_f32 v[116:117], v[180:181], v[96:97], v[80:81] op_sel_hi:[1, 0, 1]
	v_pk_fma_f32 v[150:151], v[182:183], v[42:43], v[122:123] op_sel_hi:[1, 0, 1]
	v_pk_fma_f32 v[42:43], v[180:181], v[114:115], v[110:111] op_sel_hi:[1, 0, 1]
	v_pk_fma_f32 v[136:137], v[182:183], v[76:77], v[108:109] op_sel_hi:[1, 0, 1]
	s_waitcnt lgkmcnt(0)
	v_pk_fma_f32 v[96:97], v[180:181], v[74:75], v[64:65] op_sel_hi:[1, 0, 1]
	v_pk_fma_f32 v[64:65], v[182:183], v[74:75], v[66:67] op_sel_hi:[1, 0, 1]
	v_mov_b32_e32 v66, v75
	v_pk_fma_f32 v[108:109], v[180:181], v[66:67], v[56:57] op_sel_hi:[1, 0, 1]
	v_pk_fma_f32 v[110:111], v[182:183], v[66:67], v[58:59] op_sel_hi:[1, 0, 1]
	ds_read_b128 v[56:59], v174 offset:160
	v_pk_fma_f32 v[130:131], v[182:183], v[114:115], v[100:101] op_sel:[0, 1, 0]
	v_pk_fma_f32 v[122:123], v[180:181], v[114:115], v[112:113] op_sel:[0, 1, 0]
	v_pk_fma_f32 v[112:113], v[180:181], v[94:95], v[90:91] op_sel_hi:[1, 0, 1]
	v_pk_fma_f32 v[114:115], v[180:181], v[94:95], v[88:89] op_sel:[0, 1, 0]
	s_waitcnt lgkmcnt(0)
	v_pk_fma_f32 v[82:83], v[180:181], v[58:59], v[44:45] op_sel_hi:[1, 0, 1]
	v_mov_b32_e32 v44, v59
	v_pk_fma_f32 v[86:87], v[180:181], v[44:45], v[36:37] op_sel_hi:[1, 0, 1]
	v_pk_fma_f32 v[84:85], v[182:183], v[44:45], v[38:39] op_sel_hi:[1, 0, 1]
	ds_read_b128 v[36:39], v174 offset:176
	v_pk_fma_f32 v[74:75], v[180:181], v[56:57], v[52:53] op_sel_hi:[1, 0, 1]
	v_pk_fma_f32 v[76:77], v[182:183], v[56:57], v[50:51] op_sel:[0, 1, 0]
	ds_read_b128 v[50:53], v174 offset:208
	v_pk_fma_f32 v[120:121], v[182:183], v[94:95], v[78:79] op_sel:[0, 1, 0]
	s_waitcnt lgkmcnt(1)
	v_pk_fma_f32 v[100:101], v[180:181], v[38:39], v[28:29] op_sel_hi:[1, 0, 1]
	v_mov_b32_e32 v28, v39
	v_pk_fma_f32 v[68:69], v[180:181], v[72:73], v[68:69] op_sel_hi:[1, 0, 1]
	v_pk_fma_f32 v[70:71], v[180:181], v[72:73], v[70:71] op_sel:[0, 1, 0]
	v_pk_fma_f32 v[78:79], v[180:181], v[56:57], v[48:49] op_sel:[0, 1, 0]
	v_pk_fma_f32 v[90:91], v[180:181], v[36:37], v[98:99] op_sel_hi:[1, 0, 1]
	v_pk_fma_f32 v[94:95], v[180:181], v[36:37], v[32:33] op_sel:[0, 1, 0]
	v_pk_fma_f32 v[104:105], v[180:181], v[28:29], v[24:25] op_sel_hi:[1, 0, 1]
	v_add_co_u32_e64 v0, s[42:43], s8, v22
	v_pk_fma_f32 v[60:61], v[182:183], v[72:73], v[60:61] op_sel_hi:[1, 0, 1]
	s_nop 0
	v_addc_co_u32_e64 v1, s[42:43], 0, v23, s[42:43]
	v_pk_fma_f32 v[62:63], v[182:183], v[72:73], v[62:63] op_sel:[0, 1, 0]
	v_pk_fma_f32 v[72:73], v[182:183], v[56:57], v[54:55] op_sel_hi:[1, 0, 1]
	v_pk_fma_f32 v[80:81], v[182:183], v[58:59], v[46:47] op_sel_hi:[1, 0, 1]
	v_pk_fma_f32 v[88:89], v[182:183], v[36:37], v[92:93] op_sel_hi:[1, 0, 1]
	v_pk_fma_f32 v[92:93], v[182:183], v[36:37], v[34:35] op_sel:[0, 1, 0]
	v_pk_fma_f32 v[98:99], v[182:183], v[38:39], v[30:31] op_sel_hi:[1, 0, 1]
	v_pk_fma_f32 v[102:103], v[182:183], v[28:29], v[26:27] op_sel_hi:[1, 0, 1]
	ds_read_b128 v[34:37], v174 offset:192
	ds_read_b128 v[56:59], v174 offset:224
	s_waitcnt lgkmcnt(2)
	v_mov_b32_e32 v54, v53
	s_waitcnt lgkmcnt(1)
	v_mov_b32_e32 v38, v37
	s_waitcnt vmcnt(5)
	v_pk_fma_f32 v[40:41], v[186:187], v[50:51], v[40:41] op_sel_hi:[1, 0, 1]
	v_pk_fma_f32 v[42:43], v[184:185], v[50:51], v[42:43] op_sel_hi:[1, 0, 1]
	v_pk_fma_f32 v[44:45], v[186:187], v[50:51], v[130:131] op_sel:[0, 1, 0]
	v_pk_fma_f32 v[46:47], v[184:185], v[50:51], v[122:123] op_sel:[0, 1, 0]
	v_pk_fma_f32 v[48:49], v[186:187], v[52:53], v[134:135] op_sel_hi:[1, 0, 1]
	v_pk_fma_f32 v[50:51], v[184:185], v[52:53], v[124:125] op_sel_hi:[1, 0, 1]
	v_pk_fma_f32 v[52:53], v[186:187], v[54:55], v[136:137] op_sel_hi:[1, 0, 1]
	v_pk_fma_f32 v[54:55], v[184:185], v[54:55], v[126:127] op_sel_hi:[1, 0, 1]
	s_waitcnt lgkmcnt(0)
	v_pk_fma_f32 v[122:123], v[184:185], v[56:57], v[112:113] op_sel_hi:[1, 0, 1]
	v_pk_fma_f32 v[126:127], v[184:185], v[56:57], v[114:115] op_sel:[0, 1, 0]
	ds_read_b128 v[112:115], v174 offset:240
	v_pk_fma_f32 v[106:107], v[186:187], v[56:57], v[106:107] op_sel_hi:[1, 0, 1]
	v_pk_fma_f32 v[124:125], v[186:187], v[56:57], v[120:121] op_sel:[0, 1, 0]
	v_mov_b32_e32 v56, v59
	v_pk_fma_f32 v[130:131], v[184:185], v[58:59], v[116:117] op_sel_hi:[1, 0, 1]
	v_pk_fma_f32 v[132:133], v[186:187], v[56:57], v[132:133] op_sel_hi:[1, 0, 1]
	v_pk_fma_f32 v[134:135], v[184:185], v[56:57], v[118:119] op_sel_hi:[1, 0, 1]
	ds_read_b128 v[116:119], v174 offset:288
	s_waitcnt lgkmcnt(1)
	v_pk_fma_f32 v[56:57], v[186:187], v[112:113], v[60:61] op_sel_hi:[1, 0, 1]
	v_pk_fma_f32 v[60:61], v[186:187], v[112:113], v[62:63] op_sel:[0, 1, 0]
	v_pk_fma_f32 v[62:63], v[184:185], v[112:113], v[70:71] op_sel:[0, 1, 0]
	v_mov_b32_e32 v70, v115
	v_pk_fma_f32 v[128:129], v[186:187], v[58:59], v[128:129] op_sel_hi:[1, 0, 1]
	v_pk_fma_f32 v[58:59], v[184:185], v[112:113], v[68:69] op_sel_hi:[1, 0, 1]
	v_pk_fma_f32 v[68:69], v[186:187], v[70:71], v[110:111] op_sel_hi:[1, 0, 1]
	v_pk_fma_f32 v[70:71], v[184:185], v[70:71], v[108:109] op_sel_hi:[1, 0, 1]
	ds_read_b128 v[108:111], v174 offset:256
	v_pk_fma_f32 v[66:67], v[184:185], v[114:115], v[96:97] op_sel_hi:[1, 0, 1]
	v_pk_fma_f32 v[24:25], v[186:187], v[34:35], v[146:147] op_sel_hi:[1, 0, 1]
	v_pk_fma_f32 v[26:27], v[184:185], v[34:35], v[138:139] op_sel_hi:[1, 0, 1]
	v_pk_fma_f32 v[28:29], v[186:187], v[34:35], v[148:149] op_sel:[0, 1, 0]
	s_waitcnt lgkmcnt(0)
; #define LAS __attribute__((address_space(3)))
; __device__ __forceinline__ void gemv24_item(const float* W, int N, int j0, LAS float* sc, LAS float* red, float (&res)[6], const int tid) {
;     ...
;     for (int kk = 0; kk < 64; ++kk) {
;         const f32x4 wv = *(const f32x4*)(w + (size_t)kk * N);
;         const LAS f32x4* s4 = (const LAS f32x4*)(sc + (ks * 64 + kk) * 24);
; #pragma unroll
;         for (int b4 = 0; b4 < 6; ++b4) { const f32x4 s = s4[b4]; acc[4 * b4] += wv * s[0]; acc[4 * b4 + 1] += wv * s[1]; acc[4 * b4 + 2] += wv * s[2]; acc[4 * b4 + 3] += wv * s[3]; }
;     }
	v_pk_fma_f32 v[72:73], v[186:187], v[108:109], v[72:73] op_sel_hi:[1, 0, 1]
	v_pk_fma_f32 v[74:75], v[184:185], v[108:109], v[74:75] op_sel_hi:[1, 0, 1]
	v_pk_fma_f32 v[76:77], v[186:187], v[108:109], v[76:77] op_sel:[0, 1, 0]
	v_pk_fma_f32 v[78:79], v[184:185], v[108:109], v[78:79] op_sel:[0, 1, 0]
	v_pk_fma_f32 v[80:81], v[186:187], v[110:111], v[80:81] op_sel_hi:[1, 0, 1]
	v_pk_fma_f32 v[82:83], v[184:185], v[110:111], v[82:83] op_sel_hi:[1, 0, 1]
	v_mov_b32_e32 v96, v111
	ds_read_b128 v[108:111], v174 offset:272
	v_pk_fma_f32 v[84:85], v[186:187], v[96:97], v[84:85] op_sel_hi:[1, 0, 1]
	v_pk_fma_f32 v[86:87], v[184:185], v[96:97], v[86:87] op_sel_hi:[1, 0, 1]
	v_pk_fma_f32 v[30:31], v[184:185], v[34:35], v[140:141] op_sel:[0, 1, 0]
	v_pk_fma_f32 v[32:33], v[186:187], v[36:37], v[150:151] op_sel_hi:[1, 0, 1]
	s_waitcnt lgkmcnt(0)
	v_pk_fma_f32 v[96:97], v[184:185], v[108:109], v[94:95] op_sel:[0, 1, 0]
	v_mov_b32_e32 v94, v111
	v_pk_fma_f32 v[34:35], v[184:185], v[36:37], v[142:143] op_sel_hi:[1, 0, 1]
	v_pk_fma_f32 v[36:37], v[186:187], v[38:39], v[152:153] op_sel_hi:[1, 0, 1]
	v_pk_fma_f32 v[38:39], v[184:185], v[38:39], v[144:145] op_sel_hi:[1, 0, 1]
	v_pk_fma_f32 v[90:91], v[184:185], v[108:109], v[90:91] op_sel_hi:[1, 0, 1]
	v_pk_fma_f32 v[100:101], v[184:185], v[110:111], v[100:101] op_sel_hi:[1, 0, 1]
	v_pk_fma_f32 v[104:105], v[184:185], v[94:95], v[104:105] op_sel_hi:[1, 0, 1]
	v_add_co_u32_e64 v0, s[42:43], s3, v22
	v_pk_fma_f32 v[64:65], v[186:187], v[114:115], v[64:65] op_sel_hi:[1, 0, 1]
	s_nop 0
	v_addc_co_u32_e64 v1, s[42:43], 0, v23, s[42:43]
	v_pk_fma_f32 v[88:89], v[186:187], v[108:109], v[88:89] op_sel_hi:[1, 0, 1]
	v_pk_fma_f32 v[92:93], v[186:187], v[108:109], v[92:93] op_sel:[0, 1, 0]
	v_pk_fma_f32 v[98:99], v[186:187], v[110:111], v[98:99] op_sel_hi:[1, 0, 1]
	v_pk_fma_f32 v[102:103], v[186:187], v[94:95], v[102:103] op_sel_hi:[1, 0, 1]
	s_waitcnt vmcnt(4)
	v_pk_fma_f32 v[94:95], v[190:191], v[116:117], v[24:25] op_sel_hi:[1, 0, 1]
	v_mov_b32_e32 v24, v119
	v_pk_fma_f32 v[108:109], v[188:189], v[116:117], v[26:27] op_sel_hi:[1, 0, 1]
	v_pk_fma_f32 v[110:111], v[190:191], v[116:117], v[28:29] op_sel:[0, 1, 0]
	v_pk_fma_f32 v[112:113], v[188:189], v[116:117], v[30:31] op_sel:[0, 1, 0]
	v_pk_fma_f32 v[114:115], v[190:191], v[118:119], v[32:33] op_sel_hi:[1, 0, 1]
	v_pk_fma_f32 v[116:117], v[188:189], v[118:119], v[34:35] op_sel_hi:[1, 0, 1]
	v_pk_fma_f32 v[118:119], v[190:191], v[24:25], v[36:37] op_sel_hi:[1, 0, 1]
	v_pk_fma_f32 v[120:121], v[188:189], v[24:25], v[38:39] op_sel_hi:[1, 0, 1]
	ds_read_b128 v[24:27], v174 offset:304
	ds_read_b128 v[34:37], v174 offset:320
	s_waitcnt lgkmcnt(1)
	v_pk_fma_f32 v[40:41], v[190:191], v[24:25], v[40:41] op_sel_hi:[1, 0, 1]
	v_pk_fma_f32 v[42:43], v[188:189], v[24:25], v[42:43] op_sel_hi:[1, 0, 1]
	v_pk_fma_f32 v[44:45], v[190:191], v[24:25], v[44:45] op_sel:[0, 1, 0]
	v_pk_fma_f32 v[46:47], v[188:189], v[24:25], v[46:47] op_sel:[0, 1, 0]
	v_pk_fma_f32 v[48:49], v[190:191], v[26:27], v[48:49] op_sel_hi:[1, 0, 1]
	v_pk_fma_f32 v[50:51], v[188:189], v[26:27], v[50:51] op_sel_hi:[1, 0, 1]
	v_mov_b32_e32 v24, v27
	s_waitcnt lgkmcnt(0)
	v_pk_fma_f32 v[26:27], v[188:189], v[34:35], v[122:123] op_sel_hi:[1, 0, 1]
	v_pk_fma_f32 v[28:29], v[190:191], v[34:35], v[124:125] op_sel:[0, 1, 0]
	ds_read_b128 v[122:125], v174 offset:336
	v_pk_fma_f32 v[52:53], v[190:191], v[24:25], v[52:53] op_sel_hi:[1, 0, 1]
	v_pk_fma_f32 v[54:55], v[188:189], v[24:25], v[54:55] op_sel_hi:[1, 0, 1]
	v_pk_fma_f32 v[24:25], v[190:191], v[34:35], v[106:107] op_sel_hi:[1, 0, 1]
	v_mov_b32_e32 v38, v37
	s_waitcnt lgkmcnt(0)
	v_pk_fma_f32 v[56:57], v[190:191], v[122:123], v[56:57] op_sel_hi:[1, 0, 1]
	v_pk_fma_f32 v[58:59], v[188:189], v[122:123], v[58:59] op_sel_hi:[1, 0, 1]
	v_pk_fma_f32 v[60:61], v[190:191], v[122:123], v[60:61] op_sel:[0, 1, 0]
	v_pk_fma_f32 v[62:63], v[188:189], v[122:123], v[62:63] op_sel:[0, 1, 0]
	v_pk_fma_f32 v[64:65], v[190:191], v[124:125], v[64:65] op_sel_hi:[1, 0, 1]
	v_pk_fma_f32 v[66:67], v[188:189], v[124:125], v[66:67] op_sel_hi:[1, 0, 1]
	v_mov_b32_e32 v106, v125
	ds_read_b128 v[122:125], v174 offset:352
	v_pk_fma_f32 v[68:69], v[190:191], v[106:107], v[68:69] op_sel_hi:[1, 0, 1]
	v_pk_fma_f32 v[70:71], v[188:189], v[106:107], v[70:71] op_sel_hi:[1, 0, 1]
	v_pk_fma_f32 v[30:31], v[188:189], v[34:35], v[126:127] op_sel:[0, 1, 0]
	v_pk_fma_f32 v[32:33], v[190:191], v[36:37], v[128:129] op_sel_hi:[1, 0, 1]
	s_waitcnt lgkmcnt(0)
	v_pk_fma_f32 v[72:73], v[190:191], v[122:123], v[72:73] op_sel_hi:[1, 0, 1]
	v_pk_fma_f32 v[74:75], v[188:189], v[122:123], v[74:75] op_sel_hi:[1, 0, 1]
	v_pk_fma_f32 v[76:77], v[190:191], v[122:123], v[76:77] op_sel:[0, 1, 0]
	v_pk_fma_f32 v[78:79], v[188:189], v[122:123], v[78:79] op_sel:[0, 1, 0]
	v_pk_fma_f32 v[80:81], v[190:191], v[124:125], v[80:81] op_sel_hi:[1, 0, 1]
	v_pk_fma_f32 v[82:83], v[188:189], v[124:125], v[82:83] op_sel_hi:[1, 0, 1]
	v_mov_b32_e32 v106, v125
	ds_read_b128 v[122:125], v174 offset:368
	v_pk_fma_f32 v[84:85], v[190:191], v[106:107], v[84:85] op_sel_hi:[1, 0, 1]
	v_pk_fma_f32 v[86:87], v[188:189], v[106:107], v[86:87] op_sel_hi:[1, 0, 1]
	v_pk_fma_f32 v[34:35], v[188:189], v[36:37], v[130:131] op_sel_hi:[1, 0, 1]
	v_pk_fma_f32 v[36:37], v[190:191], v[38:39], v[132:133] op_sel_hi:[1, 0, 1]
	s_waitcnt lgkmcnt(0)
; #define LAS __attribute__((address_space(3)))
; __device__ __forceinline__ void gemv24_item(const float* W, int N, int j0, LAS float* sc, LAS float* red, float (&res)[6], const int tid) {
;     ...
;     for (int kk = 0; kk < 64; ++kk) {
;         const f32x4 wv = *(const f32x4*)(w + (size_t)kk * N);
;         const LAS f32x4* s4 = (const LAS f32x4*)(sc + (ks * 64 + kk) * 24);
; #pragma unroll
;         for (int b4 = 0; b4 < 6; ++b4) { const f32x4 s = s4[b4]; acc[4 * b4] += wv * s[0]; acc[4 * b4 + 1] += wv * s[1]; acc[4 * b4 + 2] += wv * s[2]; acc[4 * b4 + 3] += wv * s[3]; }
;     }
	v_mov_b32_e32 v106, v125
	v_pk_fma_f32 v[38:39], v[188:189], v[38:39], v[134:135] op_sel_hi:[1, 0, 1]
	v_pk_fma_f32 v[90:91], v[188:189], v[122:123], v[90:91] op_sel_hi:[1, 0, 1]
	v_pk_fma_f32 v[96:97], v[188:189], v[122:123], v[96:97] op_sel:[0, 1, 0]
	v_pk_fma_f32 v[100:101], v[188:189], v[124:125], v[100:101] op_sel_hi:[1, 0, 1]
	v_pk_fma_f32 v[104:105], v[188:189], v[106:107], v[104:105] op_sel_hi:[1, 0, 1]
	v_add_co_u32_e64 v0, s[42:43], s0, v22
	v_pk_fma_f32 v[88:89], v[190:191], v[122:123], v[88:89] op_sel_hi:[1, 0, 1]
	s_nop 0
	v_addc_co_u32_e64 v1, s[42:43], 0, v23, s[42:43]
	v_pk_fma_f32 v[92:93], v[190:191], v[122:123], v[92:93] op_sel:[0, 1, 0]
	v_pk_fma_f32 v[98:99], v[190:191], v[124:125], v[98:99] op_sel_hi:[1, 0, 1]
	v_pk_fma_f32 v[102:103], v[190:191], v[106:107], v[102:103] op_sel_hi:[1, 0, 1]
	ds_read_b128 v[122:125], v174 offset:384
	s_mov_b32 s0, 0x2d000
	s_waitcnt vmcnt(3) lgkmcnt(0)
	v_pk_fma_f32 v[106:107], v[194:195], v[122:123], v[94:95] op_sel_hi:[1, 0, 1]
	v_mov_b32_e32 v94, v125
	v_pk_fma_f32 v[108:109], v[192:193], v[122:123], v[108:109] op_sel_hi:[1, 0, 1]
	v_pk_fma_f32 v[110:111], v[194:195], v[122:123], v[110:111] op_sel:[0, 1, 0]
	v_pk_fma_f32 v[112:113], v[192:193], v[122:123], v[112:113] op_sel:[0, 1, 0]
	v_pk_fma_f32 v[128:129], v[192:193], v[94:95], v[120:121] op_sel_hi:[1, 0, 1]
	ds_read_b128 v[120:123], v174 offset:400
	v_pk_fma_f32 v[118:119], v[194:195], v[94:95], v[118:119] op_sel_hi:[1, 0, 1]
	v_pk_fma_f32 v[116:117], v[192:193], v[124:125], v[116:117] op_sel_hi:[1, 0, 1]
	v_pk_fma_f32 v[114:115], v[194:195], v[124:125], v[114:115] op_sel_hi:[1, 0, 1]
	s_waitcnt lgkmcnt(0)
	v_pk_fma_f32 v[144:145], v[194:195], v[120:121], v[40:41] op_sel_hi:[1, 0, 1]
	v_mov_b32_e32 v40, v123
	v_pk_fma_f32 v[146:147], v[192:193], v[120:121], v[42:43] op_sel_hi:[1, 0, 1]
	v_pk_fma_f32 v[44:45], v[194:195], v[120:121], v[44:45] op_sel:[0, 1, 0]
	v_pk_fma_f32 v[46:47], v[192:193], v[120:121], v[46:47] op_sel:[0, 1, 0]
	v_pk_fma_f32 v[48:49], v[194:195], v[122:123], v[48:49] op_sel_hi:[1, 0, 1]
	v_pk_fma_f32 v[50:51], v[192:193], v[122:123], v[50:51] op_sel_hi:[1, 0, 1]
	v_pk_fma_f32 v[52:53], v[194:195], v[40:41], v[52:53] op_sel_hi:[1, 0, 1]
	v_pk_fma_f32 v[54:55], v[192:193], v[40:41], v[54:55] op_sel_hi:[1, 0, 1]
	ds_read_b128 v[40:43], v174 offset:416
	ds_read_b128 v[120:123], v174 offset:432
	s_waitcnt lgkmcnt(1)
	v_pk_fma_f32 v[148:149], v[194:195], v[40:41], v[24:25] op_sel_hi:[1, 0, 1]
	v_pk_fma_f32 v[150:151], v[192:193], v[40:41], v[26:27] op_sel_hi:[1, 0, 1]
	v_mov_b32_e32 v24, v43
	s_waitcnt lgkmcnt(0)
	v_pk_fma_f32 v[26:27], v[192:193], v[120:121], v[58:59] op_sel_hi:[1, 0, 1]
	v_mov_b32_e32 v58, v123
	v_pk_fma_f32 v[152:153], v[194:195], v[40:41], v[28:29] op_sel:[0, 1, 0]
	v_pk_fma_f32 v[36:37], v[194:195], v[24:25], v[36:37] op_sel_hi:[1, 0, 1]
	v_pk_fma_f32 v[38:39], v[192:193], v[24:25], v[38:39] op_sel_hi:[1, 0, 1]
	v_pk_fma_f32 v[24:25], v[194:195], v[120:121], v[56:57] op_sel_hi:[1, 0, 1]
	v_pk_fma_f32 v[28:29], v[194:195], v[120:121], v[60:61] op_sel:[0, 1, 0]
	v_pk_fma_f32 v[56:57], v[194:195], v[58:59], v[68:69] op_sel_hi:[1, 0, 1]
	v_pk_fma_f32 v[130:131], v[192:193], v[58:59], v[70:71] op_sel_hi:[1, 0, 1]
	ds_read_b128 v[58:61], v174 offset:448
	v_pk_fma_f32 v[154:155], v[192:193], v[40:41], v[30:31] op_sel:[0, 1, 0]
	v_pk_fma_f32 v[32:33], v[194:195], v[42:43], v[32:33] op_sel_hi:[1, 0, 1]
	v_pk_fma_f32 v[34:35], v[192:193], v[42:43], v[34:35] op_sel_hi:[1, 0, 1]
	v_pk_fma_f32 v[40:41], v[194:195], v[122:123], v[64:65] op_sel_hi:[1, 0, 1]
	v_pk_fma_f32 v[42:43], v[192:193], v[122:123], v[66:67] op_sel_hi:[1, 0, 1]
	ds_read_b128 v[64:67], v174 offset:496
	s_waitcnt lgkmcnt(1)
	v_pk_fma_f32 v[72:73], v[194:195], v[58:59], v[72:73] op_sel_hi:[1, 0, 1]
	v_pk_fma_f32 v[74:75], v[192:193], v[58:59], v[74:75] op_sel_hi:[1, 0, 1]
	v_pk_fma_f32 v[132:133], v[194:195], v[58:59], v[76:77] op_sel:[0, 1, 0]
	v_pk_fma_f32 v[134:135], v[192:193], v[58:59], v[78:79] op_sel:[0, 1, 0]
	v_mov_b32_e32 v58, v61
	v_pk_fma_f32 v[136:137], v[194:195], v[60:61], v[80:81] op_sel_hi:[1, 0, 1]
	v_pk_fma_f32 v[138:139], v[192:193], v[60:61], v[82:83] op_sel_hi:[1, 0, 1]
	v_pk_fma_f32 v[140:141], v[194:195], v[58:59], v[84:85] op_sel_hi:[1, 0, 1]
	v_pk_fma_f32 v[142:143], v[192:193], v[58:59], v[86:87] op_sel_hi:[1, 0, 1]
	ds_read_b128 v[58:61], v174 offset:464
	v_pk_fma_f32 v[30:31], v[192:193], v[120:121], v[62:63] op_sel:[0, 1, 0]
	s_waitcnt lgkmcnt(0)
	v_pk_fma_f32 v[80:81], v[194:195], v[58:59], v[88:89] op_sel_hi:[1, 0, 1]
	v_pk_fma_f32 v[84:85], v[192:193], v[58:59], v[90:91] op_sel_hi:[1, 0, 1]
	v_pk_fma_f32 v[94:95], v[194:195], v[58:59], v[92:93] op_sel:[0, 1, 0]
	v_pk_fma_f32 v[96:97], v[192:193], v[58:59], v[96:97] op_sel:[0, 1, 0]
	v_mov_b32_e32 v58, v61
	v_pk_fma_f32 v[122:123], v[192:193], v[60:61], v[100:101] op_sel_hi:[1, 0, 1]
	v_pk_fma_f32 v[126:127], v[192:193], v[58:59], v[104:105] op_sel_hi:[1, 0, 1]
	v_add_co_u32_e64 v0, s[42:43], s0, v22
	v_pk_fma_f32 v[120:121], v[194:195], v[60:61], v[98:99] op_sel_hi:[1, 0, 1]
	s_nop 0
	v_addc_co_u32_e64 v1, s[42:43], 0, v23, s[42:43]
	v_pk_fma_f32 v[124:125], v[194:195], v[58:59], v[102:103] op_sel_hi:[1, 0, 1]
	ds_read_b128 v[58:61], v174 offset:480
	s_mov_b32 s0, 0x36000
	s_waitcnt vmcnt(2)
	v_pk_fma_f32 v[62:63], v[198:199], v[64:65], v[44:45] op_sel:[0, 1, 0]
	v_mov_b32_e32 v44, v67
	v_pk_fma_f32 v[92:93], v[196:197], v[66:67], v[50:51] op_sel_hi:[1, 0, 1]
	v_pk_fma_f32 v[98:99], v[198:199], v[44:45], v[52:53] op_sel_hi:[1, 0, 1]
	ds_read_b128 v[50:53], v174 offset:512
	s_waitcnt lgkmcnt(1)
; #define LAS __attribute__((address_space(3)))
; __device__ __forceinline__ void gemv24_item(const float* W, int N, int j0, LAS float* sc, LAS float* red, float (&res)[6], const int tid) {
;     ...
;     for (int kk = 0; kk < 64; ++kk) {
;         const f32x4 wv = *(const f32x4*)(w + (size_t)kk * N);
;         const LAS f32x4* s4 = (const LAS f32x4*)(sc + (ks * 64 + kk) * 24);
; #pragma unroll
;         for (int b4 = 0; b4 < 6; ++b4) { const f32x4 s = s4[b4]; acc[4 * b4] += wv * s[0]; acc[4 * b4 + 1] += wv * s[1]; acc[4 * b4 + 2] += wv * s[2]; acc[4 * b4 + 3] += wv * s[3]; }
;     }
	v_pk_fma_f32 v[82:83], v[196:197], v[58:59], v[108:109] op_sel_hi:[1, 0, 1]
	v_pk_fma_f32 v[86:87], v[198:199], v[58:59], v[110:111] op_sel:[0, 1, 0]
	ds_read_b128 v[108:111], v174 offset:528
	v_pk_fma_f32 v[90:91], v[198:199], v[66:67], v[48:49] op_sel_hi:[1, 0, 1]
	s_waitcnt lgkmcnt(1)
	v_pk_fma_f32 v[66:67], v[198:199], v[52:53], v[32:33] op_sel_hi:[1, 0, 1]
	v_mov_b32_e32 v32, v53
	v_pk_fma_f32 v[78:79], v[198:199], v[58:59], v[106:107] op_sel_hi:[1, 0, 1]
	v_pk_fma_f32 v[88:89], v[196:197], v[58:59], v[112:113] op_sel:[0, 1, 0]
	v_pk_fma_f32 v[100:101], v[198:199], v[60:61], v[114:115] op_sel_hi:[1, 0, 1]
	v_pk_fma_f32 v[102:103], v[196:197], v[60:61], v[116:117] op_sel_hi:[1, 0, 1]
	v_mov_b32_e32 v58, v61
	v_pk_fma_f32 v[70:71], v[198:199], v[32:33], v[36:37] op_sel_hi:[1, 0, 1]
	v_pk_fma_f32 v[76:77], v[196:197], v[32:33], v[38:39] op_sel_hi:[1, 0, 1]
	ds_read_b128 v[114:117], v174 offset:544
	s_waitcnt lgkmcnt(1)
	v_pk_fma_f32 v[32:33], v[198:199], v[108:109], v[24:25] op_sel_hi:[1, 0, 1]
	v_mov_b32_e32 v24, v111
	v_pk_fma_f32 v[112:113], v[196:197], v[58:59], v[128:129] op_sel_hi:[1, 0, 1]
	v_pk_fma_f32 v[68:69], v[196:197], v[52:53], v[34:35] op_sel_hi:[1, 0, 1]
	v_pk_fma_f32 v[34:35], v[196:197], v[108:109], v[26:27] op_sel_hi:[1, 0, 1]
	v_pk_fma_f32 v[36:37], v[198:199], v[108:109], v[28:29] op_sel:[0, 1, 0]
	v_pk_fma_f32 v[38:39], v[196:197], v[108:109], v[30:31] op_sel:[0, 1, 0]
	v_pk_fma_f32 v[108:109], v[196:197], v[24:25], v[130:131] op_sel_hi:[1, 0, 1]
	ds_read_b128 v[128:131], v174 offset:560
	v_pk_fma_f32 v[104:105], v[196:197], v[44:45], v[54:55] op_sel_hi:[1, 0, 1]
	v_pk_fma_f32 v[52:53], v[198:199], v[110:111], v[40:41] op_sel_hi:[1, 0, 1]
	v_pk_fma_f32 v[54:55], v[196:197], v[110:111], v[42:43] op_sel_hi:[1, 0, 1]
	s_waitcnt lgkmcnt(1)
	v_pk_fma_f32 v[26:27], v[196:197], v[114:115], v[74:75] op_sel_hi:[1, 0, 1]
	v_pk_fma_f32 v[30:31], v[196:197], v[114:115], v[134:135] op_sel:[0, 1, 0]
	v_pk_fma_f32 v[40:41], v[198:199], v[116:117], v[136:137] op_sel_hi:[1, 0, 1]
	v_mov_b32_e32 v74, v117
	ds_read_b128 v[134:137], v174 offset:704
	s_waitcnt lgkmcnt(1)
	v_pk_fma_f32 v[110:111], v[198:199], v[128:129], v[80:81] op_sel_hi:[1, 0, 1]
	v_mov_b32_e32 v80, v131
	v_pk_fma_f32 v[106:107], v[198:199], v[58:59], v[118:119] op_sel_hi:[1, 0, 1]
	v_pk_fma_f32 v[58:59], v[198:199], v[64:65], v[144:145] op_sel_hi:[1, 0, 1]
	v_pk_fma_f32 v[60:61], v[196:197], v[64:65], v[146:147] op_sel_hi:[1, 0, 1]
	v_pk_fma_f32 v[64:65], v[196:197], v[64:65], v[46:47] op_sel:[0, 1, 0]
	v_pk_fma_f32 v[44:45], v[198:199], v[50:51], v[148:149] op_sel_hi:[1, 0, 1]
	v_pk_fma_f32 v[46:47], v[196:197], v[50:51], v[150:151] op_sel_hi:[1, 0, 1]
	v_pk_fma_f32 v[48:49], v[198:199], v[50:51], v[152:153] op_sel:[0, 1, 0]
	v_pk_fma_f32 v[50:51], v[196:197], v[50:51], v[154:155] op_sel:[0, 1, 0]
	v_pk_fma_f32 v[56:57], v[198:199], v[24:25], v[56:57] op_sel_hi:[1, 0, 1]
	v_pk_fma_f32 v[24:25], v[198:199], v[114:115], v[72:73] op_sel_hi:[1, 0, 1]
	v_pk_fma_f32 v[28:29], v[198:199], v[114:115], v[132:133] op_sel:[0, 1, 0]
	v_pk_fma_f32 v[42:43], v[196:197], v[116:117], v[138:139] op_sel_hi:[1, 0, 1]
	v_pk_fma_f32 v[72:73], v[198:199], v[74:75], v[140:141] op_sel_hi:[1, 0, 1]
	v_pk_fma_f32 v[74:75], v[196:197], v[74:75], v[142:143] op_sel_hi:[1, 0, 1]
	v_pk_fma_f32 v[114:115], v[196:197], v[128:129], v[84:85] op_sel_hi:[1, 0, 1]
	v_pk_fma_f32 v[118:119], v[196:197], v[128:129], v[96:97] op_sel:[0, 1, 0]
	v_pk_fma_f32 v[122:123], v[196:197], v[130:131], v[122:123] op_sel_hi:[1, 0, 1]
	v_pk_fma_f32 v[126:127], v[196:197], v[80:81], v[126:127] op_sel_hi:[1, 0, 1]
	v_add_co_u32_e64 v0, s[42:43], s0, v22
	v_pk_fma_f32 v[116:117], v[198:199], v[128:129], v[94:95] op_sel:[0, 1, 0]
	s_nop 0
	v_addc_co_u32_e64 v1, s[42:43], 0, v23, s[42:43]
	v_pk_fma_f32 v[120:121], v[198:199], v[130:131], v[120:121] op_sel_hi:[1, 0, 1]
	v_pk_fma_f32 v[124:125], v[198:199], v[80:81], v[124:125] op_sel_hi:[1, 0, 1]
	ds_read_b128 v[128:131], v174 offset:576
	s_mov_b32 s0, 0x3f000
	s_waitcnt vmcnt(1) lgkmcnt(0)
	v_pk_fma_f32 v[80:81], v[202:203], v[128:129], v[78:79] op_sel_hi:[1, 0, 1]
	v_pk_fma_f32 v[84:85], v[200:201], v[128:129], v[82:83] op_sel_hi:[1, 0, 1]
	v_pk_fma_f32 v[94:95], v[202:203], v[128:129], v[86:87] op_sel:[0, 1, 0]
	v_pk_fma_f32 v[96:97], v[200:201], v[128:129], v[88:89] op_sel:[0, 1, 0]
	v_pk_fma_f32 v[100:101], v[202:203], v[130:131], v[100:101] op_sel_hi:[1, 0, 1]
	v_pk_fma_f32 v[102:103], v[200:201], v[130:131], v[102:103] op_sel_hi:[1, 0, 1]
	v_mov_b32_e32 v78, v131
	ds_read_b128 v[128:131], v174 offset:592
	v_pk_fma_f32 v[106:107], v[202:203], v[78:79], v[106:107] op_sel_hi:[1, 0, 1]
	v_pk_fma_f32 v[112:113], v[200:201], v[78:79], v[112:113] op_sel_hi:[1, 0, 1]
	s_waitcnt lgkmcnt(0)
	v_pk_fma_f32 v[78:79], v[202:203], v[128:129], v[58:59] op_sel_hi:[1, 0, 1]
	v_pk_fma_f32 v[82:83], v[200:201], v[128:129], v[60:61] op_sel_hi:[1, 0, 1]
	v_pk_fma_f32 v[86:87], v[202:203], v[128:129], v[62:63] op_sel:[0, 1, 0]
	v_pk_fma_f32 v[88:89], v[200:201], v[128:129], v[64:65] op_sel:[0, 1, 0]
	v_pk_fma_f32 v[90:91], v[202:203], v[130:131], v[90:91] op_sel_hi:[1, 0, 1]
	v_pk_fma_f32 v[92:93], v[200:201], v[130:131], v[92:93] op_sel_hi:[1, 0, 1]
	v_mov_b32_e32 v58, v131
	ds_read_b128 v[128:131], v174 offset:608
	v_pk_fma_f32 v[98:99], v[202:203], v[58:59], v[98:99] op_sel_hi:[1, 0, 1]
	v_pk_fma_f32 v[104:105], v[200:201], v[58:59], v[104:105] op_sel_hi:[1, 0, 1]
	s_waitcnt lgkmcnt(0)
; #define LAS __attribute__((address_space(3)))
; __device__ __forceinline__ void gemv24_item(const float* W, int N, int j0, LAS float* sc, LAS float* red, float (&res)[6], const int tid) {
;     ...
;     for (int kk = 0; kk < 64; ++kk) {
;         const f32x4 wv = *(const f32x4*)(w + (size_t)kk * N);
;         const LAS f32x4* s4 = (const LAS f32x4*)(sc + (ks * 64 + kk) * 24);
; #pragma unroll
;         for (int b4 = 0; b4 < 6; ++b4) { const f32x4 s = s4[b4]; acc[4 * b4] += wv * s[0]; acc[4 * b4 + 1] += wv * s[1]; acc[4 * b4 + 2] += wv * s[2]; acc[4 * b4 + 3] += wv * s[3]; }
;     }
	v_pk_fma_f32 v[58:59], v[202:203], v[128:129], v[44:45] op_sel_hi:[1, 0, 1]
	v_pk_fma_f32 v[60:61], v[200:201], v[128:129], v[46:47] op_sel_hi:[1, 0, 1]
	v_pk_fma_f32 v[62:63], v[202:203], v[128:129], v[48:49] op_sel:[0, 1, 0]
	v_pk_fma_f32 v[64:65], v[200:201], v[128:129], v[50:51] op_sel:[0, 1, 0]
	v_pk_fma_f32 v[66:67], v[202:203], v[130:131], v[66:67] op_sel_hi:[1, 0, 1]
	v_pk_fma_f32 v[68:69], v[200:201], v[130:131], v[68:69] op_sel_hi:[1, 0, 1]
	v_mov_b32_e32 v44, v131
	ds_read_b128 v[128:131], v174 offset:624
	v_pk_fma_f32 v[70:71], v[202:203], v[44:45], v[70:71] op_sel_hi:[1, 0, 1]
	v_pk_fma_f32 v[76:77], v[200:201], v[44:45], v[76:77] op_sel_hi:[1, 0, 1]
	s_waitcnt lgkmcnt(0)
	v_pk_fma_f32 v[44:45], v[202:203], v[128:129], v[32:33] op_sel_hi:[1, 0, 1]
	v_pk_fma_f32 v[46:47], v[200:201], v[128:129], v[34:35] op_sel_hi:[1, 0, 1]
	v_pk_fma_f32 v[48:49], v[202:203], v[128:129], v[36:37] op_sel:[0, 1, 0]
	v_pk_fma_f32 v[50:51], v[200:201], v[128:129], v[38:39] op_sel:[0, 1, 0]
	v_pk_fma_f32 v[52:53], v[202:203], v[130:131], v[52:53] op_sel_hi:[1, 0, 1]
	v_pk_fma_f32 v[54:55], v[200:201], v[130:131], v[54:55] op_sel_hi:[1, 0, 1]
	v_mov_b32_e32 v32, v131
	ds_read_b128 v[128:131], v174 offset:640
	v_pk_fma_f32 v[56:57], v[202:203], v[32:33], v[56:57] op_sel_hi:[1, 0, 1]
	v_pk_fma_f32 v[132:133], v[200:201], v[32:33], v[108:109] op_sel_hi:[1, 0, 1]
	s_waitcnt lgkmcnt(0)
	v_pk_fma_f32 v[32:33], v[202:203], v[128:129], v[24:25] op_sel_hi:[1, 0, 1]
	v_mov_b32_e32 v24, v131
	v_pk_fma_f32 v[34:35], v[200:201], v[128:129], v[26:27] op_sel_hi:[1, 0, 1]
	v_pk_fma_f32 v[36:37], v[202:203], v[128:129], v[28:29] op_sel:[0, 1, 0]
	v_pk_fma_f32 v[38:39], v[200:201], v[128:129], v[30:31] op_sel:[0, 1, 0]
	v_pk_fma_f32 v[40:41], v[202:203], v[130:131], v[40:41] op_sel_hi:[1, 0, 1]
	v_pk_fma_f32 v[42:43], v[200:201], v[130:131], v[42:43] op_sel_hi:[1, 0, 1]
	v_pk_fma_f32 v[128:129], v[202:203], v[24:25], v[72:73] op_sel_hi:[1, 0, 1]
	v_pk_fma_f32 v[130:131], v[200:201], v[24:25], v[74:75] op_sel_hi:[1, 0, 1]
	ds_read_b128 v[72:75], v174 offset:656
	s_waitcnt lgkmcnt(0)
	v_pk_fma_f32 v[24:25], v[202:203], v[72:73], v[110:111] op_sel_hi:[1, 0, 1]
	v_pk_fma_f32 v[26:27], v[200:201], v[72:73], v[114:115] op_sel_hi:[1, 0, 1]
	v_pk_fma_f32 v[28:29], v[202:203], v[72:73], v[116:117] op_sel:[0, 1, 0]
	v_pk_fma_f32 v[30:31], v[200:201], v[72:73], v[118:119] op_sel:[0, 1, 0]
	v_mov_b32_e32 v72, v75
	v_pk_fma_f32 v[122:123], v[200:201], v[74:75], v[122:123] op_sel_hi:[1, 0, 1]
	v_pk_fma_f32 v[126:127], v[200:201], v[72:73], v[126:127] op_sel_hi:[1, 0, 1]
	v_add_co_u32_e64 v0, s[42:43], s0, v22
	v_pk_fma_f32 v[120:121], v[202:203], v[74:75], v[120:121] op_sel_hi:[1, 0, 1]
	s_nop 0
	v_addc_co_u32_e64 v1, s[42:43], 0, v23, s[42:43]
	v_pk_fma_f32 v[124:125], v[202:203], v[72:73], v[124:125] op_sel_hi:[1, 0, 1]
	ds_read_b128 v[72:75], v174 offset:672
	s_waitcnt lgkmcnt(0)
	v_mov_b32_e32 v22, v75
	s_waitcnt vmcnt(0)
	v_pk_fma_f32 v[118:119], v[206:207], v[72:73], v[80:81] op_sel_hi:[1, 0, 1]
	v_pk_fma_f32 v[116:117], v[204:205], v[72:73], v[84:85] op_sel_hi:[1, 0, 1]
	v_pk_fma_f32 v[110:111], v[206:207], v[72:73], v[94:95] op_sel:[0, 1, 0]
	v_pk_fma_f32 v[108:109], v[204:205], v[72:73], v[96:97] op_sel:[0, 1, 0]
	v_pk_fma_f32 v[100:101], v[206:207], v[74:75], v[100:101] op_sel_hi:[1, 0, 1]
	v_pk_fma_f32 v[96:97], v[204:205], v[74:75], v[102:103] op_sel_hi:[1, 0, 1]
	ds_read_b128 v[72:75], v174 offset:688
	v_pk_fma_f32 v[84:85], v[206:207], v[22:23], v[106:107] op_sel_hi:[1, 0, 1]
	v_pk_fma_f32 v[80:81], v[204:205], v[22:23], v[112:113] op_sel_hi:[1, 0, 1]
	v_pk_fma_f32 v[68:69], v[204:205], v[136:137], v[68:69] op_sel_hi:[1, 0, 1]
	s_waitcnt lgkmcnt(0)
; #define LAS __attribute__((address_space(3)))
; __device__ __forceinline__ void gemv24_item(const float* W, int N, int j0, LAS float* sc, LAS float* red, float (&res)[6], const int tid) {
;     ...
;     for (int kk = 0; kk < 64; ++kk) {
;         const f32x4 wv = *(const f32x4*)(w + (size_t)kk * N);
;         const LAS f32x4* s4 = (const LAS f32x4*)(sc + (ks * 64 + kk) * 24);
; #pragma unroll
;         for (int b4 = 0; b4 < 6; ++b4) { const f32x4 s = s4[b4]; acc[4 * b4] += wv * s[0]; acc[4 * b4 + 1] += wv * s[1]; acc[4 * b4 + 2] += wv * s[2]; acc[4 * b4 + 3] += wv * s[3]; }
;     }
; #pragma unroll
;     for (int bg = 0; bg < 3; ++bg) {
; #pragma unroll
;         for (int bb = 0; bb < 8; ++bb) {
;             f32x4 a = acc[8 * bg + bb];
;             a[0] += __shfl_xor(a[0], 32); a[1] += __shfl_xor(a[1], 32); a[2] += __shfl_xor(a[2], 32); a[3] += __shfl_xor(a[3], 32);
;             if (lane < 32) *(LAS f32x4*)(red + ((wave * 8 + bb) * 128 + cg * 4)) = a;
	v_mov_b32_e32 v22, v75
	v_pk_fma_f32 v[114:115], v[206:207], v[72:73], v[78:79] op_sel_hi:[1, 0, 1]
	v_pk_fma_f32 v[112:113], v[204:205], v[72:73], v[82:83] op_sel_hi:[1, 0, 1]
	v_pk_fma_f32 v[106:107], v[206:207], v[72:73], v[86:87] op_sel:[0, 1, 0]
	v_pk_fma_f32 v[102:103], v[204:205], v[72:73], v[88:89] op_sel:[0, 1, 0]
	v_pk_fma_f32 v[94:95], v[206:207], v[74:75], v[90:91] op_sel_hi:[1, 0, 1]
	v_pk_fma_f32 v[90:91], v[204:205], v[74:75], v[92:93] op_sel_hi:[1, 0, 1]
	v_pk_fma_f32 v[78:79], v[206:207], v[22:23], v[98:99] op_sel_hi:[1, 0, 1]
	v_pk_fma_f32 v[74:75], v[204:205], v[22:23], v[104:105] op_sel_hi:[1, 0, 1]
	v_pk_fma_f32 v[104:105], v[206:207], v[134:135], v[58:59] op_sel_hi:[1, 0, 1]
	v_pk_fma_f32 v[98:99], v[204:205], v[134:135], v[60:61] op_sel_hi:[1, 0, 1]
	v_pk_fma_f32 v[88:89], v[206:207], v[134:135], v[62:63] op_sel:[0, 1, 0]
	v_pk_fma_f32 v[82:83], v[204:205], v[134:135], v[64:65] op_sel:[0, 1, 0]
	v_pk_fma_f32 v[72:73], v[206:207], v[136:137], v[66:67] op_sel_hi:[1, 0, 1]
	v_mov_b32_e32 v22, v137
	ds_read_b128 v[134:137], v174 offset:720
	v_pk_fma_f32 v[62:63], v[206:207], v[22:23], v[70:71] op_sel_hi:[1, 0, 1]
	v_pk_fma_f32 v[60:61], v[204:205], v[22:23], v[76:77] op_sel_hi:[1, 0, 1]
	s_waitcnt lgkmcnt(0)
	v_mov_b32_e32 v22, v137
	v_pk_fma_f32 v[92:93], v[206:207], v[134:135], v[44:45] op_sel_hi:[1, 0, 1]
	v_pk_fma_f32 v[86:87], v[204:205], v[134:135], v[46:47] op_sel_hi:[1, 0, 1]
	v_pk_fma_f32 v[76:77], v[206:207], v[134:135], v[48:49] op_sel:[0, 1, 0]
	v_pk_fma_f32 v[70:71], v[204:205], v[134:135], v[50:51] op_sel:[0, 1, 0]
	v_pk_fma_f32 v[58:59], v[206:207], v[22:23], v[56:57] op_sel_hi:[1, 0, 1]
	v_pk_fma_f32 v[56:57], v[204:205], v[22:23], v[132:133] op_sel_hi:[1, 0, 1]
	ds_read_b128 v[132:135], v174 offset:736
	v_pk_fma_f32 v[66:67], v[206:207], v[136:137], v[52:53] op_sel_hi:[1, 0, 1]
	v_pk_fma_f32 v[64:65], v[204:205], v[136:137], v[54:55] op_sel_hi:[1, 0, 1]
	s_waitcnt lgkmcnt(0)
	v_mov_b32_e32 v22, v135
	v_pk_fma_f32 v[50:51], v[206:207], v[132:133], v[36:37] op_sel:[0, 1, 0]
	v_pk_fma_f32 v[48:49], v[204:205], v[132:133], v[38:39] op_sel:[0, 1, 0]
	v_pk_fma_f32 v[38:39], v[206:207], v[22:23], v[128:129] op_sel_hi:[1, 0, 1]
	v_pk_fma_f32 v[36:37], v[204:205], v[22:23], v[130:131] op_sel_hi:[1, 0, 1]
	ds_read_b128 v[128:131], v174 offset:752
	v_pk_fma_f32 v[54:55], v[206:207], v[132:133], v[32:33] op_sel_hi:[1, 0, 1]
	v_pk_fma_f32 v[52:53], v[204:205], v[132:133], v[34:35] op_sel_hi:[1, 0, 1]
	v_pk_fma_f32 v[46:47], v[206:207], v[134:135], v[40:41] op_sel_hi:[1, 0, 1]
	v_pk_fma_f32 v[44:45], v[204:205], v[134:135], v[42:43] op_sel_hi:[1, 0, 1]
	s_waitcnt lgkmcnt(0)
	v_mov_b32_e32 v22, v131
	v_pk_fma_f32 v[42:43], v[206:207], v[128:129], v[24:25] op_sel_hi:[1, 0, 1]
	v_pk_fma_f32 v[40:41], v[204:205], v[128:129], v[26:27] op_sel_hi:[1, 0, 1]
	v_pk_fma_f32 v[34:35], v[206:207], v[128:129], v[28:29] op_sel:[0, 1, 0]
	v_pk_fma_f32 v[32:33], v[204:205], v[128:129], v[30:31] op_sel:[0, 1, 0]
	v_pk_fma_f32 v[30:31], v[206:207], v[130:131], v[120:121] op_sel_hi:[1, 0, 1]
	v_pk_fma_f32 v[28:29], v[204:205], v[130:131], v[122:123] op_sel_hi:[1, 0, 1]
	v_pk_fma_f32 v[26:27], v[206:207], v[22:23], v[124:125] op_sel_hi:[1, 0, 1]
	v_pk_fma_f32 v[24:25], v[204:205], v[22:23], v[126:127] op_sel_hi:[1, 0, 1]
	v_add_u32_e32 v174, 0x300, v174
	ds_bpermute_b32 v0, v156, v116
	ds_bpermute_b32 v1, v156, v117
	ds_bpermute_b32 v2, v156, v118
	ds_bpermute_b32 v3, v156, v119
	s_and_saveexec_b64 s[30:31], vcc
	s_cbranch_execz .LBB0_526
	s_waitcnt lgkmcnt(0)
	v_pk_add_f32 v[2:3], v[118:119], v[2:3]
	v_pk_add_f32 v[0:1], v[116:117], v[0:1]
	ds_write_b128 v157, v[0:3]
